# same as previous best but the GEMM loop bodies keep the baseline byte parity (m0 wait states filled by reordering instead of single s_nop)
# speedup vs baseline: 1.0063x; 1.0063x over previous
.Lmid1_446:
	s_add_i32 s22, 0, 0x10000
	s_add_i32 s23, 0, 0x14000
	s_add_u32 s20, s56, 0xfff50080
	s_addc_u32 s21, s57, -1
	s_cmp_eq_u32 s84, 40
	s_cselect_b32 s61, s49, s21
	s_cselect_b32 s60, s48, s20
	s_cselect_b32 s21, s51, s63
	s_cselect_b32 s20, s50, s62
	s_add_i32 m0, s47, 0xc000
	v_lshl_add_u64 v[162:163], s[56:57], 0, v[156:157]
	global_load_lds_dwordx4 v[162:163], off
	v_lshl_add_u64 v[162:163], v[162:163], 0, s[2:3]
	s_add_i32 m0, s47, 0xe000
	s_nop 0
	global_load_lds_dwordx4 v[162:163], off
	s_waitcnt vmcnt(8)
	s_waitcnt lgkmcnt(0)
	s_barrier
	s_setprio 1
	s_waitcnt lgkmcnt(0)
	v_mfma_f32_16x16x32_bf16 v[142:145], v[114:117], v[186:189], 0
	v_mfma_f32_16x16x32_bf16 v[142:145], v[126:129], v[194:197], v[142:145]
	v_mfma_f32_16x16x32_bf16 v[138:141], v[130:133], v[186:189], 0
	v_mfma_f32_16x16x32_bf16 v[138:141], v[134:137], v[194:197], v[138:141]
	v_mfma_f32_16x16x32_bf16 v[110:113], v[114:117], v[198:201], 0
	v_mfma_f32_16x16x32_bf16 v[110:113], v[126:129], v[214:217], v[110:113]
	v_mfma_f32_16x16x32_bf16 v[106:109], v[130:133], v[198:201], 0
	v_mfma_f32_16x16x32_bf16 v[106:109], v[134:137], v[214:217], v[106:109]
	v_mfma_f32_16x16x32_bf16 v[94:97], v[114:117], v[218:221], 0
	v_mfma_f32_16x16x32_bf16 v[94:97], v[126:129], v[222:225], v[94:97]
	v_mfma_f32_16x16x32_bf16 v[90:93], v[130:133], v[218:221], 0
	v_mfma_f32_16x16x32_bf16 v[90:93], v[134:137], v[222:225], v[90:93]
	v_mfma_f32_16x16x32_bf16 v[78:81], v[114:117], v[226:229], 0
	v_mfma_f32_16x16x32_bf16 v[78:81], v[126:129], v[230:233], v[78:81]
	v_mfma_f32_16x16x32_bf16 v[74:77], v[130:133], v[226:229], 0
	v_mfma_f32_16x16x32_bf16 v[74:77], v[134:137], v[230:233], v[74:77]
	s_setprio 0
	s_setprio 1
	v_mfma_f32_16x16x32_bf16 v[122:125], v[146:149], v[186:189], 0
	v_mfma_f32_16x16x32_bf16 v[122:125], v[150:153], v[194:197], v[122:125]
	v_mfma_f32_16x16x32_bf16 v[118:121], v[158:161], v[186:189], 0
	v_mfma_f32_16x16x32_bf16 v[118:121], v[182:185], v[194:197], v[118:121]
	v_mfma_f32_16x16x32_bf16 v[102:105], v[146:149], v[198:201], 0
	v_mfma_f32_16x16x32_bf16 v[102:105], v[150:153], v[214:217], v[102:105]
	v_mfma_f32_16x16x32_bf16 v[98:101], v[158:161], v[198:201], 0
	v_mfma_f32_16x16x32_bf16 v[98:101], v[182:185], v[214:217], v[98:101]
	v_mfma_f32_16x16x32_bf16 v[86:89], v[146:149], v[218:221], 0
	v_mfma_f32_16x16x32_bf16 v[86:89], v[150:153], v[222:225], v[86:89]
	v_mfma_f32_16x16x32_bf16 v[82:85], v[158:161], v[218:221], 0
	v_mfma_f32_16x16x32_bf16 v[82:85], v[182:185], v[222:225], v[82:85]
	v_mfma_f32_16x16x32_bf16 v[70:73], v[146:149], v[226:229], 0
	v_mfma_f32_16x16x32_bf16 v[70:73], v[150:153], v[230:233], v[70:73]
	v_mfma_f32_16x16x32_bf16 v[66:69], v[158:161], v[226:229], 0
	v_mfma_f32_16x16x32_bf16 v[66:69], v[182:185], v[230:233], v[66:69]
	s_setprio 0
	s_barrier
	ds_read_b128 v[186:189], v193 offset:16384
	ds_read_b128 v[194:197], v193 offset:17408
	ds_read_b128 v[198:201], v193 offset:18432
	ds_read_b128 v[214:217], v193 offset:19456
	ds_read_b128 v[218:221], v193 offset:20480
	ds_read_b128 v[222:225], v193 offset:21504
	ds_read_b128 v[226:229], v193 offset:22528
	ds_read_b128 v[230:233], v193 offset:23552
	v_lshl_add_u64 v[162:163], s[20:21], 0, v[0:1]
	s_add_i32 s20, s22, s46
	s_mov_b32 m0, s20
	s_nop 0
	s_nop 0
	global_load_lds_dwordx4 v[162:163], off
	v_lshl_add_u64 v[202:203], v[162:163], 0, s[2:3]
	s_add_i32 m0, s20, 0x2000
	s_add_i32 s20, s23, s46
	global_load_lds_dwordx4 v[202:203], off
	v_lshl_add_u64 v[202:203], v[162:163], 0, s[12:13]
	s_mov_b32 m0, s20
	s_nop 0
	global_load_lds_dwordx4 v[202:203], off
	v_lshl_add_u64 v[202:203], v[162:163], 0, s[86:87]
	s_add_i32 m0, s20, 0x2000
	s_nop 0
	global_load_lds_dwordx4 v[202:203], off
	v_lshl_add_u64 v[202:203], s[60:61], 0, v[154:155]
	s_mov_b32 m0, s47
	v_lshl_add_u64 v[234:235], v[202:203], 0, s[2:3]
	global_load_lds_dwordx4 v[202:203], off
	s_mov_b32 m0, s68
	s_nop 0
	global_load_lds_dwordx4 v[234:235], off
	s_waitcnt vmcnt(8)
	s_waitcnt lgkmcnt(0)
	s_barrier
	s_setprio 1
	s_waitcnt lgkmcnt(0)
	v_mfma_f32_16x16x32_bf16 v[62:65], v[114:117], v[186:189], 0
	v_mfma_f32_16x16x32_bf16 v[62:65], v[126:129], v[194:197], v[62:65]
	v_mfma_f32_16x16x32_bf16 v[58:61], v[130:133], v[186:189], 0
	v_mfma_f32_16x16x32_bf16 v[58:61], v[134:137], v[194:197], v[58:61]
	v_mfma_f32_16x16x32_bf16 v[46:49], v[114:117], v[198:201], 0
	v_mfma_f32_16x16x32_bf16 v[46:49], v[126:129], v[214:217], v[46:49]
	v_mfma_f32_16x16x32_bf16 v[42:45], v[130:133], v[198:201], 0
	v_mfma_f32_16x16x32_bf16 v[42:45], v[134:137], v[214:217], v[42:45]
	v_mfma_f32_16x16x32_bf16 v[30:33], v[114:117], v[218:221], 0
	v_mfma_f32_16x16x32_bf16 v[30:33], v[126:129], v[222:225], v[30:33]
	v_mfma_f32_16x16x32_bf16 v[26:29], v[130:133], v[218:221], 0
	v_mfma_f32_16x16x32_bf16 v[26:29], v[134:137], v[222:225], v[26:29]
	v_mfma_f32_16x16x32_bf16 v[14:17], v[114:117], v[226:229], 0
	v_mfma_f32_16x16x32_bf16 v[14:17], v[126:129], v[230:233], v[14:17]
	v_mfma_f32_16x16x32_bf16 v[10:13], v[130:133], v[226:229], 0
	v_mfma_f32_16x16x32_bf16 v[10:13], v[134:137], v[230:233], v[10:13]
	s_setprio 0
	s_setprio 1
	v_mfma_f32_16x16x32_bf16 v[54:57], v[146:149], v[186:189], 0
	v_mfma_f32_16x16x32_bf16 v[54:57], v[150:153], v[194:197], v[54:57]
	v_mfma_f32_16x16x32_bf16 v[50:53], v[158:161], v[186:189], 0
	v_mfma_f32_16x16x32_bf16 v[50:53], v[182:185], v[194:197], v[50:53]
	v_mfma_f32_16x16x32_bf16 v[38:41], v[146:149], v[198:201], 0
	v_mfma_f32_16x16x32_bf16 v[38:41], v[150:153], v[214:217], v[38:41]
	v_mfma_f32_16x16x32_bf16 v[34:37], v[158:161], v[198:201], 0
	v_mfma_f32_16x16x32_bf16 v[34:37], v[182:185], v[214:217], v[34:37]
	v_mfma_f32_16x16x32_bf16 v[22:25], v[146:149], v[218:221], 0
	v_mfma_f32_16x16x32_bf16 v[22:25], v[150:153], v[222:225], v[22:25]
	v_mfma_f32_16x16x32_bf16 v[18:21], v[158:161], v[218:221], 0
	v_mfma_f32_16x16x32_bf16 v[18:21], v[182:185], v[222:225], v[18:21]
	v_mfma_f32_16x16x32_bf16 v[6:9], v[146:149], v[226:229], 0
	v_mfma_f32_16x16x32_bf16 v[6:9], v[150:153], v[230:233], v[6:9]
	v_mfma_f32_16x16x32_bf16 v[2:5], v[158:161], v[226:229], 0
	v_mfma_f32_16x16x32_bf16 v[2:5], v[182:185], v[230:233], v[2:5]
	s_setprio 0
	s_barrier
	s_add_i32 s20, 0, 0x18000
	s_add_i32 s21, 0, 0x1c000
	v_add_u32_e32 v134, s20, v191
	v_add_u32_e32 v182, s21, v191
	ds_read_b128 v[114:117], v134
	ds_read_b128 v[126:129], v134 offset:1024
	ds_read_b128 v[130:133], v134 offset:2048
	ds_read_b128 v[134:137], v134 offset:3072
	ds_read_b128 v[146:149], v182
	ds_read_b128 v[150:153], v182 offset:1024
	ds_read_b128 v[158:161], v182 offset:2048
	ds_read_b128 v[182:185], v182 offset:3072
	ds_read_b128 v[186:189], v193 offset:32768
	ds_read_b128 v[194:197], v193 offset:33792
	ds_read_b128 v[198:201], v193 offset:34816
	ds_read_b128 v[214:217], v193 offset:35840
	ds_read_b128 v[218:221], v193 offset:36864
	ds_read_b128 v[222:225], v193 offset:37888
	ds_read_b128 v[226:229], v193 offset:38912
	ds_read_b128 v[230:233], v193 offset:39936
	s_mov_b32 m0, s69
	v_lshl_add_u64 v[234:235], v[202:203], 0, s[12:13]
	global_load_lds_dwordx4 v[234:235], off
	v_lshl_add_u64 v[234:235], v[202:203], 0, s[86:87]
	s_mov_b32 m0, s76
	s_nop 0
	global_load_lds_dwordx4 v[234:235], off
	s_waitcnt vmcnt(8)
	s_waitcnt lgkmcnt(0)
	s_barrier
	s_setprio 1
	s_waitcnt lgkmcnt(0)
	v_mfma_f32_16x16x32_bf16 v[142:145], v[114:117], v[186:189], v[142:145]
	v_mfma_f32_16x16x32_bf16 v[142:145], v[126:129], v[194:197], v[142:145]
	v_mfma_f32_16x16x32_bf16 v[138:141], v[130:133], v[186:189], v[138:141]
	v_mfma_f32_16x16x32_bf16 v[138:141], v[134:137], v[194:197], v[138:141]
	v_mfma_f32_16x16x32_bf16 v[110:113], v[114:117], v[198:201], v[110:113]
	v_mfma_f32_16x16x32_bf16 v[110:113], v[126:129], v[214:217], v[110:113]
	v_mfma_f32_16x16x32_bf16 v[106:109], v[130:133], v[198:201], v[106:109]
	v_mfma_f32_16x16x32_bf16 v[106:109], v[134:137], v[214:217], v[106:109]
	v_mfma_f32_16x16x32_bf16 v[94:97], v[114:117], v[218:221], v[94:97]
	v_mfma_f32_16x16x32_bf16 v[94:97], v[126:129], v[222:225], v[94:97]
	v_mfma_f32_16x16x32_bf16 v[90:93], v[130:133], v[218:221], v[90:93]
	v_mfma_f32_16x16x32_bf16 v[90:93], v[134:137], v[222:225], v[90:93]
	v_mfma_f32_16x16x32_bf16 v[78:81], v[114:117], v[226:229], v[78:81]
	v_mfma_f32_16x16x32_bf16 v[78:81], v[126:129], v[230:233], v[78:81]
	v_mfma_f32_16x16x32_bf16 v[74:77], v[130:133], v[226:229], v[74:77]
	v_mfma_f32_16x16x32_bf16 v[74:77], v[134:137], v[230:233], v[74:77]
	s_setprio 0
	s_setprio 1
	v_mfma_f32_16x16x32_bf16 v[122:125], v[146:149], v[186:189], v[122:125]
	v_mfma_f32_16x16x32_bf16 v[122:125], v[150:153], v[194:197], v[122:125]
	v_mfma_f32_16x16x32_bf16 v[118:121], v[158:161], v[186:189], v[118:121]
	v_mfma_f32_16x16x32_bf16 v[118:121], v[182:185], v[194:197], v[118:121]
	v_mfma_f32_16x16x32_bf16 v[102:105], v[146:149], v[198:201], v[102:105]
	v_mfma_f32_16x16x32_bf16 v[102:105], v[150:153], v[214:217], v[102:105]
	v_mfma_f32_16x16x32_bf16 v[98:101], v[158:161], v[198:201], v[98:101]
	v_mfma_f32_16x16x32_bf16 v[98:101], v[182:185], v[214:217], v[98:101]
	v_mfma_f32_16x16x32_bf16 v[86:89], v[146:149], v[218:221], v[86:89]
	v_mfma_f32_16x16x32_bf16 v[86:89], v[150:153], v[222:225], v[86:89]
	v_mfma_f32_16x16x32_bf16 v[82:85], v[158:161], v[218:221], v[82:85]
	v_mfma_f32_16x16x32_bf16 v[82:85], v[182:185], v[222:225], v[82:85]
	v_mfma_f32_16x16x32_bf16 v[70:73], v[146:149], v[226:229], v[70:73]
	v_mfma_f32_16x16x32_bf16 v[70:73], v[150:153], v[230:233], v[70:73]
	v_mfma_f32_16x16x32_bf16 v[66:69], v[158:161], v[226:229], v[66:69]
	v_mfma_f32_16x16x32_bf16 v[66:69], v[182:185], v[230:233], v[66:69]
	s_setprio 0
	s_barrier
	ds_read_b128 v[186:189], v193 offset:49152
	ds_read_b128 v[194:197], v193 offset:50176
	ds_read_b128 v[198:201], v193 offset:51200
	ds_read_b128 v[214:217], v193 offset:52224
	ds_read_b128 v[218:221], v193 offset:53248
	ds_read_b128 v[222:225], v193 offset:54272
	ds_read_b128 v[226:229], v193 offset:55296
	ds_read_b128 v[230:233], v193 offset:56320
	s_add_i32 s20, s20, s46
	s_mov_b32 m0, s20
	v_lshl_add_u64 v[234:235], v[162:163], 0, s[34:35]
	global_load_lds_dwordx4 v[234:235], off
	v_lshl_add_u64 v[234:235], v[162:163], 0, s[96:97]
	s_add_i32 m0, s20, 0x2000
	s_add_i32 s20, s21, s46
	global_load_lds_dwordx4 v[234:235], off
	v_lshl_add_u64 v[234:235], v[162:163], 0, vcc
	s_mov_b32 m0, s20
	v_lshl_add_u64 v[162:163], v[162:163], 0, s[0:1]
	global_load_lds_dwordx4 v[234:235], off
	s_add_i32 m0, s20, 0x2000
	s_nop 0
	global_load_lds_dwordx4 v[162:163], off
	v_lshl_add_u64 v[162:163], v[202:203], 0, s[34:35]
	s_mov_b32 m0, s77
	s_nop 0
	global_load_lds_dwordx4 v[162:163], off
	v_lshl_add_u64 v[162:163], v[202:203], 0, s[96:97]
	s_mov_b32 m0, s78
	s_nop 0
	global_load_lds_dwordx4 v[162:163], off
	s_waitcnt vmcnt(8)
	s_waitcnt lgkmcnt(0)
	s_barrier
	s_setprio 1
	s_waitcnt lgkmcnt(0)
	v_mfma_f32_16x16x32_bf16 v[62:65], v[114:117], v[186:189], v[62:65]
	v_mfma_f32_16x16x32_bf16 v[62:65], v[126:129], v[194:197], v[62:65]
	v_mfma_f32_16x16x32_bf16 v[58:61], v[130:133], v[186:189], v[58:61]
	v_mfma_f32_16x16x32_bf16 v[58:61], v[134:137], v[194:197], v[58:61]
	v_mfma_f32_16x16x32_bf16 v[46:49], v[114:117], v[198:201], v[46:49]
	v_mfma_f32_16x16x32_bf16 v[46:49], v[126:129], v[214:217], v[46:49]
	v_mfma_f32_16x16x32_bf16 v[42:45], v[130:133], v[198:201], v[42:45]
	v_mfma_f32_16x16x32_bf16 v[42:45], v[134:137], v[214:217], v[42:45]
	v_mfma_f32_16x16x32_bf16 v[30:33], v[114:117], v[218:221], v[30:33]
	v_mfma_f32_16x16x32_bf16 v[30:33], v[126:129], v[222:225], v[30:33]
	v_mfma_f32_16x16x32_bf16 v[26:29], v[130:133], v[218:221], v[26:29]
	v_mfma_f32_16x16x32_bf16 v[26:29], v[134:137], v[222:225], v[26:29]
	v_mfma_f32_16x16x32_bf16 v[14:17], v[114:117], v[226:229], v[14:17]
	v_mfma_f32_16x16x32_bf16 v[14:17], v[126:129], v[230:233], v[14:17]
	v_mfma_f32_16x16x32_bf16 v[10:13], v[130:133], v[226:229], v[10:13]
	v_mfma_f32_16x16x32_bf16 v[10:13], v[134:137], v[230:233], v[10:13]
	s_add_i32 s84, s84, 2
	s_add_u32 s56, s56, 0x100
	s_addc_u32 s57, s57, 0
	s_add_u32 s62, s62, 0x100
	s_addc_u32 s63, s63, 0
	s_setprio 0
	s_setprio 1
	v_mfma_f32_16x16x32_bf16 v[54:57], v[146:149], v[186:189], v[54:57]
	v_mfma_f32_16x16x32_bf16 v[54:57], v[150:153], v[194:197], v[54:57]
	v_mfma_f32_16x16x32_bf16 v[50:53], v[158:161], v[186:189], v[50:53]
	v_mfma_f32_16x16x32_bf16 v[50:53], v[182:185], v[194:197], v[50:53]
	v_mfma_f32_16x16x32_bf16 v[38:41], v[146:149], v[198:201], v[38:41]
	v_mfma_f32_16x16x32_bf16 v[38:41], v[150:153], v[214:217], v[38:41]
	v_mfma_f32_16x16x32_bf16 v[34:37], v[158:161], v[198:201], v[34:37]
	v_mfma_f32_16x16x32_bf16 v[34:37], v[182:185], v[214:217], v[34:37]
	v_mfma_f32_16x16x32_bf16 v[22:25], v[146:149], v[218:221], v[22:25]
	v_mfma_f32_16x16x32_bf16 v[22:25], v[150:153], v[222:225], v[22:25]
	v_mfma_f32_16x16x32_bf16 v[18:21], v[158:161], v[218:221], v[18:21]
	v_mfma_f32_16x16x32_bf16 v[18:21], v[182:185], v[222:225], v[18:21]
	v_mfma_f32_16x16x32_bf16 v[6:9], v[146:149], v[226:229], v[6:9]
	v_mfma_f32_16x16x32_bf16 v[6:9], v[150:153], v[230:233], v[6:9]
	v_mfma_f32_16x16x32_bf16 v[2:5], v[158:161], v[226:229], v[2:5]
	v_mfma_f32_16x16x32_bf16 v[2:5], v[182:185], v[230:233], v[2:5]
	s_setprio 0
	s_barrier
	s_branch .LBB0_446
	.p2alignl 6, 3212836864
.LBB0_446:
	s_add_i32 s22, 0, 0x10000
	s_add_i32 s23, 0, 0x14000
	v_add_u32_e32 v134, s22, v191
	v_add_u32_e32 v162, s23, v191
	ds_read_b128 v[114:117], v134
	ds_read_b128 v[126:129], v134 offset:1024
	ds_read_b128 v[130:133], v134 offset:2048
	ds_read_b128 v[134:137], v134 offset:3072
	ds_read_b128 v[146:149], v162
	ds_read_b128 v[150:153], v162 offset:1024
	ds_read_b128 v[158:161], v162 offset:2048
	ds_read_b128 v[182:185], v162 offset:3072
	ds_read_b128 v[186:189], v193
	ds_read_b128 v[194:197], v193 offset:1024
	ds_read_b128 v[198:201], v193 offset:2048
	ds_read_b128 v[214:217], v193 offset:3072
	ds_read_b128 v[218:221], v193 offset:4096
	ds_read_b128 v[222:225], v193 offset:5120
	ds_read_b128 v[226:229], v193 offset:6144
	ds_read_b128 v[230:233], v193 offset:7168
	s_add_u32 s20, s56, 0xfff50080
	s_addc_u32 s21, s57, -1
	s_cmp_eq_u32 s84, 40
	s_cselect_b32 s61, s49, s21
	s_cselect_b32 s60, s48, s20
	s_cselect_b32 s21, s51, s63
	s_cselect_b32 s20, s50, s62
	s_add_i32 m0, s47, 0xc000
	v_lshl_add_u64 v[162:163], s[56:57], 0, v[156:157]
	global_load_lds_dwordx4 v[162:163], off
	v_lshl_add_u64 v[162:163], v[162:163], 0, s[2:3]
	s_add_i32 m0, s47, 0xe000
	s_nop 0
	global_load_lds_dwordx4 v[162:163], off
	s_waitcnt vmcnt(8)
	s_waitcnt lgkmcnt(0)
	s_barrier
	s_setprio 1
	s_waitcnt lgkmcnt(0)
	v_mfma_f32_16x16x32_bf16 v[142:145], v[114:117], v[186:189], v[142:145]
	v_mfma_f32_16x16x32_bf16 v[142:145], v[126:129], v[194:197], v[142:145]
	v_mfma_f32_16x16x32_bf16 v[138:141], v[130:133], v[186:189], v[138:141]
	v_mfma_f32_16x16x32_bf16 v[138:141], v[134:137], v[194:197], v[138:141]
	v_mfma_f32_16x16x32_bf16 v[110:113], v[114:117], v[198:201], v[110:113]
	v_mfma_f32_16x16x32_bf16 v[110:113], v[126:129], v[214:217], v[110:113]
	v_mfma_f32_16x16x32_bf16 v[106:109], v[130:133], v[198:201], v[106:109]
	v_mfma_f32_16x16x32_bf16 v[106:109], v[134:137], v[214:217], v[106:109]
	v_mfma_f32_16x16x32_bf16 v[94:97], v[114:117], v[218:221], v[94:97]
	v_mfma_f32_16x16x32_bf16 v[94:97], v[126:129], v[222:225], v[94:97]
	v_mfma_f32_16x16x32_bf16 v[90:93], v[130:133], v[218:221], v[90:93]
	v_mfma_f32_16x16x32_bf16 v[90:93], v[134:137], v[222:225], v[90:93]
	v_mfma_f32_16x16x32_bf16 v[78:81], v[114:117], v[226:229], v[78:81]
	v_mfma_f32_16x16x32_bf16 v[78:81], v[126:129], v[230:233], v[78:81]
	v_mfma_f32_16x16x32_bf16 v[74:77], v[130:133], v[226:229], v[74:77]
	v_mfma_f32_16x16x32_bf16 v[74:77], v[134:137], v[230:233], v[74:77]
	s_setprio 0
	s_setprio 1
	v_mfma_f32_16x16x32_bf16 v[122:125], v[146:149], v[186:189], v[122:125]
	v_mfma_f32_16x16x32_bf16 v[122:125], v[150:153], v[194:197], v[122:125]
	v_mfma_f32_16x16x32_bf16 v[118:121], v[158:161], v[186:189], v[118:121]
	v_mfma_f32_16x16x32_bf16 v[118:121], v[182:185], v[194:197], v[118:121]
	v_mfma_f32_16x16x32_bf16 v[102:105], v[146:149], v[198:201], v[102:105]
	v_mfma_f32_16x16x32_bf16 v[102:105], v[150:153], v[214:217], v[102:105]
	v_mfma_f32_16x16x32_bf16 v[98:101], v[158:161], v[198:201], v[98:101]
	v_mfma_f32_16x16x32_bf16 v[98:101], v[182:185], v[214:217], v[98:101]
	v_mfma_f32_16x16x32_bf16 v[86:89], v[146:149], v[218:221], v[86:89]
	v_mfma_f32_16x16x32_bf16 v[86:89], v[150:153], v[222:225], v[86:89]
	v_mfma_f32_16x16x32_bf16 v[82:85], v[158:161], v[218:221], v[82:85]
	v_mfma_f32_16x16x32_bf16 v[82:85], v[182:185], v[222:225], v[82:85]
	v_mfma_f32_16x16x32_bf16 v[70:73], v[146:149], v[226:229], v[70:73]
	v_mfma_f32_16x16x32_bf16 v[70:73], v[150:153], v[230:233], v[70:73]
	v_mfma_f32_16x16x32_bf16 v[66:69], v[158:161], v[226:229], v[66:69]
	v_mfma_f32_16x16x32_bf16 v[66:69], v[182:185], v[230:233], v[66:69]
	s_setprio 0
	s_barrier
	ds_read_b128 v[186:189], v193 offset:16384
	ds_read_b128 v[194:197], v193 offset:17408
	ds_read_b128 v[198:201], v193 offset:18432
	ds_read_b128 v[214:217], v193 offset:19456
	ds_read_b128 v[218:221], v193 offset:20480
	ds_read_b128 v[222:225], v193 offset:21504
	ds_read_b128 v[226:229], v193 offset:22528
	ds_read_b128 v[230:233], v193 offset:23552
	v_lshl_add_u64 v[162:163], s[20:21], 0, v[0:1]
	s_add_i32 s20, s22, s46
	s_mov_b32 m0, s20
	s_nop 0
	s_nop 0
	global_load_lds_dwordx4 v[162:163], off
	v_lshl_add_u64 v[202:203], v[162:163], 0, s[2:3]
	s_add_i32 m0, s20, 0x2000
	s_add_i32 s20, s23, s46
	global_load_lds_dwordx4 v[202:203], off
	v_lshl_add_u64 v[202:203], v[162:163], 0, s[12:13]
	s_mov_b32 m0, s20
	s_nop 0
	global_load_lds_dwordx4 v[202:203], off
	v_lshl_add_u64 v[202:203], v[162:163], 0, s[86:87]
	s_add_i32 m0, s20, 0x2000
	s_nop 0
	global_load_lds_dwordx4 v[202:203], off
	v_lshl_add_u64 v[202:203], s[60:61], 0, v[154:155]
	s_mov_b32 m0, s47
	v_lshl_add_u64 v[234:235], v[202:203], 0, s[2:3]
	global_load_lds_dwordx4 v[202:203], off
	s_mov_b32 m0, s68
	s_nop 0
	global_load_lds_dwordx4 v[234:235], off
	s_waitcnt vmcnt(8)
	s_waitcnt lgkmcnt(0)
	s_barrier
	s_setprio 1
	s_waitcnt lgkmcnt(0)
	v_mfma_f32_16x16x32_bf16 v[62:65], v[114:117], v[186:189], v[62:65]
	v_mfma_f32_16x16x32_bf16 v[62:65], v[126:129], v[194:197], v[62:65]
	v_mfma_f32_16x16x32_bf16 v[58:61], v[130:133], v[186:189], v[58:61]
	v_mfma_f32_16x16x32_bf16 v[58:61], v[134:137], v[194:197], v[58:61]
	v_mfma_f32_16x16x32_bf16 v[46:49], v[114:117], v[198:201], v[46:49]
	v_mfma_f32_16x16x32_bf16 v[46:49], v[126:129], v[214:217], v[46:49]
	v_mfma_f32_16x16x32_bf16 v[42:45], v[130:133], v[198:201], v[42:45]
	v_mfma_f32_16x16x32_bf16 v[42:45], v[134:137], v[214:217], v[42:45]
	v_mfma_f32_16x16x32_bf16 v[30:33], v[114:117], v[218:221], v[30:33]
	v_mfma_f32_16x16x32_bf16 v[30:33], v[126:129], v[222:225], v[30:33]
	v_mfma_f32_16x16x32_bf16 v[26:29], v[130:133], v[218:221], v[26:29]
	v_mfma_f32_16x16x32_bf16 v[26:29], v[134:137], v[222:225], v[26:29]
	v_mfma_f32_16x16x32_bf16 v[14:17], v[114:117], v[226:229], v[14:17]
	v_mfma_f32_16x16x32_bf16 v[14:17], v[126:129], v[230:233], v[14:17]
	v_mfma_f32_16x16x32_bf16 v[10:13], v[130:133], v[226:229], v[10:13]
	v_mfma_f32_16x16x32_bf16 v[10:13], v[134:137], v[230:233], v[10:13]
	s_setprio 0
	s_setprio 1
	v_mfma_f32_16x16x32_bf16 v[54:57], v[146:149], v[186:189], v[54:57]
	v_mfma_f32_16x16x32_bf16 v[54:57], v[150:153], v[194:197], v[54:57]
	v_mfma_f32_16x16x32_bf16 v[50:53], v[158:161], v[186:189], v[50:53]
	v_mfma_f32_16x16x32_bf16 v[50:53], v[182:185], v[194:197], v[50:53]
	v_mfma_f32_16x16x32_bf16 v[38:41], v[146:149], v[198:201], v[38:41]
	v_mfma_f32_16x16x32_bf16 v[38:41], v[150:153], v[214:217], v[38:41]
	v_mfma_f32_16x16x32_bf16 v[34:37], v[158:161], v[198:201], v[34:37]
	v_mfma_f32_16x16x32_bf16 v[34:37], v[182:185], v[214:217], v[34:37]
	v_mfma_f32_16x16x32_bf16 v[22:25], v[146:149], v[218:221], v[22:25]
	v_mfma_f32_16x16x32_bf16 v[22:25], v[150:153], v[222:225], v[22:25]
	v_mfma_f32_16x16x32_bf16 v[18:21], v[158:161], v[218:221], v[18:21]
	v_mfma_f32_16x16x32_bf16 v[18:21], v[182:185], v[222:225], v[18:21]
	v_mfma_f32_16x16x32_bf16 v[6:9], v[146:149], v[226:229], v[6:9]
	v_mfma_f32_16x16x32_bf16 v[6:9], v[150:153], v[230:233], v[6:9]
	v_mfma_f32_16x16x32_bf16 v[2:5], v[158:161], v[226:229], v[2:5]
	v_mfma_f32_16x16x32_bf16 v[2:5], v[182:185], v[230:233], v[2:5]
	s_setprio 0
	s_barrier
	s_add_i32 s20, 0, 0x18000
	s_add_i32 s21, 0, 0x1c000
	v_add_u32_e32 v134, s20, v191
	v_add_u32_e32 v182, s21, v191
	ds_read_b128 v[114:117], v134
	ds_read_b128 v[126:129], v134 offset:1024
	ds_read_b128 v[130:133], v134 offset:2048
	ds_read_b128 v[134:137], v134 offset:3072
	ds_read_b128 v[146:149], v182
	ds_read_b128 v[150:153], v182 offset:1024
	ds_read_b128 v[158:161], v182 offset:2048
	ds_read_b128 v[182:185], v182 offset:3072
	ds_read_b128 v[186:189], v193 offset:32768
	ds_read_b128 v[194:197], v193 offset:33792
	ds_read_b128 v[198:201], v193 offset:34816
	ds_read_b128 v[214:217], v193 offset:35840
	ds_read_b128 v[218:221], v193 offset:36864
	ds_read_b128 v[222:225], v193 offset:37888
	ds_read_b128 v[226:229], v193 offset:38912
	ds_read_b128 v[230:233], v193 offset:39936
	s_mov_b32 m0, s69
	v_lshl_add_u64 v[234:235], v[202:203], 0, s[12:13]
	global_load_lds_dwordx4 v[234:235], off
	v_lshl_add_u64 v[234:235], v[202:203], 0, s[86:87]
	s_mov_b32 m0, s76
	s_nop 0
	global_load_lds_dwordx4 v[234:235], off
	s_waitcnt vmcnt(8)
	s_waitcnt lgkmcnt(0)
	s_barrier
	s_setprio 1
	s_waitcnt lgkmcnt(0)
	v_mfma_f32_16x16x32_bf16 v[142:145], v[114:117], v[186:189], v[142:145]
	v_mfma_f32_16x16x32_bf16 v[142:145], v[126:129], v[194:197], v[142:145]
	v_mfma_f32_16x16x32_bf16 v[138:141], v[130:133], v[186:189], v[138:141]
	v_mfma_f32_16x16x32_bf16 v[138:141], v[134:137], v[194:197], v[138:141]
	v_mfma_f32_16x16x32_bf16 v[110:113], v[114:117], v[198:201], v[110:113]
	v_mfma_f32_16x16x32_bf16 v[110:113], v[126:129], v[214:217], v[110:113]
	v_mfma_f32_16x16x32_bf16 v[106:109], v[130:133], v[198:201], v[106:109]
	v_mfma_f32_16x16x32_bf16 v[106:109], v[134:137], v[214:217], v[106:109]
	v_mfma_f32_16x16x32_bf16 v[94:97], v[114:117], v[218:221], v[94:97]
	v_mfma_f32_16x16x32_bf16 v[94:97], v[126:129], v[222:225], v[94:97]
	v_mfma_f32_16x16x32_bf16 v[90:93], v[130:133], v[218:221], v[90:93]
	v_mfma_f32_16x16x32_bf16 v[90:93], v[134:137], v[222:225], v[90:93]
	v_mfma_f32_16x16x32_bf16 v[78:81], v[114:117], v[226:229], v[78:81]
	v_mfma_f32_16x16x32_bf16 v[78:81], v[126:129], v[230:233], v[78:81]
	v_mfma_f32_16x16x32_bf16 v[74:77], v[130:133], v[226:229], v[74:77]
	v_mfma_f32_16x16x32_bf16 v[74:77], v[134:137], v[230:233], v[74:77]
	s_setprio 0
	s_setprio 1
	v_mfma_f32_16x16x32_bf16 v[122:125], v[146:149], v[186:189], v[122:125]
	v_mfma_f32_16x16x32_bf16 v[122:125], v[150:153], v[194:197], v[122:125]
	v_mfma_f32_16x16x32_bf16 v[118:121], v[158:161], v[186:189], v[118:121]
	v_mfma_f32_16x16x32_bf16 v[118:121], v[182:185], v[194:197], v[118:121]
	v_mfma_f32_16x16x32_bf16 v[102:105], v[146:149], v[198:201], v[102:105]
	v_mfma_f32_16x16x32_bf16 v[102:105], v[150:153], v[214:217], v[102:105]
	v_mfma_f32_16x16x32_bf16 v[98:101], v[158:161], v[198:201], v[98:101]
	v_mfma_f32_16x16x32_bf16 v[98:101], v[182:185], v[214:217], v[98:101]
	v_mfma_f32_16x16x32_bf16 v[86:89], v[146:149], v[218:221], v[86:89]
	v_mfma_f32_16x16x32_bf16 v[86:89], v[150:153], v[222:225], v[86:89]
	v_mfma_f32_16x16x32_bf16 v[82:85], v[158:161], v[218:221], v[82:85]
	v_mfma_f32_16x16x32_bf16 v[82:85], v[182:185], v[222:225], v[82:85]
	v_mfma_f32_16x16x32_bf16 v[70:73], v[146:149], v[226:229], v[70:73]
	v_mfma_f32_16x16x32_bf16 v[70:73], v[150:153], v[230:233], v[70:73]
	v_mfma_f32_16x16x32_bf16 v[66:69], v[158:161], v[226:229], v[66:69]
	v_mfma_f32_16x16x32_bf16 v[66:69], v[182:185], v[230:233], v[66:69]
	s_setprio 0
	s_barrier
	ds_read_b128 v[186:189], v193 offset:49152
	ds_read_b128 v[194:197], v193 offset:50176
	ds_read_b128 v[198:201], v193 offset:51200
	ds_read_b128 v[214:217], v193 offset:52224
	ds_read_b128 v[218:221], v193 offset:53248
	ds_read_b128 v[222:225], v193 offset:54272
	ds_read_b128 v[226:229], v193 offset:55296
	ds_read_b128 v[230:233], v193 offset:56320
	s_add_i32 s20, s20, s46
	s_mov_b32 m0, s20
	v_lshl_add_u64 v[234:235], v[162:163], 0, s[34:35]
	global_load_lds_dwordx4 v[234:235], off
	v_lshl_add_u64 v[234:235], v[162:163], 0, s[96:97]
	s_add_i32 m0, s20, 0x2000
	s_add_i32 s20, s21, s46
	global_load_lds_dwordx4 v[234:235], off
	v_lshl_add_u64 v[234:235], v[162:163], 0, vcc
	s_mov_b32 m0, s20
	v_lshl_add_u64 v[162:163], v[162:163], 0, s[0:1]
	global_load_lds_dwordx4 v[234:235], off
	s_add_i32 m0, s20, 0x2000
	s_nop 0
	global_load_lds_dwordx4 v[162:163], off
	v_lshl_add_u64 v[162:163], v[202:203], 0, s[34:35]
	s_mov_b32 m0, s77
	s_nop 0
	global_load_lds_dwordx4 v[162:163], off
	v_lshl_add_u64 v[162:163], v[202:203], 0, s[96:97]
	s_mov_b32 m0, s78
	s_nop 0
	global_load_lds_dwordx4 v[162:163], off
	s_waitcnt vmcnt(8)
	s_waitcnt lgkmcnt(0)
	s_barrier
	s_setprio 1
	s_waitcnt lgkmcnt(0)
	v_mfma_f32_16x16x32_bf16 v[62:65], v[114:117], v[186:189], v[62:65]
	v_mfma_f32_16x16x32_bf16 v[62:65], v[126:129], v[194:197], v[62:65]
	v_mfma_f32_16x16x32_bf16 v[58:61], v[130:133], v[186:189], v[58:61]
	v_mfma_f32_16x16x32_bf16 v[58:61], v[134:137], v[194:197], v[58:61]
	v_mfma_f32_16x16x32_bf16 v[46:49], v[114:117], v[198:201], v[46:49]
	v_mfma_f32_16x16x32_bf16 v[46:49], v[126:129], v[214:217], v[46:49]
	v_mfma_f32_16x16x32_bf16 v[42:45], v[130:133], v[198:201], v[42:45]
	v_mfma_f32_16x16x32_bf16 v[42:45], v[134:137], v[214:217], v[42:45]
	v_mfma_f32_16x16x32_bf16 v[30:33], v[114:117], v[218:221], v[30:33]
	v_mfma_f32_16x16x32_bf16 v[30:33], v[126:129], v[222:225], v[30:33]
	v_mfma_f32_16x16x32_bf16 v[26:29], v[130:133], v[218:221], v[26:29]
	v_mfma_f32_16x16x32_bf16 v[26:29], v[134:137], v[222:225], v[26:29]
	v_mfma_f32_16x16x32_bf16 v[14:17], v[114:117], v[226:229], v[14:17]
	v_mfma_f32_16x16x32_bf16 v[14:17], v[126:129], v[230:233], v[14:17]
	v_mfma_f32_16x16x32_bf16 v[10:13], v[130:133], v[226:229], v[10:13]
	v_mfma_f32_16x16x32_bf16 v[10:13], v[134:137], v[230:233], v[10:13]
	s_add_i32 s84, s84, 2
	s_add_u32 s56, s56, 0x100
	s_addc_u32 s57, s57, 0
	s_add_u32 s62, s62, 0x100
	s_addc_u32 s63, s63, 0
	s_setprio 0
	s_setprio 1
	v_mfma_f32_16x16x32_bf16 v[54:57], v[146:149], v[186:189], v[54:57]
	v_mfma_f32_16x16x32_bf16 v[54:57], v[150:153], v[194:197], v[54:57]
	v_mfma_f32_16x16x32_bf16 v[50:53], v[158:161], v[186:189], v[50:53]
	v_mfma_f32_16x16x32_bf16 v[50:53], v[182:185], v[194:197], v[50:53]
	v_mfma_f32_16x16x32_bf16 v[38:41], v[146:149], v[198:201], v[38:41]
	v_mfma_f32_16x16x32_bf16 v[38:41], v[150:153], v[214:217], v[38:41]
	v_mfma_f32_16x16x32_bf16 v[34:37], v[158:161], v[198:201], v[34:37]
	v_mfma_f32_16x16x32_bf16 v[34:37], v[182:185], v[214:217], v[34:37]
	v_mfma_f32_16x16x32_bf16 v[22:25], v[146:149], v[218:221], v[22:25]
	v_mfma_f32_16x16x32_bf16 v[22:25], v[150:153], v[222:225], v[22:25]
	v_mfma_f32_16x16x32_bf16 v[18:21], v[158:161], v[218:221], v[18:21]
	v_mfma_f32_16x16x32_bf16 v[18:21], v[182:185], v[222:225], v[18:21]
	v_mfma_f32_16x16x32_bf16 v[6:9], v[146:149], v[226:229], v[6:9]
	v_mfma_f32_16x16x32_bf16 v[6:9], v[150:153], v[230:233], v[6:9]
	v_mfma_f32_16x16x32_bf16 v[2:5], v[158:161], v[226:229], v[2:5]
	v_mfma_f32_16x16x32_bf16 v[2:5], v[182:185], v[230:233], v[2:5]
	s_setprio 0
	s_barrier
	s_cmp_gt_u32 s84, 41
	s_cbranch_scc0 .LBB0_446
	s_and_b64 vcc, exec, s[40:41]
	s_cbranch_vccz .LBB0_449
	s_barrier

.Lmid1_488:
	s_add_i32 s22, 0, 0x10000
	s_add_i32 s23, 0, 0x14000
	s_add_u32 s20, s68, 0xfffc0080
	s_addc_u32 s21, s69, -1
	s_cmp_eq_u32 s97, 12
	s_cselect_b32 s77, s57, s21
	s_cselect_b32 s76, s86, s20
	s_cselect_b32 s21, s51, s96
	s_cselect_b32 s20, s87, s91
	s_add_i32 m0, s43, 0xc000
	v_lshl_add_u64 v[202:203], s[68:69], 0, v[132:133]
	global_load_lds_dwordx4 v[202:203], off
	v_lshl_add_u64 v[202:203], v[202:203], 0, s[72:73]
	s_add_i32 m0, s43, 0xe000
	s_nop 0
	global_load_lds_dwordx4 v[202:203], off
	s_waitcnt vmcnt(8)
	s_waitcnt lgkmcnt(0)
	s_barrier
	s_setprio 1
	s_waitcnt lgkmcnt(0)
	v_mfma_f32_16x16x32_bf16 v[126:129], v[134:137], v[190:193], 0
	v_mfma_f32_16x16x32_bf16 v[126:129], v[144:147], v[194:197], v[126:129]
	v_mfma_f32_16x16x32_bf16 v[114:117], v[148:151], v[190:193], 0
	v_mfma_f32_16x16x32_bf16 v[114:117], v[152:155], v[194:197], v[114:117]
	v_mfma_f32_16x16x32_bf16 v[110:113], v[134:137], v[198:201], 0
	v_mfma_f32_16x16x32_bf16 v[110:113], v[144:147], v[214:217], v[110:113]
	v_mfma_f32_16x16x32_bf16 v[98:101], v[148:151], v[198:201], 0
	v_mfma_f32_16x16x32_bf16 v[98:101], v[152:155], v[214:217], v[98:101]
	v_mfma_f32_16x16x32_bf16 v[94:97], v[134:137], v[218:221], 0
	v_mfma_f32_16x16x32_bf16 v[94:97], v[144:147], v[222:225], v[94:97]
	v_mfma_f32_16x16x32_bf16 v[82:85], v[148:151], v[218:221], 0
	v_mfma_f32_16x16x32_bf16 v[82:85], v[152:155], v[222:225], v[82:85]
	v_mfma_f32_16x16x32_bf16 v[78:81], v[134:137], v[226:229], 0
	v_mfma_f32_16x16x32_bf16 v[78:81], v[144:147], v[230:233], v[78:81]
	v_mfma_f32_16x16x32_bf16 v[66:69], v[148:151], v[226:229], 0
	v_mfma_f32_16x16x32_bf16 v[66:69], v[152:155], v[230:233], v[66:69]
	s_setprio 0
	s_setprio 1
	v_mfma_f32_16x16x32_bf16 v[122:125], v[156:159], v[190:193], 0
	v_mfma_f32_16x16x32_bf16 v[122:125], v[160:163], v[194:197], v[122:125]
	v_mfma_f32_16x16x32_bf16 v[118:121], v[182:185], v[190:193], 0
	v_mfma_f32_16x16x32_bf16 v[118:121], v[186:189], v[194:197], v[118:121]
	v_mfma_f32_16x16x32_bf16 v[106:109], v[156:159], v[198:201], 0
	v_mfma_f32_16x16x32_bf16 v[106:109], v[160:163], v[214:217], v[106:109]
	v_mfma_f32_16x16x32_bf16 v[102:105], v[182:185], v[198:201], 0
	v_mfma_f32_16x16x32_bf16 v[102:105], v[186:189], v[214:217], v[102:105]
	v_mfma_f32_16x16x32_bf16 v[90:93], v[156:159], v[218:221], 0
	v_mfma_f32_16x16x32_bf16 v[90:93], v[160:163], v[222:225], v[90:93]
	v_mfma_f32_16x16x32_bf16 v[86:89], v[182:185], v[218:221], 0
	v_mfma_f32_16x16x32_bf16 v[86:89], v[186:189], v[222:225], v[86:89]
	v_mfma_f32_16x16x32_bf16 v[74:77], v[156:159], v[226:229], 0
	v_mfma_f32_16x16x32_bf16 v[74:77], v[160:163], v[230:233], v[74:77]
	v_mfma_f32_16x16x32_bf16 v[70:73], v[182:185], v[226:229], 0
	v_mfma_f32_16x16x32_bf16 v[70:73], v[186:189], v[230:233], v[70:73]
	s_setprio 0
	s_barrier
	ds_read_b128 v[190:193], v142 offset:16384
	ds_read_b128 v[194:197], v142 offset:17408
	ds_read_b128 v[198:201], v142 offset:18432
	ds_read_b128 v[214:217], v142 offset:19456
	ds_read_b128 v[218:221], v142 offset:20480
	ds_read_b128 v[222:225], v142 offset:21504
	ds_read_b128 v[226:229], v142 offset:22528
	ds_read_b128 v[230:233], v142 offset:23552
	v_lshl_add_u64 v[202:203], s[20:21], 0, v[0:1]
	s_add_i32 s20, s22, s14
	s_mov_b32 m0, s20
	s_nop 0
	s_nop 0
	global_load_lds_dwordx4 v[202:203], off
	v_lshl_add_u64 v[234:235], v[202:203], 0, s[72:73]
	s_add_i32 m0, s20, 0x2000
	s_add_i32 s20, s23, s14
	global_load_lds_dwordx4 v[234:235], off
	v_lshl_add_u64 v[234:235], v[202:203], 0, s[28:29]
	s_mov_b32 m0, s20
	s_nop 0
	global_load_lds_dwordx4 v[234:235], off
	v_lshl_add_u64 v[234:235], v[202:203], 0, s[82:83]
	s_add_i32 m0, s20, 0x2000
	s_nop 0
	global_load_lds_dwordx4 v[234:235], off
	v_lshl_add_u64 v[234:235], s[76:77], 0, v[130:131]
	s_mov_b32 m0, s43
	v_lshl_add_u64 v[236:237], v[234:235], 0, s[72:73]
	global_load_lds_dwordx4 v[234:235], off
	s_mov_b32 m0, s46
	s_nop 0
	global_load_lds_dwordx4 v[236:237], off
	s_waitcnt vmcnt(8)
	s_waitcnt lgkmcnt(0)
	s_barrier
	s_setprio 1
	s_waitcnt lgkmcnt(0)
	v_mfma_f32_16x16x32_bf16 v[62:65], v[134:137], v[190:193], 0
	v_mfma_f32_16x16x32_bf16 v[62:65], v[144:147], v[194:197], v[62:65]
	v_mfma_f32_16x16x32_bf16 v[50:53], v[148:151], v[190:193], 0
	v_mfma_f32_16x16x32_bf16 v[50:53], v[152:155], v[194:197], v[50:53]
	v_mfma_f32_16x16x32_bf16 v[46:49], v[134:137], v[198:201], 0
	v_mfma_f32_16x16x32_bf16 v[46:49], v[144:147], v[214:217], v[46:49]
	v_mfma_f32_16x16x32_bf16 v[34:37], v[148:151], v[198:201], 0
	v_mfma_f32_16x16x32_bf16 v[34:37], v[152:155], v[214:217], v[34:37]
	v_mfma_f32_16x16x32_bf16 v[30:33], v[134:137], v[218:221], 0
	v_mfma_f32_16x16x32_bf16 v[30:33], v[144:147], v[222:225], v[30:33]
	v_mfma_f32_16x16x32_bf16 v[18:21], v[148:151], v[218:221], 0
	v_mfma_f32_16x16x32_bf16 v[18:21], v[152:155], v[222:225], v[18:21]
	v_mfma_f32_16x16x32_bf16 v[14:17], v[134:137], v[226:229], 0
	v_mfma_f32_16x16x32_bf16 v[14:17], v[144:147], v[230:233], v[14:17]
	v_mfma_f32_16x16x32_bf16 v[6:9], v[148:151], v[226:229], 0
	v_mfma_f32_16x16x32_bf16 v[6:9], v[152:155], v[230:233], v[6:9]
	s_setprio 0
	s_setprio 1
	v_mfma_f32_16x16x32_bf16 v[58:61], v[156:159], v[190:193], 0
	v_mfma_f32_16x16x32_bf16 v[58:61], v[160:163], v[194:197], v[58:61]
	v_mfma_f32_16x16x32_bf16 v[54:57], v[182:185], v[190:193], 0
	v_mfma_f32_16x16x32_bf16 v[54:57], v[186:189], v[194:197], v[54:57]
	v_mfma_f32_16x16x32_bf16 v[42:45], v[156:159], v[198:201], 0
	v_mfma_f32_16x16x32_bf16 v[42:45], v[160:163], v[214:217], v[42:45]
	v_mfma_f32_16x16x32_bf16 v[38:41], v[182:185], v[198:201], 0
	v_mfma_f32_16x16x32_bf16 v[38:41], v[186:189], v[214:217], v[38:41]
	v_mfma_f32_16x16x32_bf16 v[26:29], v[156:159], v[218:221], 0
	v_mfma_f32_16x16x32_bf16 v[26:29], v[160:163], v[222:225], v[26:29]
	v_mfma_f32_16x16x32_bf16 v[22:25], v[182:185], v[218:221], 0
	v_mfma_f32_16x16x32_bf16 v[22:25], v[186:189], v[222:225], v[22:25]
	v_mfma_f32_16x16x32_bf16 v[10:13], v[156:159], v[226:229], 0
	v_mfma_f32_16x16x32_bf16 v[10:13], v[160:163], v[230:233], v[10:13]
	v_mfma_f32_16x16x32_bf16 v[2:5], v[182:185], v[226:229], 0
	v_mfma_f32_16x16x32_bf16 v[2:5], v[186:189], v[230:233], v[2:5]
	s_setprio 0
	s_barrier
	s_add_i32 s20, 0, 0x18000
	v_add_u32_e32 v143, s20, v139
	s_add_i32 s21, 0, 0x1c000
	ds_read_b128 v[134:137], v143
	ds_read_b128 v[144:147], v143 offset:1024
	ds_read_b128 v[148:151], v143 offset:2048
	ds_read_b128 v[152:155], v143 offset:3072
	v_add_u32_e32 v143, s21, v139
	ds_read_b128 v[156:159], v143
	ds_read_b128 v[160:163], v143 offset:1024
	ds_read_b128 v[182:185], v143 offset:2048
	ds_read_b128 v[186:189], v143 offset:3072
	ds_read_b128 v[190:193], v142 offset:32768
	ds_read_b128 v[194:197], v142 offset:33792
	ds_read_b128 v[198:201], v142 offset:34816
	ds_read_b128 v[214:217], v142 offset:35840
	ds_read_b128 v[218:221], v142 offset:36864
	ds_read_b128 v[222:225], v142 offset:37888
	ds_read_b128 v[226:229], v142 offset:38912
	ds_read_b128 v[230:233], v142 offset:39936
	s_mov_b32 m0, s47
	v_lshl_add_u64 v[236:237], v[234:235], 0, s[28:29]
	global_load_lds_dwordx4 v[236:237], off
	v_lshl_add_u64 v[236:237], v[234:235], 0, s[82:83]
	s_mov_b32 m0, s78
	s_nop 0
	global_load_lds_dwordx4 v[236:237], off
	s_waitcnt vmcnt(8)
	s_waitcnt lgkmcnt(0)
	s_barrier
	s_setprio 1
	s_waitcnt lgkmcnt(0)
	v_mfma_f32_16x16x32_bf16 v[126:129], v[134:137], v[190:193], v[126:129]
	v_mfma_f32_16x16x32_bf16 v[126:129], v[144:147], v[194:197], v[126:129]
	v_mfma_f32_16x16x32_bf16 v[114:117], v[148:151], v[190:193], v[114:117]
	v_mfma_f32_16x16x32_bf16 v[114:117], v[152:155], v[194:197], v[114:117]
	v_mfma_f32_16x16x32_bf16 v[110:113], v[134:137], v[198:201], v[110:113]
	v_mfma_f32_16x16x32_bf16 v[110:113], v[144:147], v[214:217], v[110:113]
	v_mfma_f32_16x16x32_bf16 v[98:101], v[148:151], v[198:201], v[98:101]
	v_mfma_f32_16x16x32_bf16 v[98:101], v[152:155], v[214:217], v[98:101]
	v_mfma_f32_16x16x32_bf16 v[94:97], v[134:137], v[218:221], v[94:97]
	v_mfma_f32_16x16x32_bf16 v[94:97], v[144:147], v[222:225], v[94:97]
	v_mfma_f32_16x16x32_bf16 v[82:85], v[148:151], v[218:221], v[82:85]
	v_mfma_f32_16x16x32_bf16 v[82:85], v[152:155], v[222:225], v[82:85]
	v_mfma_f32_16x16x32_bf16 v[78:81], v[134:137], v[226:229], v[78:81]
	v_mfma_f32_16x16x32_bf16 v[78:81], v[144:147], v[230:233], v[78:81]
	v_mfma_f32_16x16x32_bf16 v[66:69], v[148:151], v[226:229], v[66:69]
	v_mfma_f32_16x16x32_bf16 v[66:69], v[152:155], v[230:233], v[66:69]
	s_setprio 0
	s_setprio 1
	v_mfma_f32_16x16x32_bf16 v[122:125], v[156:159], v[190:193], v[122:125]
	v_mfma_f32_16x16x32_bf16 v[122:125], v[160:163], v[194:197], v[122:125]
	v_mfma_f32_16x16x32_bf16 v[118:121], v[182:185], v[190:193], v[118:121]
	v_mfma_f32_16x16x32_bf16 v[118:121], v[186:189], v[194:197], v[118:121]
	v_mfma_f32_16x16x32_bf16 v[106:109], v[156:159], v[198:201], v[106:109]
	v_mfma_f32_16x16x32_bf16 v[106:109], v[160:163], v[214:217], v[106:109]
	v_mfma_f32_16x16x32_bf16 v[102:105], v[182:185], v[198:201], v[102:105]
	v_mfma_f32_16x16x32_bf16 v[102:105], v[186:189], v[214:217], v[102:105]
	v_mfma_f32_16x16x32_bf16 v[90:93], v[156:159], v[218:221], v[90:93]
	v_mfma_f32_16x16x32_bf16 v[90:93], v[160:163], v[222:225], v[90:93]
	v_mfma_f32_16x16x32_bf16 v[86:89], v[182:185], v[218:221], v[86:89]
	v_mfma_f32_16x16x32_bf16 v[86:89], v[186:189], v[222:225], v[86:89]
	v_mfma_f32_16x16x32_bf16 v[74:77], v[156:159], v[226:229], v[74:77]
	v_mfma_f32_16x16x32_bf16 v[74:77], v[160:163], v[230:233], v[74:77]
	v_mfma_f32_16x16x32_bf16 v[70:73], v[182:185], v[226:229], v[70:73]
	v_mfma_f32_16x16x32_bf16 v[70:73], v[186:189], v[230:233], v[70:73]
	s_setprio 0
	s_barrier
	ds_read_b128 v[190:193], v142 offset:49152
	ds_read_b128 v[194:197], v142 offset:50176
	ds_read_b128 v[198:201], v142 offset:51200
	ds_read_b128 v[214:217], v142 offset:52224
	ds_read_b128 v[218:221], v142 offset:53248
	ds_read_b128 v[222:225], v142 offset:54272
	ds_read_b128 v[226:229], v142 offset:55296
	ds_read_b128 v[230:233], v142 offset:56320
	s_add_i32 s20, s20, s14
	s_mov_b32 m0, s20
	v_lshl_add_u64 v[236:237], v[202:203], 0, s[34:35]
	global_load_lds_dwordx4 v[236:237], off
	v_lshl_add_u64 v[236:237], v[202:203], 0, s[38:39]
	s_add_i32 m0, s20, 0x2000
	s_add_i32 s20, s21, s14
	global_load_lds_dwordx4 v[236:237], off
	v_lshl_add_u64 v[236:237], v[202:203], 0, s[44:45]
	s_mov_b32 m0, s20
	v_lshl_add_u64 v[202:203], v[202:203], 0, s[10:11]
	global_load_lds_dwordx4 v[236:237], off
	s_add_i32 m0, s20, 0x2000
	s_nop 0
	global_load_lds_dwordx4 v[202:203], off
	v_lshl_add_u64 v[202:203], v[234:235], 0, s[34:35]
	s_mov_b32 m0, s79
	s_nop 0
	global_load_lds_dwordx4 v[202:203], off
	v_lshl_add_u64 v[202:203], v[234:235], 0, s[38:39]
	s_mov_b32 m0, s88
	s_nop 0
	global_load_lds_dwordx4 v[202:203], off
	s_waitcnt vmcnt(8)
	s_waitcnt lgkmcnt(0)
	s_barrier
	s_setprio 1
	s_waitcnt lgkmcnt(0)
	v_mfma_f32_16x16x32_bf16 v[62:65], v[134:137], v[190:193], v[62:65]
	v_mfma_f32_16x16x32_bf16 v[62:65], v[144:147], v[194:197], v[62:65]
	v_mfma_f32_16x16x32_bf16 v[50:53], v[148:151], v[190:193], v[50:53]
	v_mfma_f32_16x16x32_bf16 v[50:53], v[152:155], v[194:197], v[50:53]
	v_mfma_f32_16x16x32_bf16 v[46:49], v[134:137], v[198:201], v[46:49]
	v_mfma_f32_16x16x32_bf16 v[46:49], v[144:147], v[214:217], v[46:49]
	v_mfma_f32_16x16x32_bf16 v[34:37], v[148:151], v[198:201], v[34:37]
	v_mfma_f32_16x16x32_bf16 v[34:37], v[152:155], v[214:217], v[34:37]
	v_mfma_f32_16x16x32_bf16 v[30:33], v[134:137], v[218:221], v[30:33]
	v_mfma_f32_16x16x32_bf16 v[30:33], v[144:147], v[222:225], v[30:33]
	v_mfma_f32_16x16x32_bf16 v[18:21], v[148:151], v[218:221], v[18:21]
	v_mfma_f32_16x16x32_bf16 v[18:21], v[152:155], v[222:225], v[18:21]
	v_mfma_f32_16x16x32_bf16 v[14:17], v[134:137], v[226:229], v[14:17]
	v_mfma_f32_16x16x32_bf16 v[14:17], v[144:147], v[230:233], v[14:17]
	v_mfma_f32_16x16x32_bf16 v[6:9], v[148:151], v[226:229], v[6:9]
	v_mfma_f32_16x16x32_bf16 v[6:9], v[152:155], v[230:233], v[6:9]
	s_add_i32 s97, s97, 2
	s_add_u32 s68, s68, 0x100
	s_addc_u32 s69, s69, 0
	s_add_u32 s91, s91, 0x100
	s_addc_u32 s96, s96, 0
	s_setprio 0
	s_setprio 1
	v_mfma_f32_16x16x32_bf16 v[58:61], v[156:159], v[190:193], v[58:61]
	v_mfma_f32_16x16x32_bf16 v[58:61], v[160:163], v[194:197], v[58:61]
	v_mfma_f32_16x16x32_bf16 v[54:57], v[182:185], v[190:193], v[54:57]
	v_mfma_f32_16x16x32_bf16 v[54:57], v[186:189], v[194:197], v[54:57]
	v_mfma_f32_16x16x32_bf16 v[42:45], v[156:159], v[198:201], v[42:45]
	v_mfma_f32_16x16x32_bf16 v[42:45], v[160:163], v[214:217], v[42:45]
	v_mfma_f32_16x16x32_bf16 v[38:41], v[182:185], v[198:201], v[38:41]
	v_mfma_f32_16x16x32_bf16 v[38:41], v[186:189], v[214:217], v[38:41]
	v_mfma_f32_16x16x32_bf16 v[26:29], v[156:159], v[218:221], v[26:29]
	v_mfma_f32_16x16x32_bf16 v[26:29], v[160:163], v[222:225], v[26:29]
	v_mfma_f32_16x16x32_bf16 v[22:25], v[182:185], v[218:221], v[22:25]
	v_mfma_f32_16x16x32_bf16 v[22:25], v[186:189], v[222:225], v[22:25]
	v_mfma_f32_16x16x32_bf16 v[10:13], v[156:159], v[226:229], v[10:13]
	v_mfma_f32_16x16x32_bf16 v[10:13], v[160:163], v[230:233], v[10:13]
	v_mfma_f32_16x16x32_bf16 v[2:5], v[182:185], v[226:229], v[2:5]
	v_mfma_f32_16x16x32_bf16 v[2:5], v[186:189], v[230:233], v[2:5]
	s_setprio 0
	s_barrier
	s_branch .LBB0_488
	.p2alignl 6, 3212836864
.LBB0_488:
	s_add_i32 s22, 0, 0x10000
	v_add_u32_e32 v143, s22, v139
	s_add_i32 s23, 0, 0x14000
	ds_read_b128 v[134:137], v143
	ds_read_b128 v[144:147], v143 offset:1024
	ds_read_b128 v[148:151], v143 offset:2048
	ds_read_b128 v[152:155], v143 offset:3072
	v_add_u32_e32 v143, s23, v139
	ds_read_b128 v[156:159], v143
	ds_read_b128 v[160:163], v143 offset:1024
	ds_read_b128 v[182:185], v143 offset:2048
	ds_read_b128 v[186:189], v143 offset:3072
	ds_read_b128 v[190:193], v142
	ds_read_b128 v[194:197], v142 offset:1024
	ds_read_b128 v[198:201], v142 offset:2048
	ds_read_b128 v[214:217], v142 offset:3072
	ds_read_b128 v[218:221], v142 offset:4096
	ds_read_b128 v[222:225], v142 offset:5120
	ds_read_b128 v[226:229], v142 offset:6144
	ds_read_b128 v[230:233], v142 offset:7168
	s_add_u32 s20, s68, 0xfffc0080
	s_addc_u32 s21, s69, -1
	s_cmp_eq_u32 s97, 12
	s_cselect_b32 s77, s57, s21
	s_cselect_b32 s76, s86, s20
	s_cselect_b32 s21, s51, s96
	s_cselect_b32 s20, s87, s91
	s_add_i32 m0, s43, 0xc000
	v_lshl_add_u64 v[202:203], s[68:69], 0, v[132:133]
	global_load_lds_dwordx4 v[202:203], off
	v_lshl_add_u64 v[202:203], v[202:203], 0, s[72:73]
	s_add_i32 m0, s43, 0xe000
	s_nop 0
	global_load_lds_dwordx4 v[202:203], off
	s_waitcnt vmcnt(8)
	s_waitcnt lgkmcnt(0)
	s_barrier
	s_setprio 1
	s_waitcnt lgkmcnt(0)
	v_mfma_f32_16x16x32_bf16 v[126:129], v[134:137], v[190:193], v[126:129]
	v_mfma_f32_16x16x32_bf16 v[126:129], v[144:147], v[194:197], v[126:129]
	v_mfma_f32_16x16x32_bf16 v[114:117], v[148:151], v[190:193], v[114:117]
	v_mfma_f32_16x16x32_bf16 v[114:117], v[152:155], v[194:197], v[114:117]
	v_mfma_f32_16x16x32_bf16 v[110:113], v[134:137], v[198:201], v[110:113]
	v_mfma_f32_16x16x32_bf16 v[110:113], v[144:147], v[214:217], v[110:113]
	v_mfma_f32_16x16x32_bf16 v[98:101], v[148:151], v[198:201], v[98:101]
	v_mfma_f32_16x16x32_bf16 v[98:101], v[152:155], v[214:217], v[98:101]
	v_mfma_f32_16x16x32_bf16 v[94:97], v[134:137], v[218:221], v[94:97]
	v_mfma_f32_16x16x32_bf16 v[94:97], v[144:147], v[222:225], v[94:97]
	v_mfma_f32_16x16x32_bf16 v[82:85], v[148:151], v[218:221], v[82:85]
	v_mfma_f32_16x16x32_bf16 v[82:85], v[152:155], v[222:225], v[82:85]
	v_mfma_f32_16x16x32_bf16 v[78:81], v[134:137], v[226:229], v[78:81]
	v_mfma_f32_16x16x32_bf16 v[78:81], v[144:147], v[230:233], v[78:81]
	v_mfma_f32_16x16x32_bf16 v[66:69], v[148:151], v[226:229], v[66:69]
	v_mfma_f32_16x16x32_bf16 v[66:69], v[152:155], v[230:233], v[66:69]
	s_setprio 0
	s_setprio 1
	v_mfma_f32_16x16x32_bf16 v[122:125], v[156:159], v[190:193], v[122:125]
	v_mfma_f32_16x16x32_bf16 v[122:125], v[160:163], v[194:197], v[122:125]
	v_mfma_f32_16x16x32_bf16 v[118:121], v[182:185], v[190:193], v[118:121]
	v_mfma_f32_16x16x32_bf16 v[118:121], v[186:189], v[194:197], v[118:121]
	v_mfma_f32_16x16x32_bf16 v[106:109], v[156:159], v[198:201], v[106:109]
	v_mfma_f32_16x16x32_bf16 v[106:109], v[160:163], v[214:217], v[106:109]
	v_mfma_f32_16x16x32_bf16 v[102:105], v[182:185], v[198:201], v[102:105]
	v_mfma_f32_16x16x32_bf16 v[102:105], v[186:189], v[214:217], v[102:105]
	v_mfma_f32_16x16x32_bf16 v[90:93], v[156:159], v[218:221], v[90:93]
	v_mfma_f32_16x16x32_bf16 v[90:93], v[160:163], v[222:225], v[90:93]
	v_mfma_f32_16x16x32_bf16 v[86:89], v[182:185], v[218:221], v[86:89]
	v_mfma_f32_16x16x32_bf16 v[86:89], v[186:189], v[222:225], v[86:89]
	v_mfma_f32_16x16x32_bf16 v[74:77], v[156:159], v[226:229], v[74:77]
	v_mfma_f32_16x16x32_bf16 v[74:77], v[160:163], v[230:233], v[74:77]
	v_mfma_f32_16x16x32_bf16 v[70:73], v[182:185], v[226:229], v[70:73]
	v_mfma_f32_16x16x32_bf16 v[70:73], v[186:189], v[230:233], v[70:73]
	s_setprio 0
	s_barrier
	ds_read_b128 v[190:193], v142 offset:16384
	ds_read_b128 v[194:197], v142 offset:17408
	ds_read_b128 v[198:201], v142 offset:18432
	ds_read_b128 v[214:217], v142 offset:19456
	ds_read_b128 v[218:221], v142 offset:20480
	ds_read_b128 v[222:225], v142 offset:21504
	ds_read_b128 v[226:229], v142 offset:22528
	ds_read_b128 v[230:233], v142 offset:23552
	v_lshl_add_u64 v[202:203], s[20:21], 0, v[0:1]
	s_add_i32 s20, s22, s14
	s_mov_b32 m0, s20
	s_nop 0
	s_nop 0
	global_load_lds_dwordx4 v[202:203], off
	v_lshl_add_u64 v[234:235], v[202:203], 0, s[72:73]
	s_add_i32 m0, s20, 0x2000
	s_add_i32 s20, s23, s14
	global_load_lds_dwordx4 v[234:235], off
	v_lshl_add_u64 v[234:235], v[202:203], 0, s[28:29]
	s_mov_b32 m0, s20
	s_nop 0
	global_load_lds_dwordx4 v[234:235], off
	v_lshl_add_u64 v[234:235], v[202:203], 0, s[82:83]
	s_add_i32 m0, s20, 0x2000
	s_nop 0
	global_load_lds_dwordx4 v[234:235], off
	v_lshl_add_u64 v[234:235], s[76:77], 0, v[130:131]
	s_mov_b32 m0, s43
	v_lshl_add_u64 v[236:237], v[234:235], 0, s[72:73]
	global_load_lds_dwordx4 v[234:235], off
	s_mov_b32 m0, s46
	s_nop 0
	global_load_lds_dwordx4 v[236:237], off
	s_waitcnt vmcnt(8)
	s_waitcnt lgkmcnt(0)
	s_barrier
	s_setprio 1
	s_waitcnt lgkmcnt(0)
	v_mfma_f32_16x16x32_bf16 v[62:65], v[134:137], v[190:193], v[62:65]
	v_mfma_f32_16x16x32_bf16 v[62:65], v[144:147], v[194:197], v[62:65]
	v_mfma_f32_16x16x32_bf16 v[50:53], v[148:151], v[190:193], v[50:53]
	v_mfma_f32_16x16x32_bf16 v[50:53], v[152:155], v[194:197], v[50:53]
	v_mfma_f32_16x16x32_bf16 v[46:49], v[134:137], v[198:201], v[46:49]
	v_mfma_f32_16x16x32_bf16 v[46:49], v[144:147], v[214:217], v[46:49]
	v_mfma_f32_16x16x32_bf16 v[34:37], v[148:151], v[198:201], v[34:37]
	v_mfma_f32_16x16x32_bf16 v[34:37], v[152:155], v[214:217], v[34:37]
	v_mfma_f32_16x16x32_bf16 v[30:33], v[134:137], v[218:221], v[30:33]
	v_mfma_f32_16x16x32_bf16 v[30:33], v[144:147], v[222:225], v[30:33]
	v_mfma_f32_16x16x32_bf16 v[18:21], v[148:151], v[218:221], v[18:21]
	v_mfma_f32_16x16x32_bf16 v[18:21], v[152:155], v[222:225], v[18:21]
	v_mfma_f32_16x16x32_bf16 v[14:17], v[134:137], v[226:229], v[14:17]
	v_mfma_f32_16x16x32_bf16 v[14:17], v[144:147], v[230:233], v[14:17]
	v_mfma_f32_16x16x32_bf16 v[6:9], v[148:151], v[226:229], v[6:9]
	v_mfma_f32_16x16x32_bf16 v[6:9], v[152:155], v[230:233], v[6:9]
	s_setprio 0
	s_setprio 1
	v_mfma_f32_16x16x32_bf16 v[58:61], v[156:159], v[190:193], v[58:61]
	v_mfma_f32_16x16x32_bf16 v[58:61], v[160:163], v[194:197], v[58:61]
	v_mfma_f32_16x16x32_bf16 v[54:57], v[182:185], v[190:193], v[54:57]
	v_mfma_f32_16x16x32_bf16 v[54:57], v[186:189], v[194:197], v[54:57]
	v_mfma_f32_16x16x32_bf16 v[42:45], v[156:159], v[198:201], v[42:45]
	v_mfma_f32_16x16x32_bf16 v[42:45], v[160:163], v[214:217], v[42:45]
	v_mfma_f32_16x16x32_bf16 v[38:41], v[182:185], v[198:201], v[38:41]
	v_mfma_f32_16x16x32_bf16 v[38:41], v[186:189], v[214:217], v[38:41]
	v_mfma_f32_16x16x32_bf16 v[26:29], v[156:159], v[218:221], v[26:29]
	v_mfma_f32_16x16x32_bf16 v[26:29], v[160:163], v[222:225], v[26:29]
	v_mfma_f32_16x16x32_bf16 v[22:25], v[182:185], v[218:221], v[22:25]
	v_mfma_f32_16x16x32_bf16 v[22:25], v[186:189], v[222:225], v[22:25]
	v_mfma_f32_16x16x32_bf16 v[10:13], v[156:159], v[226:229], v[10:13]
	v_mfma_f32_16x16x32_bf16 v[10:13], v[160:163], v[230:233], v[10:13]
	v_mfma_f32_16x16x32_bf16 v[2:5], v[182:185], v[226:229], v[2:5]
	v_mfma_f32_16x16x32_bf16 v[2:5], v[186:189], v[230:233], v[2:5]
	s_setprio 0
	s_barrier
	s_add_i32 s20, 0, 0x18000
	v_add_u32_e32 v143, s20, v139
	s_add_i32 s21, 0, 0x1c000
	ds_read_b128 v[134:137], v143
	ds_read_b128 v[144:147], v143 offset:1024
	ds_read_b128 v[148:151], v143 offset:2048
	ds_read_b128 v[152:155], v143 offset:3072
	v_add_u32_e32 v143, s21, v139
	ds_read_b128 v[156:159], v143
	ds_read_b128 v[160:163], v143 offset:1024
	ds_read_b128 v[182:185], v143 offset:2048
	ds_read_b128 v[186:189], v143 offset:3072
	ds_read_b128 v[190:193], v142 offset:32768
	ds_read_b128 v[194:197], v142 offset:33792
	ds_read_b128 v[198:201], v142 offset:34816
	ds_read_b128 v[214:217], v142 offset:35840
	ds_read_b128 v[218:221], v142 offset:36864
	ds_read_b128 v[222:225], v142 offset:37888
	ds_read_b128 v[226:229], v142 offset:38912
	ds_read_b128 v[230:233], v142 offset:39936
	s_mov_b32 m0, s47
	v_lshl_add_u64 v[236:237], v[234:235], 0, s[28:29]
	global_load_lds_dwordx4 v[236:237], off
	v_lshl_add_u64 v[236:237], v[234:235], 0, s[82:83]
	s_mov_b32 m0, s78
	s_nop 0
	global_load_lds_dwordx4 v[236:237], off
	s_waitcnt vmcnt(8)
	s_waitcnt lgkmcnt(0)
	s_barrier
	s_setprio 1
	s_waitcnt lgkmcnt(0)
	v_mfma_f32_16x16x32_bf16 v[126:129], v[134:137], v[190:193], v[126:129]
	v_mfma_f32_16x16x32_bf16 v[126:129], v[144:147], v[194:197], v[126:129]
	v_mfma_f32_16x16x32_bf16 v[114:117], v[148:151], v[190:193], v[114:117]
	v_mfma_f32_16x16x32_bf16 v[114:117], v[152:155], v[194:197], v[114:117]
	v_mfma_f32_16x16x32_bf16 v[110:113], v[134:137], v[198:201], v[110:113]
	v_mfma_f32_16x16x32_bf16 v[110:113], v[144:147], v[214:217], v[110:113]
	v_mfma_f32_16x16x32_bf16 v[98:101], v[148:151], v[198:201], v[98:101]
	v_mfma_f32_16x16x32_bf16 v[98:101], v[152:155], v[214:217], v[98:101]
	v_mfma_f32_16x16x32_bf16 v[94:97], v[134:137], v[218:221], v[94:97]
	v_mfma_f32_16x16x32_bf16 v[94:97], v[144:147], v[222:225], v[94:97]
	v_mfma_f32_16x16x32_bf16 v[82:85], v[148:151], v[218:221], v[82:85]
	v_mfma_f32_16x16x32_bf16 v[82:85], v[152:155], v[222:225], v[82:85]
	v_mfma_f32_16x16x32_bf16 v[78:81], v[134:137], v[226:229], v[78:81]
	v_mfma_f32_16x16x32_bf16 v[78:81], v[144:147], v[230:233], v[78:81]
	v_mfma_f32_16x16x32_bf16 v[66:69], v[148:151], v[226:229], v[66:69]
	v_mfma_f32_16x16x32_bf16 v[66:69], v[152:155], v[230:233], v[66:69]
	s_setprio 0
	s_setprio 1
	v_mfma_f32_16x16x32_bf16 v[122:125], v[156:159], v[190:193], v[122:125]
	v_mfma_f32_16x16x32_bf16 v[122:125], v[160:163], v[194:197], v[122:125]
	v_mfma_f32_16x16x32_bf16 v[118:121], v[182:185], v[190:193], v[118:121]
	v_mfma_f32_16x16x32_bf16 v[118:121], v[186:189], v[194:197], v[118:121]
	v_mfma_f32_16x16x32_bf16 v[106:109], v[156:159], v[198:201], v[106:109]
	v_mfma_f32_16x16x32_bf16 v[106:109], v[160:163], v[214:217], v[106:109]
	v_mfma_f32_16x16x32_bf16 v[102:105], v[182:185], v[198:201], v[102:105]
	v_mfma_f32_16x16x32_bf16 v[102:105], v[186:189], v[214:217], v[102:105]
	v_mfma_f32_16x16x32_bf16 v[90:93], v[156:159], v[218:221], v[90:93]
	v_mfma_f32_16x16x32_bf16 v[90:93], v[160:163], v[222:225], v[90:93]
	v_mfma_f32_16x16x32_bf16 v[86:89], v[182:185], v[218:221], v[86:89]
	v_mfma_f32_16x16x32_bf16 v[86:89], v[186:189], v[222:225], v[86:89]
	v_mfma_f32_16x16x32_bf16 v[74:77], v[156:159], v[226:229], v[74:77]
	v_mfma_f32_16x16x32_bf16 v[74:77], v[160:163], v[230:233], v[74:77]
	v_mfma_f32_16x16x32_bf16 v[70:73], v[182:185], v[226:229], v[70:73]
	v_mfma_f32_16x16x32_bf16 v[70:73], v[186:189], v[230:233], v[70:73]
	s_setprio 0
	s_barrier
	ds_read_b128 v[190:193], v142 offset:49152
	ds_read_b128 v[194:197], v142 offset:50176
	ds_read_b128 v[198:201], v142 offset:51200
	ds_read_b128 v[214:217], v142 offset:52224
	ds_read_b128 v[218:221], v142 offset:53248
	ds_read_b128 v[222:225], v142 offset:54272
	ds_read_b128 v[226:229], v142 offset:55296
	ds_read_b128 v[230:233], v142 offset:56320
	s_add_i32 s20, s20, s14
	s_mov_b32 m0, s20
	v_lshl_add_u64 v[236:237], v[202:203], 0, s[34:35]
	global_load_lds_dwordx4 v[236:237], off
	v_lshl_add_u64 v[236:237], v[202:203], 0, s[38:39]
	s_add_i32 m0, s20, 0x2000
	s_add_i32 s20, s21, s14
	global_load_lds_dwordx4 v[236:237], off
	v_lshl_add_u64 v[236:237], v[202:203], 0, s[44:45]
	s_mov_b32 m0, s20
	v_lshl_add_u64 v[202:203], v[202:203], 0, s[10:11]
	global_load_lds_dwordx4 v[236:237], off
	s_add_i32 m0, s20, 0x2000
	s_nop 0
	global_load_lds_dwordx4 v[202:203], off
	v_lshl_add_u64 v[202:203], v[234:235], 0, s[34:35]
	s_mov_b32 m0, s79
	s_nop 0
	global_load_lds_dwordx4 v[202:203], off
	v_lshl_add_u64 v[202:203], v[234:235], 0, s[38:39]
	s_mov_b32 m0, s88
	s_nop 0
	global_load_lds_dwordx4 v[202:203], off
	s_waitcnt vmcnt(8)
	s_waitcnt lgkmcnt(0)
	s_barrier
	s_setprio 1
	s_waitcnt lgkmcnt(0)
	v_mfma_f32_16x16x32_bf16 v[62:65], v[134:137], v[190:193], v[62:65]
	v_mfma_f32_16x16x32_bf16 v[62:65], v[144:147], v[194:197], v[62:65]
	v_mfma_f32_16x16x32_bf16 v[50:53], v[148:151], v[190:193], v[50:53]
	v_mfma_f32_16x16x32_bf16 v[50:53], v[152:155], v[194:197], v[50:53]
	v_mfma_f32_16x16x32_bf16 v[46:49], v[134:137], v[198:201], v[46:49]
	v_mfma_f32_16x16x32_bf16 v[46:49], v[144:147], v[214:217], v[46:49]
	v_mfma_f32_16x16x32_bf16 v[34:37], v[148:151], v[198:201], v[34:37]
	v_mfma_f32_16x16x32_bf16 v[34:37], v[152:155], v[214:217], v[34:37]
	v_mfma_f32_16x16x32_bf16 v[30:33], v[134:137], v[218:221], v[30:33]
	v_mfma_f32_16x16x32_bf16 v[30:33], v[144:147], v[222:225], v[30:33]
	v_mfma_f32_16x16x32_bf16 v[18:21], v[148:151], v[218:221], v[18:21]
	v_mfma_f32_16x16x32_bf16 v[18:21], v[152:155], v[222:225], v[18:21]
	v_mfma_f32_16x16x32_bf16 v[14:17], v[134:137], v[226:229], v[14:17]
	v_mfma_f32_16x16x32_bf16 v[14:17], v[144:147], v[230:233], v[14:17]
	v_mfma_f32_16x16x32_bf16 v[6:9], v[148:151], v[226:229], v[6:9]
	v_mfma_f32_16x16x32_bf16 v[6:9], v[152:155], v[230:233], v[6:9]
	s_add_i32 s97, s97, 2
	s_add_u32 s68, s68, 0x100
	s_addc_u32 s69, s69, 0
	s_add_u32 s91, s91, 0x100
	s_addc_u32 s96, s96, 0
	s_setprio 0
	s_setprio 1
	v_mfma_f32_16x16x32_bf16 v[58:61], v[156:159], v[190:193], v[58:61]
	v_mfma_f32_16x16x32_bf16 v[58:61], v[160:163], v[194:197], v[58:61]
	v_mfma_f32_16x16x32_bf16 v[54:57], v[182:185], v[190:193], v[54:57]
	v_mfma_f32_16x16x32_bf16 v[54:57], v[186:189], v[194:197], v[54:57]
	v_mfma_f32_16x16x32_bf16 v[42:45], v[156:159], v[198:201], v[42:45]
	v_mfma_f32_16x16x32_bf16 v[42:45], v[160:163], v[214:217], v[42:45]
	v_mfma_f32_16x16x32_bf16 v[38:41], v[182:185], v[198:201], v[38:41]
	v_mfma_f32_16x16x32_bf16 v[38:41], v[186:189], v[214:217], v[38:41]
	v_mfma_f32_16x16x32_bf16 v[26:29], v[156:159], v[218:221], v[26:29]
	v_mfma_f32_16x16x32_bf16 v[26:29], v[160:163], v[222:225], v[26:29]
	v_mfma_f32_16x16x32_bf16 v[22:25], v[182:185], v[218:221], v[22:25]
	v_mfma_f32_16x16x32_bf16 v[22:25], v[186:189], v[222:225], v[22:25]
	v_mfma_f32_16x16x32_bf16 v[10:13], v[156:159], v[226:229], v[10:13]
	v_mfma_f32_16x16x32_bf16 v[10:13], v[160:163], v[230:233], v[10:13]
	v_mfma_f32_16x16x32_bf16 v[2:5], v[182:185], v[226:229], v[2:5]
	v_mfma_f32_16x16x32_bf16 v[2:5], v[186:189], v[230:233], v[2:5]
	s_setprio 0
	s_barrier
	s_cmp_gt_u32 s97, 13
	s_cbranch_scc0 .LBB0_488
	s_and_b64 vcc, exec, s[48:49]
	s_cbranch_vccz .LBB0_491
	s_barrier

.Lmid1_604:
	s_add_i32 s22, 0, 0x10000
	s_add_i32 s23, 0, 0x14000
	s_add_u32 s20, s6, 0xfffe0080
	s_addc_u32 s21, s7, -1
	s_cmp_eq_u32 s84, 4
	s_cselect_b32 s69, s42, s21
	s_cselect_b32 s68, s43, s20
	s_cselect_b32 s21, s46, s51
	s_cselect_b32 s20, s47, s49
	s_add_i32 m0, s89, 0xc000
	v_lshl_add_u64 v[162:163], s[6:7], 0, v[132:133]
	global_load_lds_dwordx4 v[162:163], off
	v_lshl_add_u64 v[162:163], v[162:163], 0, s[64:65]
	s_add_i32 m0, s89, 0xe000
	s_nop 0
	global_load_lds_dwordx4 v[162:163], off
	s_waitcnt vmcnt(8)
	s_waitcnt lgkmcnt(0)
	s_barrier
	s_setprio 1
	s_waitcnt lgkmcnt(0)
	v_mfma_f32_16x16x32_bf16 v[126:129], v[134:137], v[190:193], 0
	v_mfma_f32_16x16x32_bf16 v[126:129], v[142:145], v[194:197], v[126:129]
	v_mfma_f32_16x16x32_bf16 v[122:125], v[146:149], v[190:193], 0
	v_mfma_f32_16x16x32_bf16 v[122:125], v[150:153], v[194:197], v[122:125]
	v_mfma_f32_16x16x32_bf16 v[110:113], v[134:137], v[198:201], 0
	v_mfma_f32_16x16x32_bf16 v[110:113], v[142:145], v[214:217], v[110:113]
	v_mfma_f32_16x16x32_bf16 v[106:109], v[146:149], v[198:201], 0
	v_mfma_f32_16x16x32_bf16 v[106:109], v[150:153], v[214:217], v[106:109]
	v_mfma_f32_16x16x32_bf16 v[94:97], v[134:137], v[218:221], 0
	v_mfma_f32_16x16x32_bf16 v[94:97], v[142:145], v[222:225], v[94:97]
	v_mfma_f32_16x16x32_bf16 v[90:93], v[146:149], v[218:221], 0
	v_mfma_f32_16x16x32_bf16 v[90:93], v[150:153], v[222:225], v[90:93]
	v_mfma_f32_16x16x32_bf16 v[78:81], v[134:137], v[226:229], 0
	v_mfma_f32_16x16x32_bf16 v[78:81], v[142:145], v[230:233], v[78:81]
	v_mfma_f32_16x16x32_bf16 v[74:77], v[146:149], v[226:229], 0
	v_mfma_f32_16x16x32_bf16 v[74:77], v[150:153], v[230:233], v[74:77]
	s_setprio 0
	s_setprio 1
	v_mfma_f32_16x16x32_bf16 v[118:121], v[154:157], v[190:193], 0
	v_mfma_f32_16x16x32_bf16 v[118:121], v[158:161], v[194:197], v[118:121]
	v_mfma_f32_16x16x32_bf16 v[114:117], v[182:185], v[190:193], 0
	v_mfma_f32_16x16x32_bf16 v[114:117], v[186:189], v[194:197], v[114:117]
	v_mfma_f32_16x16x32_bf16 v[102:105], v[154:157], v[198:201], 0
	v_mfma_f32_16x16x32_bf16 v[102:105], v[158:161], v[214:217], v[102:105]
	v_mfma_f32_16x16x32_bf16 v[98:101], v[182:185], v[198:201], 0
	v_mfma_f32_16x16x32_bf16 v[98:101], v[186:189], v[214:217], v[98:101]
	v_mfma_f32_16x16x32_bf16 v[86:89], v[154:157], v[218:221], 0
	v_mfma_f32_16x16x32_bf16 v[86:89], v[158:161], v[222:225], v[86:89]
	v_mfma_f32_16x16x32_bf16 v[82:85], v[182:185], v[218:221], 0
	v_mfma_f32_16x16x32_bf16 v[82:85], v[186:189], v[222:225], v[82:85]
	v_mfma_f32_16x16x32_bf16 v[70:73], v[154:157], v[226:229], 0
	v_mfma_f32_16x16x32_bf16 v[70:73], v[158:161], v[230:233], v[70:73]
	v_mfma_f32_16x16x32_bf16 v[66:69], v[182:185], v[226:229], 0
	v_mfma_f32_16x16x32_bf16 v[66:69], v[186:189], v[230:233], v[66:69]
	s_setprio 0
	s_barrier
	ds_read_b128 v[190:193], v141 offset:16384
	ds_read_b128 v[194:197], v141 offset:17408
	ds_read_b128 v[198:201], v141 offset:18432
	ds_read_b128 v[214:217], v141 offset:19456
	ds_read_b128 v[218:221], v141 offset:20480
	ds_read_b128 v[222:225], v141 offset:21504
	ds_read_b128 v[226:229], v141 offset:22528
	ds_read_b128 v[230:233], v141 offset:23552
	v_lshl_add_u64 v[162:163], s[20:21], 0, v[0:1]
	s_add_i32 s20, s22, s88
	s_mov_b32 m0, s20
	s_nop 0
	s_nop 0
	global_load_lds_dwordx4 v[162:163], off
	v_lshl_add_u64 v[202:203], v[162:163], 0, s[64:65]
	s_add_i32 m0, s20, 0x2000
	s_add_i32 s20, s23, s88
	global_load_lds_dwordx4 v[202:203], off
	v_lshl_add_u64 v[202:203], v[162:163], 0, s[72:73]
	s_mov_b32 m0, s20
	s_nop 0
	global_load_lds_dwordx4 v[202:203], off
	v_lshl_add_u64 v[202:203], v[162:163], 0, s[74:75]
	s_add_i32 m0, s20, 0x2000
	s_nop 0
	global_load_lds_dwordx4 v[202:203], off
	v_lshl_add_u64 v[202:203], s[68:69], 0, v[130:131]
	s_mov_b32 m0, s89
	v_lshl_add_u64 v[234:235], v[202:203], 0, s[64:65]
	global_load_lds_dwordx4 v[202:203], off
	s_mov_b32 m0, s90
	s_nop 0
	global_load_lds_dwordx4 v[234:235], off
	s_waitcnt vmcnt(8)
	s_waitcnt lgkmcnt(0)
	s_barrier
	s_setprio 1
	s_waitcnt lgkmcnt(0)
	v_mfma_f32_16x16x32_bf16 v[62:65], v[134:137], v[190:193], 0
	v_mfma_f32_16x16x32_bf16 v[62:65], v[142:145], v[194:197], v[62:65]
	v_mfma_f32_16x16x32_bf16 v[58:61], v[146:149], v[190:193], 0
	v_mfma_f32_16x16x32_bf16 v[58:61], v[150:153], v[194:197], v[58:61]
	v_mfma_f32_16x16x32_bf16 v[46:49], v[134:137], v[198:201], 0
	v_mfma_f32_16x16x32_bf16 v[46:49], v[142:145], v[214:217], v[46:49]
	v_mfma_f32_16x16x32_bf16 v[42:45], v[146:149], v[198:201], 0
	v_mfma_f32_16x16x32_bf16 v[42:45], v[150:153], v[214:217], v[42:45]
	v_mfma_f32_16x16x32_bf16 v[30:33], v[134:137], v[218:221], 0
	v_mfma_f32_16x16x32_bf16 v[30:33], v[142:145], v[222:225], v[30:33]
	v_mfma_f32_16x16x32_bf16 v[26:29], v[146:149], v[218:221], 0
	v_mfma_f32_16x16x32_bf16 v[26:29], v[150:153], v[222:225], v[26:29]
	v_mfma_f32_16x16x32_bf16 v[14:17], v[134:137], v[226:229], 0
	v_mfma_f32_16x16x32_bf16 v[14:17], v[142:145], v[230:233], v[14:17]
	v_mfma_f32_16x16x32_bf16 v[10:13], v[146:149], v[226:229], 0
	v_mfma_f32_16x16x32_bf16 v[10:13], v[150:153], v[230:233], v[10:13]
	s_setprio 0
	s_setprio 1
	v_mfma_f32_16x16x32_bf16 v[54:57], v[154:157], v[190:193], 0
	v_mfma_f32_16x16x32_bf16 v[54:57], v[158:161], v[194:197], v[54:57]
	v_mfma_f32_16x16x32_bf16 v[50:53], v[182:185], v[190:193], 0
	v_mfma_f32_16x16x32_bf16 v[50:53], v[186:189], v[194:197], v[50:53]
	v_mfma_f32_16x16x32_bf16 v[38:41], v[154:157], v[198:201], 0
	v_mfma_f32_16x16x32_bf16 v[38:41], v[158:161], v[214:217], v[38:41]
	v_mfma_f32_16x16x32_bf16 v[34:37], v[182:185], v[198:201], 0
	v_mfma_f32_16x16x32_bf16 v[34:37], v[186:189], v[214:217], v[34:37]
	v_mfma_f32_16x16x32_bf16 v[22:25], v[154:157], v[218:221], 0
	v_mfma_f32_16x16x32_bf16 v[22:25], v[158:161], v[222:225], v[22:25]
	v_mfma_f32_16x16x32_bf16 v[18:21], v[182:185], v[218:221], 0
	v_mfma_f32_16x16x32_bf16 v[18:21], v[186:189], v[222:225], v[18:21]
	v_mfma_f32_16x16x32_bf16 v[6:9], v[154:157], v[226:229], 0
	v_mfma_f32_16x16x32_bf16 v[6:9], v[158:161], v[230:233], v[6:9]
	v_mfma_f32_16x16x32_bf16 v[2:5], v[182:185], v[226:229], 0
	v_mfma_f32_16x16x32_bf16 v[2:5], v[186:189], v[230:233], v[2:5]
	s_setprio 0
	s_barrier
	s_add_i32 s20, 0, 0x18000
	s_add_i32 s21, 0, 0x1c000
	v_add_u32_e32 v150, s20, v139
	v_add_u32_e32 v186, s21, v139
	ds_read_b128 v[134:137], v150
	ds_read_b128 v[142:145], v150 offset:1024
	ds_read_b128 v[146:149], v150 offset:2048
	ds_read_b128 v[150:153], v150 offset:3072
	ds_read_b128 v[154:157], v186
	ds_read_b128 v[158:161], v186 offset:1024
	ds_read_b128 v[182:185], v186 offset:2048
	ds_read_b128 v[186:189], v186 offset:3072
	ds_read_b128 v[190:193], v141 offset:32768
	ds_read_b128 v[194:197], v141 offset:33792
	ds_read_b128 v[198:201], v141 offset:34816
	ds_read_b128 v[214:217], v141 offset:35840
	ds_read_b128 v[218:221], v141 offset:36864
	ds_read_b128 v[222:225], v141 offset:37888
	ds_read_b128 v[226:229], v141 offset:38912
	ds_read_b128 v[230:233], v141 offset:39936
	s_mov_b32 m0, s91
	v_lshl_add_u64 v[234:235], v[202:203], 0, s[72:73]
	global_load_lds_dwordx4 v[234:235], off
	v_lshl_add_u64 v[234:235], v[202:203], 0, s[74:75]
	s_mov_b32 m0, s96
	s_nop 0
	global_load_lds_dwordx4 v[234:235], off
	s_waitcnt vmcnt(8)
	s_waitcnt lgkmcnt(0)
	s_barrier
	s_setprio 1
	s_waitcnt lgkmcnt(0)
	v_mfma_f32_16x16x32_bf16 v[126:129], v[134:137], v[190:193], v[126:129]
	v_mfma_f32_16x16x32_bf16 v[126:129], v[142:145], v[194:197], v[126:129]
	v_mfma_f32_16x16x32_bf16 v[122:125], v[146:149], v[190:193], v[122:125]
	v_mfma_f32_16x16x32_bf16 v[122:125], v[150:153], v[194:197], v[122:125]
	v_mfma_f32_16x16x32_bf16 v[110:113], v[134:137], v[198:201], v[110:113]
	v_mfma_f32_16x16x32_bf16 v[110:113], v[142:145], v[214:217], v[110:113]
	v_mfma_f32_16x16x32_bf16 v[106:109], v[146:149], v[198:201], v[106:109]
	v_mfma_f32_16x16x32_bf16 v[106:109], v[150:153], v[214:217], v[106:109]
	v_mfma_f32_16x16x32_bf16 v[94:97], v[134:137], v[218:221], v[94:97]
	v_mfma_f32_16x16x32_bf16 v[94:97], v[142:145], v[222:225], v[94:97]
	v_mfma_f32_16x16x32_bf16 v[90:93], v[146:149], v[218:221], v[90:93]
	v_mfma_f32_16x16x32_bf16 v[90:93], v[150:153], v[222:225], v[90:93]
	v_mfma_f32_16x16x32_bf16 v[78:81], v[134:137], v[226:229], v[78:81]
	v_mfma_f32_16x16x32_bf16 v[78:81], v[142:145], v[230:233], v[78:81]
	v_mfma_f32_16x16x32_bf16 v[74:77], v[146:149], v[226:229], v[74:77]
	v_mfma_f32_16x16x32_bf16 v[74:77], v[150:153], v[230:233], v[74:77]
	s_setprio 0
	s_setprio 1
	v_mfma_f32_16x16x32_bf16 v[118:121], v[154:157], v[190:193], v[118:121]
	v_mfma_f32_16x16x32_bf16 v[118:121], v[158:161], v[194:197], v[118:121]
	v_mfma_f32_16x16x32_bf16 v[114:117], v[182:185], v[190:193], v[114:117]
	v_mfma_f32_16x16x32_bf16 v[114:117], v[186:189], v[194:197], v[114:117]
	v_mfma_f32_16x16x32_bf16 v[102:105], v[154:157], v[198:201], v[102:105]
	v_mfma_f32_16x16x32_bf16 v[102:105], v[158:161], v[214:217], v[102:105]
	v_mfma_f32_16x16x32_bf16 v[98:101], v[182:185], v[198:201], v[98:101]
	v_mfma_f32_16x16x32_bf16 v[98:101], v[186:189], v[214:217], v[98:101]
	v_mfma_f32_16x16x32_bf16 v[86:89], v[154:157], v[218:221], v[86:89]
	v_mfma_f32_16x16x32_bf16 v[86:89], v[158:161], v[222:225], v[86:89]
	v_mfma_f32_16x16x32_bf16 v[82:85], v[182:185], v[218:221], v[82:85]
	v_mfma_f32_16x16x32_bf16 v[82:85], v[186:189], v[222:225], v[82:85]
	v_mfma_f32_16x16x32_bf16 v[70:73], v[154:157], v[226:229], v[70:73]
	v_mfma_f32_16x16x32_bf16 v[70:73], v[158:161], v[230:233], v[70:73]
	v_mfma_f32_16x16x32_bf16 v[66:69], v[182:185], v[226:229], v[66:69]
	v_mfma_f32_16x16x32_bf16 v[66:69], v[186:189], v[230:233], v[66:69]
	s_setprio 0
	s_barrier
	ds_read_b128 v[190:193], v141 offset:49152
	ds_read_b128 v[194:197], v141 offset:50176
	ds_read_b128 v[198:201], v141 offset:51200
	ds_read_b128 v[214:217], v141 offset:52224
	ds_read_b128 v[218:221], v141 offset:53248
	ds_read_b128 v[222:225], v141 offset:54272
	ds_read_b128 v[226:229], v141 offset:55296
	ds_read_b128 v[230:233], v141 offset:56320
	s_add_i32 s20, s20, s88
	s_mov_b32 m0, s20
	v_lshl_add_u64 v[234:235], v[162:163], 0, s[34:35]
	global_load_lds_dwordx4 v[234:235], off
	v_lshl_add_u64 v[234:235], v[162:163], 0, s[80:81]
	s_add_i32 m0, s20, 0x2000
	s_add_i32 s20, s21, s88
	global_load_lds_dwordx4 v[234:235], off
	v_lshl_add_u64 v[234:235], v[162:163], 0, s[38:39]
	s_mov_b32 m0, s20
	v_lshl_add_u64 v[162:163], v[162:163], 0, s[86:87]
	global_load_lds_dwordx4 v[234:235], off
	s_add_i32 m0, s20, 0x2000
	s_nop 0
	global_load_lds_dwordx4 v[162:163], off
	v_lshl_add_u64 v[162:163], v[202:203], 0, s[34:35]
	s_mov_b32 m0, s97
	s_nop 0
	global_load_lds_dwordx4 v[162:163], off
	v_lshl_add_u64 v[162:163], v[202:203], 0, s[80:81]
	s_mov_b32 m0, s58
	s_nop 0
	global_load_lds_dwordx4 v[162:163], off
	s_waitcnt vmcnt(8)
	s_waitcnt lgkmcnt(0)
	s_barrier
	s_setprio 1
	s_waitcnt lgkmcnt(0)
	v_mfma_f32_16x16x32_bf16 v[62:65], v[134:137], v[190:193], v[62:65]
	v_mfma_f32_16x16x32_bf16 v[62:65], v[142:145], v[194:197], v[62:65]
	v_mfma_f32_16x16x32_bf16 v[58:61], v[146:149], v[190:193], v[58:61]
	v_mfma_f32_16x16x32_bf16 v[58:61], v[150:153], v[194:197], v[58:61]
	v_mfma_f32_16x16x32_bf16 v[46:49], v[134:137], v[198:201], v[46:49]
	v_mfma_f32_16x16x32_bf16 v[46:49], v[142:145], v[214:217], v[46:49]
	v_mfma_f32_16x16x32_bf16 v[42:45], v[146:149], v[198:201], v[42:45]
	v_mfma_f32_16x16x32_bf16 v[42:45], v[150:153], v[214:217], v[42:45]
	v_mfma_f32_16x16x32_bf16 v[30:33], v[134:137], v[218:221], v[30:33]
	v_mfma_f32_16x16x32_bf16 v[30:33], v[142:145], v[222:225], v[30:33]
	v_mfma_f32_16x16x32_bf16 v[26:29], v[146:149], v[218:221], v[26:29]
	v_mfma_f32_16x16x32_bf16 v[26:29], v[150:153], v[222:225], v[26:29]
	v_mfma_f32_16x16x32_bf16 v[14:17], v[134:137], v[226:229], v[14:17]
	v_mfma_f32_16x16x32_bf16 v[14:17], v[142:145], v[230:233], v[14:17]
	v_mfma_f32_16x16x32_bf16 v[10:13], v[146:149], v[226:229], v[10:13]
	v_mfma_f32_16x16x32_bf16 v[10:13], v[150:153], v[230:233], v[10:13]
	s_add_i32 s84, s84, 2
	s_add_u32 s6, s6, 0x100
	s_addc_u32 s7, s7, 0
	s_add_u32 s49, s49, 0x100
	s_addc_u32 s51, s51, 0
	s_setprio 0
	s_setprio 1
	v_mfma_f32_16x16x32_bf16 v[54:57], v[154:157], v[190:193], v[54:57]
	v_mfma_f32_16x16x32_bf16 v[54:57], v[158:161], v[194:197], v[54:57]
	v_mfma_f32_16x16x32_bf16 v[50:53], v[182:185], v[190:193], v[50:53]
	v_mfma_f32_16x16x32_bf16 v[50:53], v[186:189], v[194:197], v[50:53]
	v_mfma_f32_16x16x32_bf16 v[38:41], v[154:157], v[198:201], v[38:41]
	v_mfma_f32_16x16x32_bf16 v[38:41], v[158:161], v[214:217], v[38:41]
	v_mfma_f32_16x16x32_bf16 v[34:37], v[182:185], v[198:201], v[34:37]
	v_mfma_f32_16x16x32_bf16 v[34:37], v[186:189], v[214:217], v[34:37]
	v_mfma_f32_16x16x32_bf16 v[22:25], v[154:157], v[218:221], v[22:25]
	v_mfma_f32_16x16x32_bf16 v[22:25], v[158:161], v[222:225], v[22:25]
	v_mfma_f32_16x16x32_bf16 v[18:21], v[182:185], v[218:221], v[18:21]
	v_mfma_f32_16x16x32_bf16 v[18:21], v[186:189], v[222:225], v[18:21]
	v_mfma_f32_16x16x32_bf16 v[6:9], v[154:157], v[226:229], v[6:9]
	v_mfma_f32_16x16x32_bf16 v[6:9], v[158:161], v[230:233], v[6:9]
	v_mfma_f32_16x16x32_bf16 v[2:5], v[182:185], v[226:229], v[2:5]
	v_mfma_f32_16x16x32_bf16 v[2:5], v[186:189], v[230:233], v[2:5]
	s_setprio 0
	s_barrier
	s_branch .LBB0_604
	.p2alignl 6, 3212836864
.LBB0_604:
	s_add_i32 s22, 0, 0x10000
	s_add_i32 s23, 0, 0x14000
	v_add_u32_e32 v150, s22, v139
	v_add_u32_e32 v162, s23, v139
	ds_read_b128 v[134:137], v150
	ds_read_b128 v[142:145], v150 offset:1024
	ds_read_b128 v[146:149], v150 offset:2048
	ds_read_b128 v[150:153], v150 offset:3072
	ds_read_b128 v[154:157], v162
	ds_read_b128 v[158:161], v162 offset:1024
	ds_read_b128 v[182:185], v162 offset:2048
	ds_read_b128 v[186:189], v162 offset:3072
	ds_read_b128 v[190:193], v141
	ds_read_b128 v[194:197], v141 offset:1024
	ds_read_b128 v[198:201], v141 offset:2048
	ds_read_b128 v[214:217], v141 offset:3072
	ds_read_b128 v[218:221], v141 offset:4096
	ds_read_b128 v[222:225], v141 offset:5120
	ds_read_b128 v[226:229], v141 offset:6144
	ds_read_b128 v[230:233], v141 offset:7168
	s_add_u32 s20, s6, 0xfffe0080
	s_addc_u32 s21, s7, -1
	s_cmp_eq_u32 s84, 4
	s_cselect_b32 s69, s42, s21
	s_cselect_b32 s68, s43, s20
	s_cselect_b32 s21, s46, s51
	s_cselect_b32 s20, s47, s49
	s_add_i32 m0, s89, 0xc000
	v_lshl_add_u64 v[162:163], s[6:7], 0, v[132:133]
	global_load_lds_dwordx4 v[162:163], off
	v_lshl_add_u64 v[162:163], v[162:163], 0, s[64:65]
	s_add_i32 m0, s89, 0xe000
	s_nop 0
	global_load_lds_dwordx4 v[162:163], off
	s_waitcnt vmcnt(8)
	s_waitcnt lgkmcnt(0)
	s_barrier
	s_setprio 1
	s_waitcnt lgkmcnt(0)
	v_mfma_f32_16x16x32_bf16 v[126:129], v[134:137], v[190:193], v[126:129]
	v_mfma_f32_16x16x32_bf16 v[126:129], v[142:145], v[194:197], v[126:129]
	v_mfma_f32_16x16x32_bf16 v[122:125], v[146:149], v[190:193], v[122:125]
	v_mfma_f32_16x16x32_bf16 v[122:125], v[150:153], v[194:197], v[122:125]
	v_mfma_f32_16x16x32_bf16 v[110:113], v[134:137], v[198:201], v[110:113]
	v_mfma_f32_16x16x32_bf16 v[110:113], v[142:145], v[214:217], v[110:113]
	v_mfma_f32_16x16x32_bf16 v[106:109], v[146:149], v[198:201], v[106:109]
	v_mfma_f32_16x16x32_bf16 v[106:109], v[150:153], v[214:217], v[106:109]
	v_mfma_f32_16x16x32_bf16 v[94:97], v[134:137], v[218:221], v[94:97]
	v_mfma_f32_16x16x32_bf16 v[94:97], v[142:145], v[222:225], v[94:97]
	v_mfma_f32_16x16x32_bf16 v[90:93], v[146:149], v[218:221], v[90:93]
	v_mfma_f32_16x16x32_bf16 v[90:93], v[150:153], v[222:225], v[90:93]
	v_mfma_f32_16x16x32_bf16 v[78:81], v[134:137], v[226:229], v[78:81]
	v_mfma_f32_16x16x32_bf16 v[78:81], v[142:145], v[230:233], v[78:81]
	v_mfma_f32_16x16x32_bf16 v[74:77], v[146:149], v[226:229], v[74:77]
	v_mfma_f32_16x16x32_bf16 v[74:77], v[150:153], v[230:233], v[74:77]
	s_setprio 0
	s_setprio 1
	v_mfma_f32_16x16x32_bf16 v[118:121], v[154:157], v[190:193], v[118:121]
	v_mfma_f32_16x16x32_bf16 v[118:121], v[158:161], v[194:197], v[118:121]
	v_mfma_f32_16x16x32_bf16 v[114:117], v[182:185], v[190:193], v[114:117]
	v_mfma_f32_16x16x32_bf16 v[114:117], v[186:189], v[194:197], v[114:117]
	v_mfma_f32_16x16x32_bf16 v[102:105], v[154:157], v[198:201], v[102:105]
	v_mfma_f32_16x16x32_bf16 v[102:105], v[158:161], v[214:217], v[102:105]
	v_mfma_f32_16x16x32_bf16 v[98:101], v[182:185], v[198:201], v[98:101]
	v_mfma_f32_16x16x32_bf16 v[98:101], v[186:189], v[214:217], v[98:101]
	v_mfma_f32_16x16x32_bf16 v[86:89], v[154:157], v[218:221], v[86:89]
	v_mfma_f32_16x16x32_bf16 v[86:89], v[158:161], v[222:225], v[86:89]
	v_mfma_f32_16x16x32_bf16 v[82:85], v[182:185], v[218:221], v[82:85]
	v_mfma_f32_16x16x32_bf16 v[82:85], v[186:189], v[222:225], v[82:85]
	v_mfma_f32_16x16x32_bf16 v[70:73], v[154:157], v[226:229], v[70:73]
	v_mfma_f32_16x16x32_bf16 v[70:73], v[158:161], v[230:233], v[70:73]
	v_mfma_f32_16x16x32_bf16 v[66:69], v[182:185], v[226:229], v[66:69]
	v_mfma_f32_16x16x32_bf16 v[66:69], v[186:189], v[230:233], v[66:69]
	s_setprio 0
	s_barrier
	ds_read_b128 v[190:193], v141 offset:16384
	ds_read_b128 v[194:197], v141 offset:17408
	ds_read_b128 v[198:201], v141 offset:18432
	ds_read_b128 v[214:217], v141 offset:19456
	ds_read_b128 v[218:221], v141 offset:20480
	ds_read_b128 v[222:225], v141 offset:21504
	ds_read_b128 v[226:229], v141 offset:22528
	ds_read_b128 v[230:233], v141 offset:23552
	v_lshl_add_u64 v[162:163], s[20:21], 0, v[0:1]
	s_add_i32 s20, s22, s88
	s_mov_b32 m0, s20
	s_nop 0
	s_nop 0
	global_load_lds_dwordx4 v[162:163], off
	v_lshl_add_u64 v[202:203], v[162:163], 0, s[64:65]
	s_add_i32 m0, s20, 0x2000
	s_add_i32 s20, s23, s88
	global_load_lds_dwordx4 v[202:203], off
	v_lshl_add_u64 v[202:203], v[162:163], 0, s[72:73]
	s_mov_b32 m0, s20
	s_nop 0
	global_load_lds_dwordx4 v[202:203], off
	v_lshl_add_u64 v[202:203], v[162:163], 0, s[74:75]
	s_add_i32 m0, s20, 0x2000
	s_nop 0
	global_load_lds_dwordx4 v[202:203], off
	v_lshl_add_u64 v[202:203], s[68:69], 0, v[130:131]
	s_mov_b32 m0, s89
	v_lshl_add_u64 v[234:235], v[202:203], 0, s[64:65]
	global_load_lds_dwordx4 v[202:203], off
	s_mov_b32 m0, s90
	s_nop 0
	global_load_lds_dwordx4 v[234:235], off
	s_waitcnt vmcnt(8)
	s_waitcnt lgkmcnt(0)
	s_barrier
	s_setprio 1
	s_waitcnt lgkmcnt(0)
	v_mfma_f32_16x16x32_bf16 v[62:65], v[134:137], v[190:193], v[62:65]
	v_mfma_f32_16x16x32_bf16 v[62:65], v[142:145], v[194:197], v[62:65]
	v_mfma_f32_16x16x32_bf16 v[58:61], v[146:149], v[190:193], v[58:61]
	v_mfma_f32_16x16x32_bf16 v[58:61], v[150:153], v[194:197], v[58:61]
	v_mfma_f32_16x16x32_bf16 v[46:49], v[134:137], v[198:201], v[46:49]
	v_mfma_f32_16x16x32_bf16 v[46:49], v[142:145], v[214:217], v[46:49]
	v_mfma_f32_16x16x32_bf16 v[42:45], v[146:149], v[198:201], v[42:45]
	v_mfma_f32_16x16x32_bf16 v[42:45], v[150:153], v[214:217], v[42:45]
	v_mfma_f32_16x16x32_bf16 v[30:33], v[134:137], v[218:221], v[30:33]
	v_mfma_f32_16x16x32_bf16 v[30:33], v[142:145], v[222:225], v[30:33]
	v_mfma_f32_16x16x32_bf16 v[26:29], v[146:149], v[218:221], v[26:29]
	v_mfma_f32_16x16x32_bf16 v[26:29], v[150:153], v[222:225], v[26:29]
	v_mfma_f32_16x16x32_bf16 v[14:17], v[134:137], v[226:229], v[14:17]
	v_mfma_f32_16x16x32_bf16 v[14:17], v[142:145], v[230:233], v[14:17]
	v_mfma_f32_16x16x32_bf16 v[10:13], v[146:149], v[226:229], v[10:13]
	v_mfma_f32_16x16x32_bf16 v[10:13], v[150:153], v[230:233], v[10:13]
	s_setprio 0
	s_setprio 1
	v_mfma_f32_16x16x32_bf16 v[54:57], v[154:157], v[190:193], v[54:57]
	v_mfma_f32_16x16x32_bf16 v[54:57], v[158:161], v[194:197], v[54:57]
	v_mfma_f32_16x16x32_bf16 v[50:53], v[182:185], v[190:193], v[50:53]
	v_mfma_f32_16x16x32_bf16 v[50:53], v[186:189], v[194:197], v[50:53]
	v_mfma_f32_16x16x32_bf16 v[38:41], v[154:157], v[198:201], v[38:41]
	v_mfma_f32_16x16x32_bf16 v[38:41], v[158:161], v[214:217], v[38:41]
	v_mfma_f32_16x16x32_bf16 v[34:37], v[182:185], v[198:201], v[34:37]
	v_mfma_f32_16x16x32_bf16 v[34:37], v[186:189], v[214:217], v[34:37]
	v_mfma_f32_16x16x32_bf16 v[22:25], v[154:157], v[218:221], v[22:25]
	v_mfma_f32_16x16x32_bf16 v[22:25], v[158:161], v[222:225], v[22:25]
	v_mfma_f32_16x16x32_bf16 v[18:21], v[182:185], v[218:221], v[18:21]
	v_mfma_f32_16x16x32_bf16 v[18:21], v[186:189], v[222:225], v[18:21]
	v_mfma_f32_16x16x32_bf16 v[6:9], v[154:157], v[226:229], v[6:9]
	v_mfma_f32_16x16x32_bf16 v[6:9], v[158:161], v[230:233], v[6:9]
	v_mfma_f32_16x16x32_bf16 v[2:5], v[182:185], v[226:229], v[2:5]
	v_mfma_f32_16x16x32_bf16 v[2:5], v[186:189], v[230:233], v[2:5]
	s_setprio 0
	s_barrier
	s_add_i32 s20, 0, 0x18000
	s_add_i32 s21, 0, 0x1c000
	v_add_u32_e32 v150, s20, v139
	v_add_u32_e32 v186, s21, v139
	ds_read_b128 v[134:137], v150
	ds_read_b128 v[142:145], v150 offset:1024
	ds_read_b128 v[146:149], v150 offset:2048
	ds_read_b128 v[150:153], v150 offset:3072
	ds_read_b128 v[154:157], v186
	ds_read_b128 v[158:161], v186 offset:1024
	ds_read_b128 v[182:185], v186 offset:2048
	ds_read_b128 v[186:189], v186 offset:3072
	ds_read_b128 v[190:193], v141 offset:32768
	ds_read_b128 v[194:197], v141 offset:33792
	ds_read_b128 v[198:201], v141 offset:34816
	ds_read_b128 v[214:217], v141 offset:35840
	ds_read_b128 v[218:221], v141 offset:36864
	ds_read_b128 v[222:225], v141 offset:37888
	ds_read_b128 v[226:229], v141 offset:38912
	ds_read_b128 v[230:233], v141 offset:39936
	s_mov_b32 m0, s91
	v_lshl_add_u64 v[234:235], v[202:203], 0, s[72:73]
	global_load_lds_dwordx4 v[234:235], off
	v_lshl_add_u64 v[234:235], v[202:203], 0, s[74:75]
	s_mov_b32 m0, s96
	s_nop 0
	global_load_lds_dwordx4 v[234:235], off
	s_waitcnt vmcnt(8)
	s_waitcnt lgkmcnt(0)
	s_barrier
	s_setprio 1
	s_waitcnt lgkmcnt(0)
	v_mfma_f32_16x16x32_bf16 v[126:129], v[134:137], v[190:193], v[126:129]
	v_mfma_f32_16x16x32_bf16 v[126:129], v[142:145], v[194:197], v[126:129]
	v_mfma_f32_16x16x32_bf16 v[122:125], v[146:149], v[190:193], v[122:125]
	v_mfma_f32_16x16x32_bf16 v[122:125], v[150:153], v[194:197], v[122:125]
	v_mfma_f32_16x16x32_bf16 v[110:113], v[134:137], v[198:201], v[110:113]
	v_mfma_f32_16x16x32_bf16 v[110:113], v[142:145], v[214:217], v[110:113]
	v_mfma_f32_16x16x32_bf16 v[106:109], v[146:149], v[198:201], v[106:109]
	v_mfma_f32_16x16x32_bf16 v[106:109], v[150:153], v[214:217], v[106:109]
	v_mfma_f32_16x16x32_bf16 v[94:97], v[134:137], v[218:221], v[94:97]
	v_mfma_f32_16x16x32_bf16 v[94:97], v[142:145], v[222:225], v[94:97]
	v_mfma_f32_16x16x32_bf16 v[90:93], v[146:149], v[218:221], v[90:93]
	v_mfma_f32_16x16x32_bf16 v[90:93], v[150:153], v[222:225], v[90:93]
	v_mfma_f32_16x16x32_bf16 v[78:81], v[134:137], v[226:229], v[78:81]
	v_mfma_f32_16x16x32_bf16 v[78:81], v[142:145], v[230:233], v[78:81]
	v_mfma_f32_16x16x32_bf16 v[74:77], v[146:149], v[226:229], v[74:77]
	v_mfma_f32_16x16x32_bf16 v[74:77], v[150:153], v[230:233], v[74:77]
	s_setprio 0
	s_setprio 1
	v_mfma_f32_16x16x32_bf16 v[118:121], v[154:157], v[190:193], v[118:121]
	v_mfma_f32_16x16x32_bf16 v[118:121], v[158:161], v[194:197], v[118:121]
	v_mfma_f32_16x16x32_bf16 v[114:117], v[182:185], v[190:193], v[114:117]
	v_mfma_f32_16x16x32_bf16 v[114:117], v[186:189], v[194:197], v[114:117]
	v_mfma_f32_16x16x32_bf16 v[102:105], v[154:157], v[198:201], v[102:105]
	v_mfma_f32_16x16x32_bf16 v[102:105], v[158:161], v[214:217], v[102:105]
	v_mfma_f32_16x16x32_bf16 v[98:101], v[182:185], v[198:201], v[98:101]
	v_mfma_f32_16x16x32_bf16 v[98:101], v[186:189], v[214:217], v[98:101]
	v_mfma_f32_16x16x32_bf16 v[86:89], v[154:157], v[218:221], v[86:89]
	v_mfma_f32_16x16x32_bf16 v[86:89], v[158:161], v[222:225], v[86:89]
	v_mfma_f32_16x16x32_bf16 v[82:85], v[182:185], v[218:221], v[82:85]
	v_mfma_f32_16x16x32_bf16 v[82:85], v[186:189], v[222:225], v[82:85]
	v_mfma_f32_16x16x32_bf16 v[70:73], v[154:157], v[226:229], v[70:73]
	v_mfma_f32_16x16x32_bf16 v[70:73], v[158:161], v[230:233], v[70:73]
	v_mfma_f32_16x16x32_bf16 v[66:69], v[182:185], v[226:229], v[66:69]
	v_mfma_f32_16x16x32_bf16 v[66:69], v[186:189], v[230:233], v[66:69]
	s_setprio 0
	s_barrier
	ds_read_b128 v[190:193], v141 offset:49152
	ds_read_b128 v[194:197], v141 offset:50176
	ds_read_b128 v[198:201], v141 offset:51200
	ds_read_b128 v[214:217], v141 offset:52224
	ds_read_b128 v[218:221], v141 offset:53248
	ds_read_b128 v[222:225], v141 offset:54272
	ds_read_b128 v[226:229], v141 offset:55296
	ds_read_b128 v[230:233], v141 offset:56320
	s_add_i32 s20, s20, s88
	s_mov_b32 m0, s20
	v_lshl_add_u64 v[234:235], v[162:163], 0, s[34:35]
	global_load_lds_dwordx4 v[234:235], off
	v_lshl_add_u64 v[234:235], v[162:163], 0, s[80:81]
	s_add_i32 m0, s20, 0x2000
	s_add_i32 s20, s21, s88
	global_load_lds_dwordx4 v[234:235], off
	v_lshl_add_u64 v[234:235], v[162:163], 0, s[38:39]
	s_mov_b32 m0, s20
	v_lshl_add_u64 v[162:163], v[162:163], 0, s[86:87]
	global_load_lds_dwordx4 v[234:235], off
	s_add_i32 m0, s20, 0x2000
	s_nop 0
	global_load_lds_dwordx4 v[162:163], off
	v_lshl_add_u64 v[162:163], v[202:203], 0, s[34:35]
	s_mov_b32 m0, s97
	s_nop 0
	global_load_lds_dwordx4 v[162:163], off
	v_lshl_add_u64 v[162:163], v[202:203], 0, s[80:81]
	s_mov_b32 m0, s58
	s_nop 0
	global_load_lds_dwordx4 v[162:163], off
	s_waitcnt vmcnt(8)
	s_waitcnt lgkmcnt(0)
	s_barrier
	s_setprio 1
	s_waitcnt lgkmcnt(0)
	v_mfma_f32_16x16x32_bf16 v[62:65], v[134:137], v[190:193], v[62:65]
	v_mfma_f32_16x16x32_bf16 v[62:65], v[142:145], v[194:197], v[62:65]
	v_mfma_f32_16x16x32_bf16 v[58:61], v[146:149], v[190:193], v[58:61]
	v_mfma_f32_16x16x32_bf16 v[58:61], v[150:153], v[194:197], v[58:61]
	v_mfma_f32_16x16x32_bf16 v[46:49], v[134:137], v[198:201], v[46:49]
	v_mfma_f32_16x16x32_bf16 v[46:49], v[142:145], v[214:217], v[46:49]
	v_mfma_f32_16x16x32_bf16 v[42:45], v[146:149], v[198:201], v[42:45]
	v_mfma_f32_16x16x32_bf16 v[42:45], v[150:153], v[214:217], v[42:45]
	v_mfma_f32_16x16x32_bf16 v[30:33], v[134:137], v[218:221], v[30:33]
	v_mfma_f32_16x16x32_bf16 v[30:33], v[142:145], v[222:225], v[30:33]
	v_mfma_f32_16x16x32_bf16 v[26:29], v[146:149], v[218:221], v[26:29]
	v_mfma_f32_16x16x32_bf16 v[26:29], v[150:153], v[222:225], v[26:29]
	v_mfma_f32_16x16x32_bf16 v[14:17], v[134:137], v[226:229], v[14:17]
	v_mfma_f32_16x16x32_bf16 v[14:17], v[142:145], v[230:233], v[14:17]
	v_mfma_f32_16x16x32_bf16 v[10:13], v[146:149], v[226:229], v[10:13]
	v_mfma_f32_16x16x32_bf16 v[10:13], v[150:153], v[230:233], v[10:13]
	s_add_i32 s84, s84, 2
	s_add_u32 s6, s6, 0x100
	s_addc_u32 s7, s7, 0
	s_add_u32 s49, s49, 0x100
	s_addc_u32 s51, s51, 0
	s_setprio 0
	s_setprio 1
	v_mfma_f32_16x16x32_bf16 v[54:57], v[154:157], v[190:193], v[54:57]
	v_mfma_f32_16x16x32_bf16 v[54:57], v[158:161], v[194:197], v[54:57]
	v_mfma_f32_16x16x32_bf16 v[50:53], v[182:185], v[190:193], v[50:53]
	v_mfma_f32_16x16x32_bf16 v[50:53], v[186:189], v[194:197], v[50:53]
	v_mfma_f32_16x16x32_bf16 v[38:41], v[154:157], v[198:201], v[38:41]
	v_mfma_f32_16x16x32_bf16 v[38:41], v[158:161], v[214:217], v[38:41]
	v_mfma_f32_16x16x32_bf16 v[34:37], v[182:185], v[198:201], v[34:37]
	v_mfma_f32_16x16x32_bf16 v[34:37], v[186:189], v[214:217], v[34:37]
	v_mfma_f32_16x16x32_bf16 v[22:25], v[154:157], v[218:221], v[22:25]
	v_mfma_f32_16x16x32_bf16 v[22:25], v[158:161], v[222:225], v[22:25]
	v_mfma_f32_16x16x32_bf16 v[18:21], v[182:185], v[218:221], v[18:21]
	v_mfma_f32_16x16x32_bf16 v[18:21], v[186:189], v[222:225], v[18:21]
	v_mfma_f32_16x16x32_bf16 v[6:9], v[154:157], v[226:229], v[6:9]
	v_mfma_f32_16x16x32_bf16 v[6:9], v[158:161], v[230:233], v[6:9]
	v_mfma_f32_16x16x32_bf16 v[2:5], v[182:185], v[226:229], v[2:5]
	v_mfma_f32_16x16x32_bf16 v[2:5], v[186:189], v[230:233], v[2:5]
	s_setprio 0
	s_barrier
	s_cmp_gt_u32 s84, 5
	s_cbranch_scc0 .LBB0_604
	s_and_b64 vcc, exec, s[52:53]
	s_cbranch_vccz .LBB0_607
	s_barrier

.Lmid1_778:
	s_add_i32 s22, 0, 0x10000
	s_add_i32 s23, 0, 0x14000
	s_add_u32 s20, s76, 0xfffc0080
	s_addc_u32 s21, s77, -1
	s_cmp_eq_u32 vcc_hi, 12
	s_cselect_b32 s79, s61, s21
	s_cselect_b32 s78, s85, s20
	s_cselect_b32 s21, s59, vcc_lo
	s_cselect_b32 s20, s86, s87
	s_add_i32 m0, s43, 0xc000
	v_lshl_add_u64 v[202:203], s[76:77], 0, v[182:183]
	global_load_lds_dwordx4 v[202:203], off
	v_lshl_add_u64 v[202:203], v[202:203], 0, s[72:73]
	s_add_i32 m0, s43, 0xe000
	s_nop 0
	global_load_lds_dwordx4 v[202:203], off
	s_waitcnt vmcnt(8)
	s_waitcnt lgkmcnt(0)
	s_barrier
	s_setprio 1
	s_waitcnt lgkmcnt(0)
	v_mfma_f32_16x16x32_bf16 v[126:129], v[130:133], v[184:187], 0
	v_mfma_f32_16x16x32_bf16 v[126:129], v[134:137], v[188:191], v[126:129]
	v_mfma_f32_16x16x32_bf16 v[122:125], v[138:141], v[184:187], 0
	v_mfma_f32_16x16x32_bf16 v[122:125], v[142:145], v[188:191], v[122:125]
	v_mfma_f32_16x16x32_bf16 v[110:113], v[130:133], v[198:201], 0
	v_mfma_f32_16x16x32_bf16 v[110:113], v[134:137], v[214:217], v[110:113]
	v_mfma_f32_16x16x32_bf16 v[106:109], v[138:141], v[198:201], 0
	v_mfma_f32_16x16x32_bf16 v[106:109], v[142:145], v[214:217], v[106:109]
	v_mfma_f32_16x16x32_bf16 v[94:97], v[130:133], v[218:221], 0
	v_mfma_f32_16x16x32_bf16 v[94:97], v[134:137], v[222:225], v[94:97]
	v_mfma_f32_16x16x32_bf16 v[90:93], v[138:141], v[218:221], 0
	v_mfma_f32_16x16x32_bf16 v[90:93], v[142:145], v[222:225], v[90:93]
	v_mfma_f32_16x16x32_bf16 v[78:81], v[130:133], v[226:229], 0
	v_mfma_f32_16x16x32_bf16 v[78:81], v[134:137], v[230:233], v[78:81]
	v_mfma_f32_16x16x32_bf16 v[74:77], v[138:141], v[226:229], 0
	v_mfma_f32_16x16x32_bf16 v[74:77], v[142:145], v[230:233], v[74:77]
	s_setprio 0
	s_setprio 1
	v_mfma_f32_16x16x32_bf16 v[118:121], v[146:149], v[184:187], 0
	v_mfma_f32_16x16x32_bf16 v[118:121], v[150:153], v[188:191], v[118:121]
	v_mfma_f32_16x16x32_bf16 v[114:117], v[154:157], v[184:187], 0
	v_mfma_f32_16x16x32_bf16 v[114:117], v[158:161], v[188:191], v[114:117]
	v_mfma_f32_16x16x32_bf16 v[102:105], v[146:149], v[198:201], 0
	v_mfma_f32_16x16x32_bf16 v[102:105], v[150:153], v[214:217], v[102:105]
	v_mfma_f32_16x16x32_bf16 v[98:101], v[154:157], v[198:201], 0
	v_mfma_f32_16x16x32_bf16 v[98:101], v[158:161], v[214:217], v[98:101]
	v_mfma_f32_16x16x32_bf16 v[86:89], v[146:149], v[218:221], 0
	v_mfma_f32_16x16x32_bf16 v[86:89], v[150:153], v[222:225], v[86:89]
	v_mfma_f32_16x16x32_bf16 v[82:85], v[154:157], v[218:221], 0
	v_mfma_f32_16x16x32_bf16 v[82:85], v[158:161], v[222:225], v[82:85]
	v_mfma_f32_16x16x32_bf16 v[70:73], v[146:149], v[226:229], 0
	v_mfma_f32_16x16x32_bf16 v[70:73], v[150:153], v[230:233], v[70:73]
	v_mfma_f32_16x16x32_bf16 v[66:69], v[154:157], v[226:229], 0
	v_mfma_f32_16x16x32_bf16 v[66:69], v[158:161], v[230:233], v[66:69]
	s_setprio 0
	s_barrier
	ds_read_b128 v[184:187], v196 offset:16384
	ds_read_b128 v[188:191], v196 offset:17408
	ds_read_b128 v[198:201], v196 offset:18432
	ds_read_b128 v[214:217], v196 offset:19456
	ds_read_b128 v[218:221], v196 offset:20480
	ds_read_b128 v[222:225], v196 offset:21504
	ds_read_b128 v[226:229], v196 offset:22528
	ds_read_b128 v[230:233], v196 offset:23552
	v_lshl_add_u64 v[202:203], s[20:21], 0, v[0:1]
	s_add_i32 s20, s22, s14
	s_mov_b32 m0, s20
	s_nop 0
	s_nop 0
	global_load_lds_dwordx4 v[202:203], off
	v_lshl_add_u64 v[234:235], v[202:203], 0, s[72:73]
	s_add_i32 m0, s20, 0x2000
	s_add_i32 s20, s23, s14
	global_load_lds_dwordx4 v[234:235], off
	v_lshl_add_u64 v[234:235], v[202:203], 0, s[28:29]
	s_mov_b32 m0, s20
	s_nop 0
	global_load_lds_dwordx4 v[234:235], off
	v_lshl_add_u64 v[234:235], v[202:203], 0, s[82:83]
	s_add_i32 m0, s20, 0x2000
	s_nop 0
	global_load_lds_dwordx4 v[234:235], off
	v_lshl_add_u64 v[234:235], s[78:79], 0, v[162:163]
	s_mov_b32 m0, s43
	v_lshl_add_u64 v[236:237], v[234:235], 0, s[72:73]
	global_load_lds_dwordx4 v[234:235], off
	s_mov_b32 m0, s46
	s_nop 0
	global_load_lds_dwordx4 v[236:237], off
	s_waitcnt vmcnt(8)
	s_waitcnt lgkmcnt(0)
	s_barrier
	s_setprio 1
	s_waitcnt lgkmcnt(0)
	v_mfma_f32_16x16x32_bf16 v[62:65], v[130:133], v[184:187], 0
	v_mfma_f32_16x16x32_bf16 v[62:65], v[134:137], v[188:191], v[62:65]
	v_mfma_f32_16x16x32_bf16 v[58:61], v[138:141], v[184:187], 0
	v_mfma_f32_16x16x32_bf16 v[58:61], v[142:145], v[188:191], v[58:61]
	v_mfma_f32_16x16x32_bf16 v[46:49], v[130:133], v[198:201], 0
	v_mfma_f32_16x16x32_bf16 v[46:49], v[134:137], v[214:217], v[46:49]
	v_mfma_f32_16x16x32_bf16 v[42:45], v[138:141], v[198:201], 0
	v_mfma_f32_16x16x32_bf16 v[42:45], v[142:145], v[214:217], v[42:45]
	v_mfma_f32_16x16x32_bf16 v[30:33], v[130:133], v[218:221], 0
	v_mfma_f32_16x16x32_bf16 v[30:33], v[134:137], v[222:225], v[30:33]
	v_mfma_f32_16x16x32_bf16 v[26:29], v[138:141], v[218:221], 0
	v_mfma_f32_16x16x32_bf16 v[26:29], v[142:145], v[222:225], v[26:29]
	v_mfma_f32_16x16x32_bf16 v[14:17], v[130:133], v[226:229], 0
	v_mfma_f32_16x16x32_bf16 v[14:17], v[134:137], v[230:233], v[14:17]
	v_mfma_f32_16x16x32_bf16 v[10:13], v[138:141], v[226:229], 0
	v_mfma_f32_16x16x32_bf16 v[10:13], v[142:145], v[230:233], v[10:13]
	s_setprio 0
	s_setprio 1
	v_mfma_f32_16x16x32_bf16 v[54:57], v[146:149], v[184:187], 0
	v_mfma_f32_16x16x32_bf16 v[54:57], v[150:153], v[188:191], v[54:57]
	v_mfma_f32_16x16x32_bf16 v[50:53], v[154:157], v[184:187], 0
	v_mfma_f32_16x16x32_bf16 v[50:53], v[158:161], v[188:191], v[50:53]
	v_mfma_f32_16x16x32_bf16 v[38:41], v[146:149], v[198:201], 0
	v_mfma_f32_16x16x32_bf16 v[38:41], v[150:153], v[214:217], v[38:41]
	v_mfma_f32_16x16x32_bf16 v[34:37], v[154:157], v[198:201], 0
	v_mfma_f32_16x16x32_bf16 v[34:37], v[158:161], v[214:217], v[34:37]
	v_mfma_f32_16x16x32_bf16 v[22:25], v[146:149], v[218:221], 0
	v_mfma_f32_16x16x32_bf16 v[22:25], v[150:153], v[222:225], v[22:25]
	v_mfma_f32_16x16x32_bf16 v[18:21], v[154:157], v[218:221], 0
	v_mfma_f32_16x16x32_bf16 v[18:21], v[158:161], v[222:225], v[18:21]
	v_mfma_f32_16x16x32_bf16 v[6:9], v[146:149], v[226:229], 0
	v_mfma_f32_16x16x32_bf16 v[6:9], v[150:153], v[230:233], v[6:9]
	v_mfma_f32_16x16x32_bf16 v[2:5], v[154:157], v[226:229], 0
	v_mfma_f32_16x16x32_bf16 v[2:5], v[158:161], v[230:233], v[2:5]
	s_setprio 0
	s_barrier
	s_add_i32 s20, 0, 0x18000
	s_add_i32 s21, 0, 0x1c000
	v_add_u32_e32 v142, s20, v193
	v_add_u32_e32 v158, s21, v193
	ds_read_b128 v[130:133], v142
	ds_read_b128 v[134:137], v142 offset:1024
	ds_read_b128 v[138:141], v142 offset:2048
	ds_read_b128 v[142:145], v142 offset:3072
	ds_read_b128 v[146:149], v158
	ds_read_b128 v[150:153], v158 offset:1024
	ds_read_b128 v[154:157], v158 offset:2048
	ds_read_b128 v[158:161], v158 offset:3072
	ds_read_b128 v[184:187], v196 offset:32768
	ds_read_b128 v[188:191], v196 offset:33792
	ds_read_b128 v[198:201], v196 offset:34816
	ds_read_b128 v[214:217], v196 offset:35840
	ds_read_b128 v[218:221], v196 offset:36864
	ds_read_b128 v[222:225], v196 offset:37888
	ds_read_b128 v[226:229], v196 offset:38912
	ds_read_b128 v[230:233], v196 offset:39936
	s_mov_b32 m0, s47
	v_lshl_add_u64 v[236:237], v[234:235], 0, s[28:29]
	global_load_lds_dwordx4 v[236:237], off
	v_lshl_add_u64 v[236:237], v[234:235], 0, s[82:83]
	s_mov_b32 m0, s88
	s_nop 0
	global_load_lds_dwordx4 v[236:237], off
	s_waitcnt vmcnt(8)
	s_waitcnt lgkmcnt(0)
	s_barrier
	s_setprio 1
	s_waitcnt lgkmcnt(0)
	v_mfma_f32_16x16x32_bf16 v[126:129], v[130:133], v[184:187], v[126:129]
	v_mfma_f32_16x16x32_bf16 v[126:129], v[134:137], v[188:191], v[126:129]
	v_mfma_f32_16x16x32_bf16 v[122:125], v[138:141], v[184:187], v[122:125]
	v_mfma_f32_16x16x32_bf16 v[122:125], v[142:145], v[188:191], v[122:125]
	v_mfma_f32_16x16x32_bf16 v[110:113], v[130:133], v[198:201], v[110:113]
	v_mfma_f32_16x16x32_bf16 v[110:113], v[134:137], v[214:217], v[110:113]
	v_mfma_f32_16x16x32_bf16 v[106:109], v[138:141], v[198:201], v[106:109]
	v_mfma_f32_16x16x32_bf16 v[106:109], v[142:145], v[214:217], v[106:109]
	v_mfma_f32_16x16x32_bf16 v[94:97], v[130:133], v[218:221], v[94:97]
	v_mfma_f32_16x16x32_bf16 v[94:97], v[134:137], v[222:225], v[94:97]
	v_mfma_f32_16x16x32_bf16 v[90:93], v[138:141], v[218:221], v[90:93]
	v_mfma_f32_16x16x32_bf16 v[90:93], v[142:145], v[222:225], v[90:93]
	v_mfma_f32_16x16x32_bf16 v[78:81], v[130:133], v[226:229], v[78:81]
	v_mfma_f32_16x16x32_bf16 v[78:81], v[134:137], v[230:233], v[78:81]
	v_mfma_f32_16x16x32_bf16 v[74:77], v[138:141], v[226:229], v[74:77]
	v_mfma_f32_16x16x32_bf16 v[74:77], v[142:145], v[230:233], v[74:77]
	s_setprio 0
	s_setprio 1
	v_mfma_f32_16x16x32_bf16 v[118:121], v[146:149], v[184:187], v[118:121]
	v_mfma_f32_16x16x32_bf16 v[118:121], v[150:153], v[188:191], v[118:121]
	v_mfma_f32_16x16x32_bf16 v[114:117], v[154:157], v[184:187], v[114:117]
	v_mfma_f32_16x16x32_bf16 v[114:117], v[158:161], v[188:191], v[114:117]
	v_mfma_f32_16x16x32_bf16 v[102:105], v[146:149], v[198:201], v[102:105]
	v_mfma_f32_16x16x32_bf16 v[102:105], v[150:153], v[214:217], v[102:105]
	v_mfma_f32_16x16x32_bf16 v[98:101], v[154:157], v[198:201], v[98:101]
	v_mfma_f32_16x16x32_bf16 v[98:101], v[158:161], v[214:217], v[98:101]
	v_mfma_f32_16x16x32_bf16 v[86:89], v[146:149], v[218:221], v[86:89]
	v_mfma_f32_16x16x32_bf16 v[86:89], v[150:153], v[222:225], v[86:89]
	v_mfma_f32_16x16x32_bf16 v[82:85], v[154:157], v[218:221], v[82:85]
	v_mfma_f32_16x16x32_bf16 v[82:85], v[158:161], v[222:225], v[82:85]
	v_mfma_f32_16x16x32_bf16 v[70:73], v[146:149], v[226:229], v[70:73]
	v_mfma_f32_16x16x32_bf16 v[70:73], v[150:153], v[230:233], v[70:73]
	v_mfma_f32_16x16x32_bf16 v[66:69], v[154:157], v[226:229], v[66:69]
	v_mfma_f32_16x16x32_bf16 v[66:69], v[158:161], v[230:233], v[66:69]
	s_setprio 0
	s_barrier
	ds_read_b128 v[184:187], v196 offset:49152
	ds_read_b128 v[188:191], v196 offset:50176
	ds_read_b128 v[198:201], v196 offset:51200
	ds_read_b128 v[214:217], v196 offset:52224
	ds_read_b128 v[218:221], v196 offset:53248
	ds_read_b128 v[222:225], v196 offset:54272
	ds_read_b128 v[226:229], v196 offset:55296
	ds_read_b128 v[230:233], v196 offset:56320
	s_add_i32 s20, s20, s14
	s_mov_b32 m0, s20
	v_lshl_add_u64 v[236:237], v[202:203], 0, s[34:35]
	global_load_lds_dwordx4 v[236:237], off
	v_lshl_add_u64 v[236:237], v[202:203], 0, s[38:39]
	s_add_i32 m0, s20, 0x2000
	s_add_i32 s20, s21, s14
	global_load_lds_dwordx4 v[236:237], off
	v_lshl_add_u64 v[236:237], v[202:203], 0, s[44:45]
	s_mov_b32 m0, s20
	v_lshl_add_u64 v[202:203], v[202:203], 0, s[10:11]
	global_load_lds_dwordx4 v[236:237], off
	s_add_i32 m0, s20, 0x2000
	s_nop 0
	global_load_lds_dwordx4 v[202:203], off
	v_lshl_add_u64 v[202:203], v[234:235], 0, s[34:35]
	s_mov_b32 m0, s89
	s_nop 0
	global_load_lds_dwordx4 v[202:203], off
	v_lshl_add_u64 v[202:203], v[234:235], 0, s[38:39]
	s_mov_b32 m0, s90
	s_nop 0
	global_load_lds_dwordx4 v[202:203], off
	s_waitcnt vmcnt(8)
	s_waitcnt lgkmcnt(0)
	s_barrier
	s_setprio 1
	s_waitcnt lgkmcnt(0)
	v_mfma_f32_16x16x32_bf16 v[62:65], v[130:133], v[184:187], v[62:65]
	v_mfma_f32_16x16x32_bf16 v[62:65], v[134:137], v[188:191], v[62:65]
	v_mfma_f32_16x16x32_bf16 v[58:61], v[138:141], v[184:187], v[58:61]
	v_mfma_f32_16x16x32_bf16 v[58:61], v[142:145], v[188:191], v[58:61]
	v_mfma_f32_16x16x32_bf16 v[46:49], v[130:133], v[198:201], v[46:49]
	v_mfma_f32_16x16x32_bf16 v[46:49], v[134:137], v[214:217], v[46:49]
	v_mfma_f32_16x16x32_bf16 v[42:45], v[138:141], v[198:201], v[42:45]
	v_mfma_f32_16x16x32_bf16 v[42:45], v[142:145], v[214:217], v[42:45]
	v_mfma_f32_16x16x32_bf16 v[30:33], v[130:133], v[218:221], v[30:33]
	v_mfma_f32_16x16x32_bf16 v[30:33], v[134:137], v[222:225], v[30:33]
	v_mfma_f32_16x16x32_bf16 v[26:29], v[138:141], v[218:221], v[26:29]
	v_mfma_f32_16x16x32_bf16 v[26:29], v[142:145], v[222:225], v[26:29]
	v_mfma_f32_16x16x32_bf16 v[14:17], v[130:133], v[226:229], v[14:17]
	v_mfma_f32_16x16x32_bf16 v[14:17], v[134:137], v[230:233], v[14:17]
	v_mfma_f32_16x16x32_bf16 v[10:13], v[138:141], v[226:229], v[10:13]
	v_mfma_f32_16x16x32_bf16 v[10:13], v[142:145], v[230:233], v[10:13]
	s_add_i32 vcc_hi, vcc_hi, 2
	s_add_u32 s76, s76, 0x100
	s_addc_u32 s77, s77, 0
	s_add_u32 s87, s87, 0x100
	s_addc_u32 vcc_lo, vcc_lo, 0
	s_setprio 0
	s_setprio 1
	v_mfma_f32_16x16x32_bf16 v[54:57], v[146:149], v[184:187], v[54:57]
	v_mfma_f32_16x16x32_bf16 v[54:57], v[150:153], v[188:191], v[54:57]
	v_mfma_f32_16x16x32_bf16 v[50:53], v[154:157], v[184:187], v[50:53]
	v_mfma_f32_16x16x32_bf16 v[50:53], v[158:161], v[188:191], v[50:53]
	v_mfma_f32_16x16x32_bf16 v[38:41], v[146:149], v[198:201], v[38:41]
	v_mfma_f32_16x16x32_bf16 v[38:41], v[150:153], v[214:217], v[38:41]
	v_mfma_f32_16x16x32_bf16 v[34:37], v[154:157], v[198:201], v[34:37]
	v_mfma_f32_16x16x32_bf16 v[34:37], v[158:161], v[214:217], v[34:37]
	v_mfma_f32_16x16x32_bf16 v[22:25], v[146:149], v[218:221], v[22:25]
	v_mfma_f32_16x16x32_bf16 v[22:25], v[150:153], v[222:225], v[22:25]
	v_mfma_f32_16x16x32_bf16 v[18:21], v[154:157], v[218:221], v[18:21]
	v_mfma_f32_16x16x32_bf16 v[18:21], v[158:161], v[222:225], v[18:21]
	v_mfma_f32_16x16x32_bf16 v[6:9], v[146:149], v[226:229], v[6:9]
	v_mfma_f32_16x16x32_bf16 v[6:9], v[150:153], v[230:233], v[6:9]
	v_mfma_f32_16x16x32_bf16 v[2:5], v[154:157], v[226:229], v[2:5]
	v_mfma_f32_16x16x32_bf16 v[2:5], v[158:161], v[230:233], v[2:5]
	s_setprio 0
	s_barrier
	s_branch .LBB0_778
	.p2alignl 6, 3212836864
.LBB0_778:
	s_add_i32 s22, 0, 0x10000
	s_add_i32 s23, 0, 0x14000
	v_add_u32_e32 v142, s22, v193
	v_add_u32_e32 v158, s23, v193
	ds_read_b128 v[130:133], v142
	ds_read_b128 v[134:137], v142 offset:1024
	ds_read_b128 v[138:141], v142 offset:2048
	ds_read_b128 v[142:145], v142 offset:3072
	ds_read_b128 v[146:149], v158
	ds_read_b128 v[150:153], v158 offset:1024
	ds_read_b128 v[154:157], v158 offset:2048
	ds_read_b128 v[158:161], v158 offset:3072
	ds_read_b128 v[184:187], v196
	ds_read_b128 v[188:191], v196 offset:1024
	ds_read_b128 v[198:201], v196 offset:2048
	ds_read_b128 v[214:217], v196 offset:3072
	ds_read_b128 v[218:221], v196 offset:4096
	ds_read_b128 v[222:225], v196 offset:5120
	ds_read_b128 v[226:229], v196 offset:6144
	ds_read_b128 v[230:233], v196 offset:7168
	s_add_u32 s20, s76, 0xfffc0080
	s_addc_u32 s21, s77, -1
	s_cmp_eq_u32 vcc_hi, 12
	s_cselect_b32 s79, s61, s21
	s_cselect_b32 s78, s85, s20
	s_cselect_b32 s21, s59, vcc_lo
	s_cselect_b32 s20, s86, s87
	s_add_i32 m0, s43, 0xc000
	v_lshl_add_u64 v[202:203], s[76:77], 0, v[182:183]
	global_load_lds_dwordx4 v[202:203], off
	v_lshl_add_u64 v[202:203], v[202:203], 0, s[72:73]
	s_add_i32 m0, s43, 0xe000
	s_nop 0
	global_load_lds_dwordx4 v[202:203], off
	s_waitcnt vmcnt(8)
	s_waitcnt lgkmcnt(0)
	s_barrier
	s_setprio 1
	s_waitcnt lgkmcnt(0)
	v_mfma_f32_16x16x32_bf16 v[126:129], v[130:133], v[184:187], v[126:129]
	v_mfma_f32_16x16x32_bf16 v[126:129], v[134:137], v[188:191], v[126:129]
	v_mfma_f32_16x16x32_bf16 v[122:125], v[138:141], v[184:187], v[122:125]
	v_mfma_f32_16x16x32_bf16 v[122:125], v[142:145], v[188:191], v[122:125]
	v_mfma_f32_16x16x32_bf16 v[110:113], v[130:133], v[198:201], v[110:113]
	v_mfma_f32_16x16x32_bf16 v[110:113], v[134:137], v[214:217], v[110:113]
	v_mfma_f32_16x16x32_bf16 v[106:109], v[138:141], v[198:201], v[106:109]
	v_mfma_f32_16x16x32_bf16 v[106:109], v[142:145], v[214:217], v[106:109]
	v_mfma_f32_16x16x32_bf16 v[94:97], v[130:133], v[218:221], v[94:97]
	v_mfma_f32_16x16x32_bf16 v[94:97], v[134:137], v[222:225], v[94:97]
	v_mfma_f32_16x16x32_bf16 v[90:93], v[138:141], v[218:221], v[90:93]
	v_mfma_f32_16x16x32_bf16 v[90:93], v[142:145], v[222:225], v[90:93]
	v_mfma_f32_16x16x32_bf16 v[78:81], v[130:133], v[226:229], v[78:81]
	v_mfma_f32_16x16x32_bf16 v[78:81], v[134:137], v[230:233], v[78:81]
	v_mfma_f32_16x16x32_bf16 v[74:77], v[138:141], v[226:229], v[74:77]
	v_mfma_f32_16x16x32_bf16 v[74:77], v[142:145], v[230:233], v[74:77]
	s_setprio 0
	s_setprio 1
	v_mfma_f32_16x16x32_bf16 v[118:121], v[146:149], v[184:187], v[118:121]
	v_mfma_f32_16x16x32_bf16 v[118:121], v[150:153], v[188:191], v[118:121]
	v_mfma_f32_16x16x32_bf16 v[114:117], v[154:157], v[184:187], v[114:117]
	v_mfma_f32_16x16x32_bf16 v[114:117], v[158:161], v[188:191], v[114:117]
	v_mfma_f32_16x16x32_bf16 v[102:105], v[146:149], v[198:201], v[102:105]
	v_mfma_f32_16x16x32_bf16 v[102:105], v[150:153], v[214:217], v[102:105]
	v_mfma_f32_16x16x32_bf16 v[98:101], v[154:157], v[198:201], v[98:101]
	v_mfma_f32_16x16x32_bf16 v[98:101], v[158:161], v[214:217], v[98:101]
	v_mfma_f32_16x16x32_bf16 v[86:89], v[146:149], v[218:221], v[86:89]
	v_mfma_f32_16x16x32_bf16 v[86:89], v[150:153], v[222:225], v[86:89]
	v_mfma_f32_16x16x32_bf16 v[82:85], v[154:157], v[218:221], v[82:85]
	v_mfma_f32_16x16x32_bf16 v[82:85], v[158:161], v[222:225], v[82:85]
	v_mfma_f32_16x16x32_bf16 v[70:73], v[146:149], v[226:229], v[70:73]
	v_mfma_f32_16x16x32_bf16 v[70:73], v[150:153], v[230:233], v[70:73]
	v_mfma_f32_16x16x32_bf16 v[66:69], v[154:157], v[226:229], v[66:69]
	v_mfma_f32_16x16x32_bf16 v[66:69], v[158:161], v[230:233], v[66:69]
	s_setprio 0
	s_barrier
	ds_read_b128 v[184:187], v196 offset:16384
	ds_read_b128 v[188:191], v196 offset:17408
	ds_read_b128 v[198:201], v196 offset:18432
	ds_read_b128 v[214:217], v196 offset:19456
	ds_read_b128 v[218:221], v196 offset:20480
	ds_read_b128 v[222:225], v196 offset:21504
	ds_read_b128 v[226:229], v196 offset:22528
	ds_read_b128 v[230:233], v196 offset:23552
	v_lshl_add_u64 v[202:203], s[20:21], 0, v[0:1]
	s_add_i32 s20, s22, s14
	s_mov_b32 m0, s20
	s_nop 0
	s_nop 0
	global_load_lds_dwordx4 v[202:203], off
	v_lshl_add_u64 v[234:235], v[202:203], 0, s[72:73]
	s_add_i32 m0, s20, 0x2000
	s_add_i32 s20, s23, s14
	global_load_lds_dwordx4 v[234:235], off
	v_lshl_add_u64 v[234:235], v[202:203], 0, s[28:29]
	s_mov_b32 m0, s20
	s_nop 0
	global_load_lds_dwordx4 v[234:235], off
	v_lshl_add_u64 v[234:235], v[202:203], 0, s[82:83]
	s_add_i32 m0, s20, 0x2000
	s_nop 0
	global_load_lds_dwordx4 v[234:235], off
	v_lshl_add_u64 v[234:235], s[78:79], 0, v[162:163]
	s_mov_b32 m0, s43
	v_lshl_add_u64 v[236:237], v[234:235], 0, s[72:73]
	global_load_lds_dwordx4 v[234:235], off
	s_mov_b32 m0, s46
	s_nop 0
	global_load_lds_dwordx4 v[236:237], off
	s_waitcnt vmcnt(8)
	s_waitcnt lgkmcnt(0)
	s_barrier
	s_setprio 1
	s_waitcnt lgkmcnt(0)
	v_mfma_f32_16x16x32_bf16 v[62:65], v[130:133], v[184:187], v[62:65]
	v_mfma_f32_16x16x32_bf16 v[62:65], v[134:137], v[188:191], v[62:65]
	v_mfma_f32_16x16x32_bf16 v[58:61], v[138:141], v[184:187], v[58:61]
	v_mfma_f32_16x16x32_bf16 v[58:61], v[142:145], v[188:191], v[58:61]
	v_mfma_f32_16x16x32_bf16 v[46:49], v[130:133], v[198:201], v[46:49]
	v_mfma_f32_16x16x32_bf16 v[46:49], v[134:137], v[214:217], v[46:49]
	v_mfma_f32_16x16x32_bf16 v[42:45], v[138:141], v[198:201], v[42:45]
	v_mfma_f32_16x16x32_bf16 v[42:45], v[142:145], v[214:217], v[42:45]
	v_mfma_f32_16x16x32_bf16 v[30:33], v[130:133], v[218:221], v[30:33]
	v_mfma_f32_16x16x32_bf16 v[30:33], v[134:137], v[222:225], v[30:33]
	v_mfma_f32_16x16x32_bf16 v[26:29], v[138:141], v[218:221], v[26:29]
	v_mfma_f32_16x16x32_bf16 v[26:29], v[142:145], v[222:225], v[26:29]
	v_mfma_f32_16x16x32_bf16 v[14:17], v[130:133], v[226:229], v[14:17]
	v_mfma_f32_16x16x32_bf16 v[14:17], v[134:137], v[230:233], v[14:17]
	v_mfma_f32_16x16x32_bf16 v[10:13], v[138:141], v[226:229], v[10:13]
	v_mfma_f32_16x16x32_bf16 v[10:13], v[142:145], v[230:233], v[10:13]
	s_setprio 0
	s_setprio 1
	v_mfma_f32_16x16x32_bf16 v[54:57], v[146:149], v[184:187], v[54:57]
	v_mfma_f32_16x16x32_bf16 v[54:57], v[150:153], v[188:191], v[54:57]
	v_mfma_f32_16x16x32_bf16 v[50:53], v[154:157], v[184:187], v[50:53]
	v_mfma_f32_16x16x32_bf16 v[50:53], v[158:161], v[188:191], v[50:53]
	v_mfma_f32_16x16x32_bf16 v[38:41], v[146:149], v[198:201], v[38:41]
	v_mfma_f32_16x16x32_bf16 v[38:41], v[150:153], v[214:217], v[38:41]
	v_mfma_f32_16x16x32_bf16 v[34:37], v[154:157], v[198:201], v[34:37]
	v_mfma_f32_16x16x32_bf16 v[34:37], v[158:161], v[214:217], v[34:37]
	v_mfma_f32_16x16x32_bf16 v[22:25], v[146:149], v[218:221], v[22:25]
	v_mfma_f32_16x16x32_bf16 v[22:25], v[150:153], v[222:225], v[22:25]
	v_mfma_f32_16x16x32_bf16 v[18:21], v[154:157], v[218:221], v[18:21]
	v_mfma_f32_16x16x32_bf16 v[18:21], v[158:161], v[222:225], v[18:21]
	v_mfma_f32_16x16x32_bf16 v[6:9], v[146:149], v[226:229], v[6:9]
	v_mfma_f32_16x16x32_bf16 v[6:9], v[150:153], v[230:233], v[6:9]
	v_mfma_f32_16x16x32_bf16 v[2:5], v[154:157], v[226:229], v[2:5]
	v_mfma_f32_16x16x32_bf16 v[2:5], v[158:161], v[230:233], v[2:5]
	s_setprio 0
	s_barrier
	s_add_i32 s20, 0, 0x18000
	s_add_i32 s21, 0, 0x1c000
	v_add_u32_e32 v142, s20, v193
	v_add_u32_e32 v158, s21, v193
	ds_read_b128 v[130:133], v142
	ds_read_b128 v[134:137], v142 offset:1024
	ds_read_b128 v[138:141], v142 offset:2048
	ds_read_b128 v[142:145], v142 offset:3072
	ds_read_b128 v[146:149], v158
	ds_read_b128 v[150:153], v158 offset:1024
	ds_read_b128 v[154:157], v158 offset:2048
	ds_read_b128 v[158:161], v158 offset:3072
	ds_read_b128 v[184:187], v196 offset:32768
	ds_read_b128 v[188:191], v196 offset:33792
	ds_read_b128 v[198:201], v196 offset:34816
	ds_read_b128 v[214:217], v196 offset:35840
	ds_read_b128 v[218:221], v196 offset:36864
	ds_read_b128 v[222:225], v196 offset:37888
	ds_read_b128 v[226:229], v196 offset:38912
	ds_read_b128 v[230:233], v196 offset:39936
	s_mov_b32 m0, s47
	v_lshl_add_u64 v[236:237], v[234:235], 0, s[28:29]
	global_load_lds_dwordx4 v[236:237], off
	v_lshl_add_u64 v[236:237], v[234:235], 0, s[82:83]
	s_mov_b32 m0, s88
	s_nop 0
	global_load_lds_dwordx4 v[236:237], off
	s_waitcnt vmcnt(8)
	s_waitcnt lgkmcnt(0)
	s_barrier
	s_setprio 1
	s_waitcnt lgkmcnt(0)
	v_mfma_f32_16x16x32_bf16 v[126:129], v[130:133], v[184:187], v[126:129]
	v_mfma_f32_16x16x32_bf16 v[126:129], v[134:137], v[188:191], v[126:129]
	v_mfma_f32_16x16x32_bf16 v[122:125], v[138:141], v[184:187], v[122:125]
	v_mfma_f32_16x16x32_bf16 v[122:125], v[142:145], v[188:191], v[122:125]
	v_mfma_f32_16x16x32_bf16 v[110:113], v[130:133], v[198:201], v[110:113]
	v_mfma_f32_16x16x32_bf16 v[110:113], v[134:137], v[214:217], v[110:113]
	v_mfma_f32_16x16x32_bf16 v[106:109], v[138:141], v[198:201], v[106:109]
	v_mfma_f32_16x16x32_bf16 v[106:109], v[142:145], v[214:217], v[106:109]
	v_mfma_f32_16x16x32_bf16 v[94:97], v[130:133], v[218:221], v[94:97]
	v_mfma_f32_16x16x32_bf16 v[94:97], v[134:137], v[222:225], v[94:97]
	v_mfma_f32_16x16x32_bf16 v[90:93], v[138:141], v[218:221], v[90:93]
	v_mfma_f32_16x16x32_bf16 v[90:93], v[142:145], v[222:225], v[90:93]
	v_mfma_f32_16x16x32_bf16 v[78:81], v[130:133], v[226:229], v[78:81]
	v_mfma_f32_16x16x32_bf16 v[78:81], v[134:137], v[230:233], v[78:81]
	v_mfma_f32_16x16x32_bf16 v[74:77], v[138:141], v[226:229], v[74:77]
	v_mfma_f32_16x16x32_bf16 v[74:77], v[142:145], v[230:233], v[74:77]
	s_setprio 0
	s_setprio 1
	v_mfma_f32_16x16x32_bf16 v[118:121], v[146:149], v[184:187], v[118:121]
	v_mfma_f32_16x16x32_bf16 v[118:121], v[150:153], v[188:191], v[118:121]
	v_mfma_f32_16x16x32_bf16 v[114:117], v[154:157], v[184:187], v[114:117]
	v_mfma_f32_16x16x32_bf16 v[114:117], v[158:161], v[188:191], v[114:117]
	v_mfma_f32_16x16x32_bf16 v[102:105], v[146:149], v[198:201], v[102:105]
	v_mfma_f32_16x16x32_bf16 v[102:105], v[150:153], v[214:217], v[102:105]
	v_mfma_f32_16x16x32_bf16 v[98:101], v[154:157], v[198:201], v[98:101]
	v_mfma_f32_16x16x32_bf16 v[98:101], v[158:161], v[214:217], v[98:101]
	v_mfma_f32_16x16x32_bf16 v[86:89], v[146:149], v[218:221], v[86:89]
	v_mfma_f32_16x16x32_bf16 v[86:89], v[150:153], v[222:225], v[86:89]
	v_mfma_f32_16x16x32_bf16 v[82:85], v[154:157], v[218:221], v[82:85]
	v_mfma_f32_16x16x32_bf16 v[82:85], v[158:161], v[222:225], v[82:85]
	v_mfma_f32_16x16x32_bf16 v[70:73], v[146:149], v[226:229], v[70:73]
	v_mfma_f32_16x16x32_bf16 v[70:73], v[150:153], v[230:233], v[70:73]
	v_mfma_f32_16x16x32_bf16 v[66:69], v[154:157], v[226:229], v[66:69]
	v_mfma_f32_16x16x32_bf16 v[66:69], v[158:161], v[230:233], v[66:69]
	s_setprio 0
	s_barrier
	ds_read_b128 v[184:187], v196 offset:49152
	ds_read_b128 v[188:191], v196 offset:50176
	ds_read_b128 v[198:201], v196 offset:51200
	ds_read_b128 v[214:217], v196 offset:52224
	ds_read_b128 v[218:221], v196 offset:53248
	ds_read_b128 v[222:225], v196 offset:54272
	ds_read_b128 v[226:229], v196 offset:55296
	ds_read_b128 v[230:233], v196 offset:56320
	s_add_i32 s20, s20, s14
	s_mov_b32 m0, s20
	v_lshl_add_u64 v[236:237], v[202:203], 0, s[34:35]
	global_load_lds_dwordx4 v[236:237], off
	v_lshl_add_u64 v[236:237], v[202:203], 0, s[38:39]
	s_add_i32 m0, s20, 0x2000
	s_add_i32 s20, s21, s14
	global_load_lds_dwordx4 v[236:237], off
	v_lshl_add_u64 v[236:237], v[202:203], 0, s[44:45]
	s_mov_b32 m0, s20
	v_lshl_add_u64 v[202:203], v[202:203], 0, s[10:11]
	global_load_lds_dwordx4 v[236:237], off
	s_add_i32 m0, s20, 0x2000
	s_nop 0
	global_load_lds_dwordx4 v[202:203], off
	v_lshl_add_u64 v[202:203], v[234:235], 0, s[34:35]
	s_mov_b32 m0, s89
	s_nop 0
	global_load_lds_dwordx4 v[202:203], off
	v_lshl_add_u64 v[202:203], v[234:235], 0, s[38:39]
	s_mov_b32 m0, s90
	s_nop 0
	global_load_lds_dwordx4 v[202:203], off
	s_waitcnt vmcnt(8)
	s_waitcnt lgkmcnt(0)
	s_barrier
	s_setprio 1
	s_waitcnt lgkmcnt(0)
	v_mfma_f32_16x16x32_bf16 v[62:65], v[130:133], v[184:187], v[62:65]
	v_mfma_f32_16x16x32_bf16 v[62:65], v[134:137], v[188:191], v[62:65]
	v_mfma_f32_16x16x32_bf16 v[58:61], v[138:141], v[184:187], v[58:61]
	v_mfma_f32_16x16x32_bf16 v[58:61], v[142:145], v[188:191], v[58:61]
	v_mfma_f32_16x16x32_bf16 v[46:49], v[130:133], v[198:201], v[46:49]
	v_mfma_f32_16x16x32_bf16 v[46:49], v[134:137], v[214:217], v[46:49]
	v_mfma_f32_16x16x32_bf16 v[42:45], v[138:141], v[198:201], v[42:45]
	v_mfma_f32_16x16x32_bf16 v[42:45], v[142:145], v[214:217], v[42:45]
	v_mfma_f32_16x16x32_bf16 v[30:33], v[130:133], v[218:221], v[30:33]
	v_mfma_f32_16x16x32_bf16 v[30:33], v[134:137], v[222:225], v[30:33]
	v_mfma_f32_16x16x32_bf16 v[26:29], v[138:141], v[218:221], v[26:29]
	v_mfma_f32_16x16x32_bf16 v[26:29], v[142:145], v[222:225], v[26:29]
	v_mfma_f32_16x16x32_bf16 v[14:17], v[130:133], v[226:229], v[14:17]
	v_mfma_f32_16x16x32_bf16 v[14:17], v[134:137], v[230:233], v[14:17]
	v_mfma_f32_16x16x32_bf16 v[10:13], v[138:141], v[226:229], v[10:13]
	v_mfma_f32_16x16x32_bf16 v[10:13], v[142:145], v[230:233], v[10:13]
	s_add_i32 vcc_hi, vcc_hi, 2
	s_add_u32 s76, s76, 0x100
	s_addc_u32 s77, s77, 0
	s_add_u32 s87, s87, 0x100
	s_addc_u32 vcc_lo, vcc_lo, 0
	s_setprio 0
	s_setprio 1
	v_mfma_f32_16x16x32_bf16 v[54:57], v[146:149], v[184:187], v[54:57]
	v_mfma_f32_16x16x32_bf16 v[54:57], v[150:153], v[188:191], v[54:57]
	v_mfma_f32_16x16x32_bf16 v[50:53], v[154:157], v[184:187], v[50:53]
	v_mfma_f32_16x16x32_bf16 v[50:53], v[158:161], v[188:191], v[50:53]
	v_mfma_f32_16x16x32_bf16 v[38:41], v[146:149], v[198:201], v[38:41]
	v_mfma_f32_16x16x32_bf16 v[38:41], v[150:153], v[214:217], v[38:41]
	v_mfma_f32_16x16x32_bf16 v[34:37], v[154:157], v[198:201], v[34:37]
	v_mfma_f32_16x16x32_bf16 v[34:37], v[158:161], v[214:217], v[34:37]
	v_mfma_f32_16x16x32_bf16 v[22:25], v[146:149], v[218:221], v[22:25]
	v_mfma_f32_16x16x32_bf16 v[22:25], v[150:153], v[222:225], v[22:25]
	v_mfma_f32_16x16x32_bf16 v[18:21], v[154:157], v[218:221], v[18:21]
	v_mfma_f32_16x16x32_bf16 v[18:21], v[158:161], v[222:225], v[18:21]
	v_mfma_f32_16x16x32_bf16 v[6:9], v[146:149], v[226:229], v[6:9]
	v_mfma_f32_16x16x32_bf16 v[6:9], v[150:153], v[230:233], v[6:9]
	v_mfma_f32_16x16x32_bf16 v[2:5], v[154:157], v[226:229], v[2:5]
	v_mfma_f32_16x16x32_bf16 v[2:5], v[158:161], v[230:233], v[2:5]
	s_setprio 0
	s_barrier
	s_cmp_gt_u32 vcc_hi, 13
	s_cbranch_scc0 .LBB0_778
	s_and_b64 vcc, exec, s[50:51]
	s_cbranch_vccz .LBB0_781
	s_barrier

.Lmid1_850:
	s_add_i32 vcc_lo, 0, 0x10000
	s_add_i32 vcc_hi, 0, 0x14000
	s_add_u32 s20, s56, 0xfffc0080
	s_addc_u32 s21, s57, -1
	s_cmp_eq_u32 s91, 12
	s_cselect_b32 s59, s76, s21
	s_cselect_b32 s58, s77, s20
	s_cselect_b32 s21, s69, s87
	s_cselect_b32 s20, s79, s86
	s_add_i32 m0, s15, 0xc000
	v_lshl_add_u64 v[142:143], s[56:57], 0, v[136:137]
	global_load_lds_dwordx4 v[142:143], off
	v_lshl_add_u64 v[142:143], v[142:143], 0, s[72:73]
	s_add_i32 m0, s15, 0xe000
	s_nop 0
	global_load_lds_dwordx4 v[142:143], off
	s_waitcnt vmcnt(8)
	s_waitcnt lgkmcnt(0)
	s_barrier
	s_setprio 1
	s_waitcnt lgkmcnt(0)
	v_mfma_f32_16x16x32_bf16 v[126:129], v[138:141], v[198:201], 0
	v_mfma_f32_16x16x32_bf16 v[126:129], v[146:149], v[214:217], v[126:129]
	v_mfma_f32_16x16x32_bf16 v[122:125], v[150:153], v[198:201], 0
	v_mfma_f32_16x16x32_bf16 v[122:125], v[158:161], v[214:217], v[122:125]
	v_mfma_f32_16x16x32_bf16 v[110:113], v[138:141], v[218:221], 0
	v_mfma_f32_16x16x32_bf16 v[110:113], v[146:149], v[222:225], v[110:113]
	v_mfma_f32_16x16x32_bf16 v[106:109], v[150:153], v[218:221], 0
	v_mfma_f32_16x16x32_bf16 v[106:109], v[158:161], v[222:225], v[106:109]
	v_mfma_f32_16x16x32_bf16 v[94:97], v[138:141], v[226:229], 0
	v_mfma_f32_16x16x32_bf16 v[94:97], v[146:149], v[230:233], v[94:97]
	v_mfma_f32_16x16x32_bf16 v[90:93], v[150:153], v[226:229], 0
	v_mfma_f32_16x16x32_bf16 v[90:93], v[158:161], v[230:233], v[90:93]
	v_mfma_f32_16x16x32_bf16 v[78:81], v[138:141], v[234:237], 0
	v_mfma_f32_16x16x32_bf16 v[78:81], v[146:149], v[238:241], v[78:81]
	v_mfma_f32_16x16x32_bf16 v[74:77], v[150:153], v[234:237], 0
	v_mfma_f32_16x16x32_bf16 v[74:77], v[158:161], v[238:241], v[74:77]
	s_setprio 0
	s_setprio 1
	v_mfma_f32_16x16x32_bf16 v[118:121], v[182:185], v[198:201], 0
	v_mfma_f32_16x16x32_bf16 v[118:121], v[186:189], v[214:217], v[118:121]
	v_mfma_f32_16x16x32_bf16 v[114:117], v[190:193], v[198:201], 0
	v_mfma_f32_16x16x32_bf16 v[114:117], v[194:197], v[214:217], v[114:117]
	v_mfma_f32_16x16x32_bf16 v[102:105], v[182:185], v[218:221], 0
	v_mfma_f32_16x16x32_bf16 v[102:105], v[186:189], v[222:225], v[102:105]
	v_mfma_f32_16x16x32_bf16 v[98:101], v[190:193], v[218:221], 0
	v_mfma_f32_16x16x32_bf16 v[98:101], v[194:197], v[222:225], v[98:101]
	v_mfma_f32_16x16x32_bf16 v[86:89], v[182:185], v[226:229], 0
	v_mfma_f32_16x16x32_bf16 v[86:89], v[186:189], v[230:233], v[86:89]
	v_mfma_f32_16x16x32_bf16 v[82:85], v[190:193], v[226:229], 0
	v_mfma_f32_16x16x32_bf16 v[82:85], v[194:197], v[230:233], v[82:85]
	v_mfma_f32_16x16x32_bf16 v[70:73], v[182:185], v[234:237], 0
	v_mfma_f32_16x16x32_bf16 v[70:73], v[186:189], v[238:241], v[70:73]
	v_mfma_f32_16x16x32_bf16 v[66:69], v[190:193], v[234:237], 0
	v_mfma_f32_16x16x32_bf16 v[66:69], v[194:197], v[238:241], v[66:69]
	s_setprio 0
	s_barrier
	ds_read_b128 v[198:201], v157 offset:16384
	ds_read_b128 v[214:217], v157 offset:17408
	ds_read_b128 v[218:221], v157 offset:18432
	ds_read_b128 v[222:225], v157 offset:19456
	ds_read_b128 v[226:229], v157 offset:20480
	ds_read_b128 v[230:233], v157 offset:21504
	ds_read_b128 v[234:237], v157 offset:22528
	ds_read_b128 v[238:241], v157 offset:23552
	v_lshl_add_u64 v[142:143], s[20:21], 0, v[130:131]
	s_add_i32 s20, vcc_lo, s14
	s_mov_b32 m0, s20
	s_nop 0
	s_nop 0
	global_load_lds_dwordx4 v[142:143], off
	v_lshl_add_u64 v[162:163], v[142:143], 0, s[72:73]
	s_add_i32 m0, s20, 0x2000
	s_add_i32 s20, vcc_hi, s14
	global_load_lds_dwordx4 v[162:163], off
	v_lshl_add_u64 v[162:163], v[142:143], 0, s[28:29]
	s_mov_b32 m0, s20
	s_nop 0
	global_load_lds_dwordx4 v[162:163], off
	v_lshl_add_u64 v[162:163], v[142:143], 0, s[82:83]
	s_add_i32 m0, s20, 0x2000
	s_nop 0
	global_load_lds_dwordx4 v[162:163], off
	v_lshl_add_u64 v[162:163], s[58:59], 0, v[132:133]
	s_mov_b32 m0, s15
	v_lshl_add_u64 v[202:203], v[162:163], 0, s[72:73]
	global_load_lds_dwordx4 v[162:163], off
	s_mov_b32 m0, s42
	s_nop 0
	global_load_lds_dwordx4 v[202:203], off
	s_waitcnt vmcnt(8)
	s_waitcnt lgkmcnt(0)
	s_barrier
	s_setprio 1
	s_waitcnt lgkmcnt(0)
	v_mfma_f32_16x16x32_bf16 v[62:65], v[138:141], v[198:201], 0
	v_mfma_f32_16x16x32_bf16 v[62:65], v[146:149], v[214:217], v[62:65]
	v_mfma_f32_16x16x32_bf16 v[58:61], v[150:153], v[198:201], 0
	v_mfma_f32_16x16x32_bf16 v[58:61], v[158:161], v[214:217], v[58:61]
	v_mfma_f32_16x16x32_bf16 v[46:49], v[138:141], v[218:221], 0
	v_mfma_f32_16x16x32_bf16 v[46:49], v[146:149], v[222:225], v[46:49]
	v_mfma_f32_16x16x32_bf16 v[42:45], v[150:153], v[218:221], 0
	v_mfma_f32_16x16x32_bf16 v[42:45], v[158:161], v[222:225], v[42:45]
	v_mfma_f32_16x16x32_bf16 v[30:33], v[138:141], v[226:229], 0
	v_mfma_f32_16x16x32_bf16 v[30:33], v[146:149], v[230:233], v[30:33]
	v_mfma_f32_16x16x32_bf16 v[26:29], v[150:153], v[226:229], 0
	v_mfma_f32_16x16x32_bf16 v[26:29], v[158:161], v[230:233], v[26:29]
	v_mfma_f32_16x16x32_bf16 v[14:17], v[138:141], v[234:237], 0
	v_mfma_f32_16x16x32_bf16 v[14:17], v[146:149], v[238:241], v[14:17]
	v_mfma_f32_16x16x32_bf16 v[10:13], v[150:153], v[234:237], 0
	v_mfma_f32_16x16x32_bf16 v[10:13], v[158:161], v[238:241], v[10:13]
	s_setprio 0
	s_setprio 1
	v_mfma_f32_16x16x32_bf16 v[54:57], v[182:185], v[198:201], 0
	v_mfma_f32_16x16x32_bf16 v[54:57], v[186:189], v[214:217], v[54:57]
	v_mfma_f32_16x16x32_bf16 v[50:53], v[190:193], v[198:201], 0
	v_mfma_f32_16x16x32_bf16 v[50:53], v[194:197], v[214:217], v[50:53]
	v_mfma_f32_16x16x32_bf16 v[38:41], v[182:185], v[218:221], 0
	v_mfma_f32_16x16x32_bf16 v[38:41], v[186:189], v[222:225], v[38:41]
	v_mfma_f32_16x16x32_bf16 v[34:37], v[190:193], v[218:221], 0
	v_mfma_f32_16x16x32_bf16 v[34:37], v[194:197], v[222:225], v[34:37]
	v_mfma_f32_16x16x32_bf16 v[22:25], v[182:185], v[226:229], 0
	v_mfma_f32_16x16x32_bf16 v[22:25], v[186:189], v[230:233], v[22:25]
	v_mfma_f32_16x16x32_bf16 v[18:21], v[190:193], v[226:229], 0
	v_mfma_f32_16x16x32_bf16 v[18:21], v[194:197], v[230:233], v[18:21]
	v_mfma_f32_16x16x32_bf16 v[6:9], v[182:185], v[234:237], 0
	v_mfma_f32_16x16x32_bf16 v[6:9], v[186:189], v[238:241], v[6:9]
	v_mfma_f32_16x16x32_bf16 v[2:5], v[190:193], v[234:237], 0
	v_mfma_f32_16x16x32_bf16 v[2:5], v[194:197], v[238:241], v[2:5]
	s_setprio 0
	s_barrier
	s_add_i32 s20, 0, 0x18000
	v_add_u32_e32 v0, s20, v145
	s_add_i32 s21, 0, 0x1c000
	ds_read_b128 v[138:141], v0
	ds_read_b128 v[146:149], v0 offset:1024
	ds_read_b128 v[150:153], v0 offset:2048
	ds_read_b128 v[158:161], v0 offset:3072
	v_add_u32_e32 v0, s21, v145
	ds_read_b128 v[182:185], v0
	ds_read_b128 v[186:189], v0 offset:1024
	ds_read_b128 v[190:193], v0 offset:2048
	ds_read_b128 v[194:197], v0 offset:3072
	ds_read_b128 v[198:201], v157 offset:32768
	ds_read_b128 v[214:217], v157 offset:33792
	ds_read_b128 v[218:221], v157 offset:34816
	ds_read_b128 v[222:225], v157 offset:35840
	ds_read_b128 v[226:229], v157 offset:36864
	ds_read_b128 v[230:233], v157 offset:37888
	ds_read_b128 v[234:237], v157 offset:38912
	ds_read_b128 v[238:241], v157 offset:39936
	s_mov_b32 m0, s43
	v_lshl_add_u64 v[202:203], v[162:163], 0, s[28:29]
	global_load_lds_dwordx4 v[202:203], off
	v_lshl_add_u64 v[202:203], v[162:163], 0, s[82:83]
	s_mov_b32 m0, s46
	s_nop 0
	global_load_lds_dwordx4 v[202:203], off
	s_waitcnt vmcnt(8)
	s_waitcnt lgkmcnt(0)
	s_barrier
	s_setprio 1
	s_waitcnt lgkmcnt(0)
	v_mfma_f32_16x16x32_bf16 v[126:129], v[138:141], v[198:201], v[126:129]
	v_mfma_f32_16x16x32_bf16 v[126:129], v[146:149], v[214:217], v[126:129]
	v_mfma_f32_16x16x32_bf16 v[122:125], v[150:153], v[198:201], v[122:125]
	v_mfma_f32_16x16x32_bf16 v[122:125], v[158:161], v[214:217], v[122:125]
	v_mfma_f32_16x16x32_bf16 v[110:113], v[138:141], v[218:221], v[110:113]
	v_mfma_f32_16x16x32_bf16 v[110:113], v[146:149], v[222:225], v[110:113]
	v_mfma_f32_16x16x32_bf16 v[106:109], v[150:153], v[218:221], v[106:109]
	v_mfma_f32_16x16x32_bf16 v[106:109], v[158:161], v[222:225], v[106:109]
	v_mfma_f32_16x16x32_bf16 v[94:97], v[138:141], v[226:229], v[94:97]
	v_mfma_f32_16x16x32_bf16 v[94:97], v[146:149], v[230:233], v[94:97]
	v_mfma_f32_16x16x32_bf16 v[90:93], v[150:153], v[226:229], v[90:93]
	v_mfma_f32_16x16x32_bf16 v[90:93], v[158:161], v[230:233], v[90:93]
	v_mfma_f32_16x16x32_bf16 v[78:81], v[138:141], v[234:237], v[78:81]
	v_mfma_f32_16x16x32_bf16 v[78:81], v[146:149], v[238:241], v[78:81]
	v_mfma_f32_16x16x32_bf16 v[74:77], v[150:153], v[234:237], v[74:77]
	v_mfma_f32_16x16x32_bf16 v[74:77], v[158:161], v[238:241], v[74:77]
	s_setprio 0
	s_setprio 1
	v_mfma_f32_16x16x32_bf16 v[118:121], v[182:185], v[198:201], v[118:121]
	v_mfma_f32_16x16x32_bf16 v[118:121], v[186:189], v[214:217], v[118:121]
	v_mfma_f32_16x16x32_bf16 v[114:117], v[190:193], v[198:201], v[114:117]
	v_mfma_f32_16x16x32_bf16 v[114:117], v[194:197], v[214:217], v[114:117]
	v_mfma_f32_16x16x32_bf16 v[102:105], v[182:185], v[218:221], v[102:105]
	v_mfma_f32_16x16x32_bf16 v[102:105], v[186:189], v[222:225], v[102:105]
	v_mfma_f32_16x16x32_bf16 v[98:101], v[190:193], v[218:221], v[98:101]
	v_mfma_f32_16x16x32_bf16 v[98:101], v[194:197], v[222:225], v[98:101]
	v_mfma_f32_16x16x32_bf16 v[86:89], v[182:185], v[226:229], v[86:89]
	v_mfma_f32_16x16x32_bf16 v[86:89], v[186:189], v[230:233], v[86:89]
	v_mfma_f32_16x16x32_bf16 v[82:85], v[190:193], v[226:229], v[82:85]
	v_mfma_f32_16x16x32_bf16 v[82:85], v[194:197], v[230:233], v[82:85]
	v_mfma_f32_16x16x32_bf16 v[70:73], v[182:185], v[234:237], v[70:73]
	v_mfma_f32_16x16x32_bf16 v[70:73], v[186:189], v[238:241], v[70:73]
	v_mfma_f32_16x16x32_bf16 v[66:69], v[190:193], v[234:237], v[66:69]
	v_mfma_f32_16x16x32_bf16 v[66:69], v[194:197], v[238:241], v[66:69]
	s_setprio 0
	s_barrier
	ds_read_b128 v[198:201], v157 offset:49152
	ds_read_b128 v[214:217], v157 offset:50176
	ds_read_b128 v[218:221], v157 offset:51200
	ds_read_b128 v[222:225], v157 offset:52224
	ds_read_b128 v[226:229], v157 offset:53248
	ds_read_b128 v[230:233], v157 offset:54272
	ds_read_b128 v[234:237], v157 offset:55296
	ds_read_b128 v[238:241], v157 offset:56320
	s_add_i32 s20, s20, s14
	s_mov_b32 m0, s20
	v_lshl_add_u64 v[202:203], v[142:143], 0, s[34:35]
	global_load_lds_dwordx4 v[202:203], off
	v_lshl_add_u64 v[202:203], v[142:143], 0, s[38:39]
	s_add_i32 m0, s20, 0x2000
	s_add_i32 s20, s21, s14
	global_load_lds_dwordx4 v[202:203], off
	v_lshl_add_u64 v[202:203], v[142:143], 0, s[44:45]
	s_mov_b32 m0, s20
	v_lshl_add_u64 v[142:143], v[142:143], 0, s[10:11]
	global_load_lds_dwordx4 v[202:203], off
	s_add_i32 m0, s20, 0x2000
	s_nop 0
	global_load_lds_dwordx4 v[142:143], off
	v_lshl_add_u64 v[142:143], v[162:163], 0, s[34:35]
	s_mov_b32 m0, s47
	s_nop 0
	global_load_lds_dwordx4 v[142:143], off
	v_lshl_add_u64 v[142:143], v[162:163], 0, s[38:39]
	s_mov_b32 m0, s96
	s_nop 0
	global_load_lds_dwordx4 v[142:143], off
	s_waitcnt vmcnt(8)
	s_waitcnt lgkmcnt(0)
	s_barrier
	s_setprio 1
	s_waitcnt lgkmcnt(0)
	v_mfma_f32_16x16x32_bf16 v[62:65], v[138:141], v[198:201], v[62:65]
	v_mfma_f32_16x16x32_bf16 v[62:65], v[146:149], v[214:217], v[62:65]
	v_mfma_f32_16x16x32_bf16 v[58:61], v[150:153], v[198:201], v[58:61]
	v_mfma_f32_16x16x32_bf16 v[58:61], v[158:161], v[214:217], v[58:61]
	v_mfma_f32_16x16x32_bf16 v[46:49], v[138:141], v[218:221], v[46:49]
	v_mfma_f32_16x16x32_bf16 v[46:49], v[146:149], v[222:225], v[46:49]
	v_mfma_f32_16x16x32_bf16 v[42:45], v[150:153], v[218:221], v[42:45]
	v_mfma_f32_16x16x32_bf16 v[42:45], v[158:161], v[222:225], v[42:45]
	v_mfma_f32_16x16x32_bf16 v[30:33], v[138:141], v[226:229], v[30:33]
	v_mfma_f32_16x16x32_bf16 v[30:33], v[146:149], v[230:233], v[30:33]
	v_mfma_f32_16x16x32_bf16 v[26:29], v[150:153], v[226:229], v[26:29]
	v_mfma_f32_16x16x32_bf16 v[26:29], v[158:161], v[230:233], v[26:29]
	v_mfma_f32_16x16x32_bf16 v[14:17], v[138:141], v[234:237], v[14:17]
	v_mfma_f32_16x16x32_bf16 v[14:17], v[146:149], v[238:241], v[14:17]
	v_mfma_f32_16x16x32_bf16 v[10:13], v[150:153], v[234:237], v[10:13]
	v_mfma_f32_16x16x32_bf16 v[10:13], v[158:161], v[238:241], v[10:13]
	s_add_i32 s91, s91, 2
	s_add_u32 s56, s56, 0x100
	s_addc_u32 s57, s57, 0
	s_add_u32 s86, s86, 0x100
	s_addc_u32 s87, s87, 0
	s_setprio 0
	s_setprio 1
	v_mfma_f32_16x16x32_bf16 v[54:57], v[182:185], v[198:201], v[54:57]
	v_mfma_f32_16x16x32_bf16 v[54:57], v[186:189], v[214:217], v[54:57]
	v_mfma_f32_16x16x32_bf16 v[50:53], v[190:193], v[198:201], v[50:53]
	v_mfma_f32_16x16x32_bf16 v[50:53], v[194:197], v[214:217], v[50:53]
	v_mfma_f32_16x16x32_bf16 v[38:41], v[182:185], v[218:221], v[38:41]
	v_mfma_f32_16x16x32_bf16 v[38:41], v[186:189], v[222:225], v[38:41]
	v_mfma_f32_16x16x32_bf16 v[34:37], v[190:193], v[218:221], v[34:37]
	v_mfma_f32_16x16x32_bf16 v[34:37], v[194:197], v[222:225], v[34:37]
	v_mfma_f32_16x16x32_bf16 v[22:25], v[182:185], v[226:229], v[22:25]
	v_mfma_f32_16x16x32_bf16 v[22:25], v[186:189], v[230:233], v[22:25]
	v_mfma_f32_16x16x32_bf16 v[18:21], v[190:193], v[226:229], v[18:21]
	v_mfma_f32_16x16x32_bf16 v[18:21], v[194:197], v[230:233], v[18:21]
	v_mfma_f32_16x16x32_bf16 v[6:9], v[182:185], v[234:237], v[6:9]
	v_mfma_f32_16x16x32_bf16 v[6:9], v[186:189], v[238:241], v[6:9]
	v_mfma_f32_16x16x32_bf16 v[2:5], v[190:193], v[234:237], v[2:5]
	v_mfma_f32_16x16x32_bf16 v[2:5], v[194:197], v[238:241], v[2:5]
	s_setprio 0
	s_barrier
	s_branch .LBB0_850
	.p2alignl 6, 3212836864
.LBB0_850:
	s_add_i32 vcc_lo, 0, 0x10000
	v_add_u32_e32 v0, vcc_lo, v145
	s_add_i32 vcc_hi, 0, 0x14000
	ds_read_b128 v[138:141], v0
	ds_read_b128 v[146:149], v0 offset:1024
	ds_read_b128 v[150:153], v0 offset:2048
	ds_read_b128 v[158:161], v0 offset:3072
	v_add_u32_e32 v0, vcc_hi, v145
	ds_read_b128 v[182:185], v0
	ds_read_b128 v[186:189], v0 offset:1024
	ds_read_b128 v[190:193], v0 offset:2048
	ds_read_b128 v[194:197], v0 offset:3072
	ds_read_b128 v[198:201], v157
	ds_read_b128 v[214:217], v157 offset:1024
	ds_read_b128 v[218:221], v157 offset:2048
	ds_read_b128 v[222:225], v157 offset:3072
	ds_read_b128 v[226:229], v157 offset:4096
	ds_read_b128 v[230:233], v157 offset:5120
	ds_read_b128 v[234:237], v157 offset:6144
	ds_read_b128 v[238:241], v157 offset:7168
	s_add_u32 s20, s56, 0xfffc0080
	s_addc_u32 s21, s57, -1
	s_cmp_eq_u32 s91, 12
	s_cselect_b32 s59, s76, s21
	s_cselect_b32 s58, s77, s20
	s_cselect_b32 s21, s69, s87
	s_cselect_b32 s20, s79, s86
	s_add_i32 m0, s15, 0xc000
	v_lshl_add_u64 v[142:143], s[56:57], 0, v[136:137]
	global_load_lds_dwordx4 v[142:143], off
	v_lshl_add_u64 v[142:143], v[142:143], 0, s[72:73]
	s_add_i32 m0, s15, 0xe000
	s_nop 0
	global_load_lds_dwordx4 v[142:143], off
	s_waitcnt vmcnt(8)
	s_waitcnt lgkmcnt(0)
	s_barrier
	s_setprio 1
	s_waitcnt lgkmcnt(0)
	v_mfma_f32_16x16x32_bf16 v[126:129], v[138:141], v[198:201], v[126:129]
	v_mfma_f32_16x16x32_bf16 v[126:129], v[146:149], v[214:217], v[126:129]
	v_mfma_f32_16x16x32_bf16 v[122:125], v[150:153], v[198:201], v[122:125]
	v_mfma_f32_16x16x32_bf16 v[122:125], v[158:161], v[214:217], v[122:125]
	v_mfma_f32_16x16x32_bf16 v[110:113], v[138:141], v[218:221], v[110:113]
	v_mfma_f32_16x16x32_bf16 v[110:113], v[146:149], v[222:225], v[110:113]
	v_mfma_f32_16x16x32_bf16 v[106:109], v[150:153], v[218:221], v[106:109]
	v_mfma_f32_16x16x32_bf16 v[106:109], v[158:161], v[222:225], v[106:109]
	v_mfma_f32_16x16x32_bf16 v[94:97], v[138:141], v[226:229], v[94:97]
	v_mfma_f32_16x16x32_bf16 v[94:97], v[146:149], v[230:233], v[94:97]
	v_mfma_f32_16x16x32_bf16 v[90:93], v[150:153], v[226:229], v[90:93]
	v_mfma_f32_16x16x32_bf16 v[90:93], v[158:161], v[230:233], v[90:93]
	v_mfma_f32_16x16x32_bf16 v[78:81], v[138:141], v[234:237], v[78:81]
	v_mfma_f32_16x16x32_bf16 v[78:81], v[146:149], v[238:241], v[78:81]
	v_mfma_f32_16x16x32_bf16 v[74:77], v[150:153], v[234:237], v[74:77]
	v_mfma_f32_16x16x32_bf16 v[74:77], v[158:161], v[238:241], v[74:77]
	s_setprio 0
	s_setprio 1
	v_mfma_f32_16x16x32_bf16 v[118:121], v[182:185], v[198:201], v[118:121]
	v_mfma_f32_16x16x32_bf16 v[118:121], v[186:189], v[214:217], v[118:121]
	v_mfma_f32_16x16x32_bf16 v[114:117], v[190:193], v[198:201], v[114:117]
	v_mfma_f32_16x16x32_bf16 v[114:117], v[194:197], v[214:217], v[114:117]
	v_mfma_f32_16x16x32_bf16 v[102:105], v[182:185], v[218:221], v[102:105]
	v_mfma_f32_16x16x32_bf16 v[102:105], v[186:189], v[222:225], v[102:105]
	v_mfma_f32_16x16x32_bf16 v[98:101], v[190:193], v[218:221], v[98:101]
	v_mfma_f32_16x16x32_bf16 v[98:101], v[194:197], v[222:225], v[98:101]
	v_mfma_f32_16x16x32_bf16 v[86:89], v[182:185], v[226:229], v[86:89]
	v_mfma_f32_16x16x32_bf16 v[86:89], v[186:189], v[230:233], v[86:89]
	v_mfma_f32_16x16x32_bf16 v[82:85], v[190:193], v[226:229], v[82:85]
	v_mfma_f32_16x16x32_bf16 v[82:85], v[194:197], v[230:233], v[82:85]
	v_mfma_f32_16x16x32_bf16 v[70:73], v[182:185], v[234:237], v[70:73]
	v_mfma_f32_16x16x32_bf16 v[70:73], v[186:189], v[238:241], v[70:73]
	v_mfma_f32_16x16x32_bf16 v[66:69], v[190:193], v[234:237], v[66:69]
	v_mfma_f32_16x16x32_bf16 v[66:69], v[194:197], v[238:241], v[66:69]
	s_setprio 0
	s_barrier
	ds_read_b128 v[198:201], v157 offset:16384
	ds_read_b128 v[214:217], v157 offset:17408
	ds_read_b128 v[218:221], v157 offset:18432
	ds_read_b128 v[222:225], v157 offset:19456
	ds_read_b128 v[226:229], v157 offset:20480
	ds_read_b128 v[230:233], v157 offset:21504
	ds_read_b128 v[234:237], v157 offset:22528
	ds_read_b128 v[238:241], v157 offset:23552
	v_lshl_add_u64 v[142:143], s[20:21], 0, v[130:131]
	s_add_i32 s20, vcc_lo, s14
	s_mov_b32 m0, s20
	s_nop 0
	s_nop 0
	global_load_lds_dwordx4 v[142:143], off
	v_lshl_add_u64 v[162:163], v[142:143], 0, s[72:73]
	s_add_i32 m0, s20, 0x2000
	s_add_i32 s20, vcc_hi, s14
	global_load_lds_dwordx4 v[162:163], off
	v_lshl_add_u64 v[162:163], v[142:143], 0, s[28:29]
	s_mov_b32 m0, s20
	s_nop 0
	global_load_lds_dwordx4 v[162:163], off
	v_lshl_add_u64 v[162:163], v[142:143], 0, s[82:83]
	s_add_i32 m0, s20, 0x2000
	s_nop 0
	global_load_lds_dwordx4 v[162:163], off
	v_lshl_add_u64 v[162:163], s[58:59], 0, v[132:133]
	s_mov_b32 m0, s15
	v_lshl_add_u64 v[202:203], v[162:163], 0, s[72:73]
	global_load_lds_dwordx4 v[162:163], off
	s_mov_b32 m0, s42
	s_nop 0
	global_load_lds_dwordx4 v[202:203], off
	s_waitcnt vmcnt(8)
	s_waitcnt lgkmcnt(0)
	s_barrier
	s_setprio 1
	s_waitcnt lgkmcnt(0)
	v_mfma_f32_16x16x32_bf16 v[62:65], v[138:141], v[198:201], v[62:65]
	v_mfma_f32_16x16x32_bf16 v[62:65], v[146:149], v[214:217], v[62:65]
	v_mfma_f32_16x16x32_bf16 v[58:61], v[150:153], v[198:201], v[58:61]
	v_mfma_f32_16x16x32_bf16 v[58:61], v[158:161], v[214:217], v[58:61]
	v_mfma_f32_16x16x32_bf16 v[46:49], v[138:141], v[218:221], v[46:49]
	v_mfma_f32_16x16x32_bf16 v[46:49], v[146:149], v[222:225], v[46:49]
	v_mfma_f32_16x16x32_bf16 v[42:45], v[150:153], v[218:221], v[42:45]
	v_mfma_f32_16x16x32_bf16 v[42:45], v[158:161], v[222:225], v[42:45]
	v_mfma_f32_16x16x32_bf16 v[30:33], v[138:141], v[226:229], v[30:33]
	v_mfma_f32_16x16x32_bf16 v[30:33], v[146:149], v[230:233], v[30:33]
	v_mfma_f32_16x16x32_bf16 v[26:29], v[150:153], v[226:229], v[26:29]
	v_mfma_f32_16x16x32_bf16 v[26:29], v[158:161], v[230:233], v[26:29]
	v_mfma_f32_16x16x32_bf16 v[14:17], v[138:141], v[234:237], v[14:17]
	v_mfma_f32_16x16x32_bf16 v[14:17], v[146:149], v[238:241], v[14:17]
	v_mfma_f32_16x16x32_bf16 v[10:13], v[150:153], v[234:237], v[10:13]
	v_mfma_f32_16x16x32_bf16 v[10:13], v[158:161], v[238:241], v[10:13]
	s_setprio 0
	s_setprio 1
	v_mfma_f32_16x16x32_bf16 v[54:57], v[182:185], v[198:201], v[54:57]
	v_mfma_f32_16x16x32_bf16 v[54:57], v[186:189], v[214:217], v[54:57]
	v_mfma_f32_16x16x32_bf16 v[50:53], v[190:193], v[198:201], v[50:53]
	v_mfma_f32_16x16x32_bf16 v[50:53], v[194:197], v[214:217], v[50:53]
	v_mfma_f32_16x16x32_bf16 v[38:41], v[182:185], v[218:221], v[38:41]
	v_mfma_f32_16x16x32_bf16 v[38:41], v[186:189], v[222:225], v[38:41]
	v_mfma_f32_16x16x32_bf16 v[34:37], v[190:193], v[218:221], v[34:37]
	v_mfma_f32_16x16x32_bf16 v[34:37], v[194:197], v[222:225], v[34:37]
	v_mfma_f32_16x16x32_bf16 v[22:25], v[182:185], v[226:229], v[22:25]
	v_mfma_f32_16x16x32_bf16 v[22:25], v[186:189], v[230:233], v[22:25]
	v_mfma_f32_16x16x32_bf16 v[18:21], v[190:193], v[226:229], v[18:21]
	v_mfma_f32_16x16x32_bf16 v[18:21], v[194:197], v[230:233], v[18:21]
	v_mfma_f32_16x16x32_bf16 v[6:9], v[182:185], v[234:237], v[6:9]
	v_mfma_f32_16x16x32_bf16 v[6:9], v[186:189], v[238:241], v[6:9]
	v_mfma_f32_16x16x32_bf16 v[2:5], v[190:193], v[234:237], v[2:5]
	v_mfma_f32_16x16x32_bf16 v[2:5], v[194:197], v[238:241], v[2:5]
	s_setprio 0
	s_barrier
	s_add_i32 s20, 0, 0x18000
	v_add_u32_e32 v0, s20, v145
	s_add_i32 s21, 0, 0x1c000
	ds_read_b128 v[138:141], v0
	ds_read_b128 v[146:149], v0 offset:1024
	ds_read_b128 v[150:153], v0 offset:2048
	ds_read_b128 v[158:161], v0 offset:3072
	v_add_u32_e32 v0, s21, v145
	ds_read_b128 v[182:185], v0
	ds_read_b128 v[186:189], v0 offset:1024
	ds_read_b128 v[190:193], v0 offset:2048
	ds_read_b128 v[194:197], v0 offset:3072
	ds_read_b128 v[198:201], v157 offset:32768
	ds_read_b128 v[214:217], v157 offset:33792
	ds_read_b128 v[218:221], v157 offset:34816
	ds_read_b128 v[222:225], v157 offset:35840
	ds_read_b128 v[226:229], v157 offset:36864
	ds_read_b128 v[230:233], v157 offset:37888
	ds_read_b128 v[234:237], v157 offset:38912
	ds_read_b128 v[238:241], v157 offset:39936
	s_mov_b32 m0, s43
	v_lshl_add_u64 v[202:203], v[162:163], 0, s[28:29]
	global_load_lds_dwordx4 v[202:203], off
	v_lshl_add_u64 v[202:203], v[162:163], 0, s[82:83]
	s_mov_b32 m0, s46
	s_nop 0
	global_load_lds_dwordx4 v[202:203], off
	s_waitcnt vmcnt(8)
	s_waitcnt lgkmcnt(0)
	s_barrier
	s_setprio 1
	s_waitcnt lgkmcnt(0)
	v_mfma_f32_16x16x32_bf16 v[126:129], v[138:141], v[198:201], v[126:129]
	v_mfma_f32_16x16x32_bf16 v[126:129], v[146:149], v[214:217], v[126:129]
	v_mfma_f32_16x16x32_bf16 v[122:125], v[150:153], v[198:201], v[122:125]
	v_mfma_f32_16x16x32_bf16 v[122:125], v[158:161], v[214:217], v[122:125]
	v_mfma_f32_16x16x32_bf16 v[110:113], v[138:141], v[218:221], v[110:113]
	v_mfma_f32_16x16x32_bf16 v[110:113], v[146:149], v[222:225], v[110:113]
	v_mfma_f32_16x16x32_bf16 v[106:109], v[150:153], v[218:221], v[106:109]
	v_mfma_f32_16x16x32_bf16 v[106:109], v[158:161], v[222:225], v[106:109]
	v_mfma_f32_16x16x32_bf16 v[94:97], v[138:141], v[226:229], v[94:97]
	v_mfma_f32_16x16x32_bf16 v[94:97], v[146:149], v[230:233], v[94:97]
	v_mfma_f32_16x16x32_bf16 v[90:93], v[150:153], v[226:229], v[90:93]
	v_mfma_f32_16x16x32_bf16 v[90:93], v[158:161], v[230:233], v[90:93]
	v_mfma_f32_16x16x32_bf16 v[78:81], v[138:141], v[234:237], v[78:81]
	v_mfma_f32_16x16x32_bf16 v[78:81], v[146:149], v[238:241], v[78:81]
	v_mfma_f32_16x16x32_bf16 v[74:77], v[150:153], v[234:237], v[74:77]
	v_mfma_f32_16x16x32_bf16 v[74:77], v[158:161], v[238:241], v[74:77]
	s_setprio 0
	s_setprio 1
	v_mfma_f32_16x16x32_bf16 v[118:121], v[182:185], v[198:201], v[118:121]
	v_mfma_f32_16x16x32_bf16 v[118:121], v[186:189], v[214:217], v[118:121]
	v_mfma_f32_16x16x32_bf16 v[114:117], v[190:193], v[198:201], v[114:117]
	v_mfma_f32_16x16x32_bf16 v[114:117], v[194:197], v[214:217], v[114:117]
	v_mfma_f32_16x16x32_bf16 v[102:105], v[182:185], v[218:221], v[102:105]
	v_mfma_f32_16x16x32_bf16 v[102:105], v[186:189], v[222:225], v[102:105]
	v_mfma_f32_16x16x32_bf16 v[98:101], v[190:193], v[218:221], v[98:101]
	v_mfma_f32_16x16x32_bf16 v[98:101], v[194:197], v[222:225], v[98:101]
	v_mfma_f32_16x16x32_bf16 v[86:89], v[182:185], v[226:229], v[86:89]
	v_mfma_f32_16x16x32_bf16 v[86:89], v[186:189], v[230:233], v[86:89]
	v_mfma_f32_16x16x32_bf16 v[82:85], v[190:193], v[226:229], v[82:85]
	v_mfma_f32_16x16x32_bf16 v[82:85], v[194:197], v[230:233], v[82:85]
	v_mfma_f32_16x16x32_bf16 v[70:73], v[182:185], v[234:237], v[70:73]
	v_mfma_f32_16x16x32_bf16 v[70:73], v[186:189], v[238:241], v[70:73]
	v_mfma_f32_16x16x32_bf16 v[66:69], v[190:193], v[234:237], v[66:69]
	v_mfma_f32_16x16x32_bf16 v[66:69], v[194:197], v[238:241], v[66:69]
	s_setprio 0
	s_barrier
	ds_read_b128 v[198:201], v157 offset:49152
	ds_read_b128 v[214:217], v157 offset:50176
	ds_read_b128 v[218:221], v157 offset:51200
	ds_read_b128 v[222:225], v157 offset:52224
	ds_read_b128 v[226:229], v157 offset:53248
	ds_read_b128 v[230:233], v157 offset:54272
	ds_read_b128 v[234:237], v157 offset:55296
	ds_read_b128 v[238:241], v157 offset:56320
	s_add_i32 s20, s20, s14
	s_mov_b32 m0, s20
	v_lshl_add_u64 v[202:203], v[142:143], 0, s[34:35]
	global_load_lds_dwordx4 v[202:203], off
	v_lshl_add_u64 v[202:203], v[142:143], 0, s[38:39]
	s_add_i32 m0, s20, 0x2000
	s_add_i32 s20, s21, s14
	global_load_lds_dwordx4 v[202:203], off
	v_lshl_add_u64 v[202:203], v[142:143], 0, s[44:45]
	s_mov_b32 m0, s20
	v_lshl_add_u64 v[142:143], v[142:143], 0, s[10:11]
	global_load_lds_dwordx4 v[202:203], off
	s_add_i32 m0, s20, 0x2000
	s_nop 0
	global_load_lds_dwordx4 v[142:143], off
	v_lshl_add_u64 v[142:143], v[162:163], 0, s[34:35]
	s_mov_b32 m0, s47
	s_nop 0
	global_load_lds_dwordx4 v[142:143], off
	v_lshl_add_u64 v[142:143], v[162:163], 0, s[38:39]
	s_mov_b32 m0, s96
	s_nop 0
	global_load_lds_dwordx4 v[142:143], off
	s_waitcnt vmcnt(8)
	s_waitcnt lgkmcnt(0)
	s_barrier
	s_setprio 1
	s_waitcnt lgkmcnt(0)
	v_mfma_f32_16x16x32_bf16 v[62:65], v[138:141], v[198:201], v[62:65]
	v_mfma_f32_16x16x32_bf16 v[62:65], v[146:149], v[214:217], v[62:65]
	v_mfma_f32_16x16x32_bf16 v[58:61], v[150:153], v[198:201], v[58:61]
	v_mfma_f32_16x16x32_bf16 v[58:61], v[158:161], v[214:217], v[58:61]
	v_mfma_f32_16x16x32_bf16 v[46:49], v[138:141], v[218:221], v[46:49]
	v_mfma_f32_16x16x32_bf16 v[46:49], v[146:149], v[222:225], v[46:49]
	v_mfma_f32_16x16x32_bf16 v[42:45], v[150:153], v[218:221], v[42:45]
	v_mfma_f32_16x16x32_bf16 v[42:45], v[158:161], v[222:225], v[42:45]
	v_mfma_f32_16x16x32_bf16 v[30:33], v[138:141], v[226:229], v[30:33]
	v_mfma_f32_16x16x32_bf16 v[30:33], v[146:149], v[230:233], v[30:33]
	v_mfma_f32_16x16x32_bf16 v[26:29], v[150:153], v[226:229], v[26:29]
	v_mfma_f32_16x16x32_bf16 v[26:29], v[158:161], v[230:233], v[26:29]
	v_mfma_f32_16x16x32_bf16 v[14:17], v[138:141], v[234:237], v[14:17]
	v_mfma_f32_16x16x32_bf16 v[14:17], v[146:149], v[238:241], v[14:17]
	v_mfma_f32_16x16x32_bf16 v[10:13], v[150:153], v[234:237], v[10:13]
	v_mfma_f32_16x16x32_bf16 v[10:13], v[158:161], v[238:241], v[10:13]
	s_add_i32 s91, s91, 2
	s_add_u32 s56, s56, 0x100
	s_addc_u32 s57, s57, 0
	s_add_u32 s86, s86, 0x100
	s_addc_u32 s87, s87, 0
	s_setprio 0
	s_setprio 1
	v_mfma_f32_16x16x32_bf16 v[54:57], v[182:185], v[198:201], v[54:57]
	v_mfma_f32_16x16x32_bf16 v[54:57], v[186:189], v[214:217], v[54:57]
	v_mfma_f32_16x16x32_bf16 v[50:53], v[190:193], v[198:201], v[50:53]
	v_mfma_f32_16x16x32_bf16 v[50:53], v[194:197], v[214:217], v[50:53]
	v_mfma_f32_16x16x32_bf16 v[38:41], v[182:185], v[218:221], v[38:41]
	v_mfma_f32_16x16x32_bf16 v[38:41], v[186:189], v[222:225], v[38:41]
	v_mfma_f32_16x16x32_bf16 v[34:37], v[190:193], v[218:221], v[34:37]
	v_mfma_f32_16x16x32_bf16 v[34:37], v[194:197], v[222:225], v[34:37]
	v_mfma_f32_16x16x32_bf16 v[22:25], v[182:185], v[226:229], v[22:25]
	v_mfma_f32_16x16x32_bf16 v[22:25], v[186:189], v[230:233], v[22:25]
	v_mfma_f32_16x16x32_bf16 v[18:21], v[190:193], v[226:229], v[18:21]
	v_mfma_f32_16x16x32_bf16 v[18:21], v[194:197], v[230:233], v[18:21]
	v_mfma_f32_16x16x32_bf16 v[6:9], v[182:185], v[234:237], v[6:9]
	v_mfma_f32_16x16x32_bf16 v[6:9], v[186:189], v[238:241], v[6:9]
	v_mfma_f32_16x16x32_bf16 v[2:5], v[190:193], v[234:237], v[2:5]
	v_mfma_f32_16x16x32_bf16 v[2:5], v[194:197], v[238:241], v[2:5]
	s_setprio 0
	s_barrier
	s_cmp_gt_u32 s91, 13
	s_cbranch_scc0 .LBB0_850
	s_and_b64 vcc, exec, s[62:63]
	s_cbranch_vccz .LBB0_853
	s_barrier
